# variant: original per-segment setprio flips kept, loader VALU removed
# baseline (speedup 1.0000x reference)
; #define PG8_STAGE(bufoff, gbase, voff) do { _Pragma("unroll") for (int _i = 0; _i < 2; ++_i) \
;         __builtin_amdgcn_global_load_lds((const unsigned*)((const char*)(gbase) + (voff)[_i]), (PG8_LAS unsigned*)(lds + (bufoff) + ldsw + _i * 8192), 16, 0, 0); } while (0)
; #define PG8_LDA(dst, b, h) do { _Pragma("unroll") for (int m = 0; m < 4; ++m) _Pragma("unroll") for (int k = 0; k < 2; ++k) dst[m][k] = *(const PG8_LAS bf16x8*)(lds + PG8_SA(b, h) + aoff + m * 2048 + k * 1024); } while (0)
; #define PG8_LDB(dst, b, h) do { _Pragma("unroll") for (int n = 0; n < 2; ++n) _Pragma("unroll") for (int k = 0; k < 2; ++k) dst[n][k] = *(const PG8_LAS bf16x8*)(lds + PG8_SB(b, h) + boff + n * 2048 + k * 1024); } while (0)
; #define PG8_MMA(ai, bj, At, Bt) do { __builtin_amdgcn_s_setprio(1); _Pragma("unroll") for (int m = 0; m < 4; ++m) _Pragma("unroll") for (int n = 0; n < 2; ++n) _Pragma("unroll") for (int k = 0; k < 2; ++k) \
;         acc[ai][bj][m][n] = __builtin_amdgcn_mfma_f32_16x16x32_bf16(Bt[n][k], At[m][k], acc[ai][bj][m][n], 0, 0, 0); __builtin_amdgcn_s_setprio(0); } while (0)
; #define PG8_WAIT_V(n) asm volatile("s_waitcnt vmcnt(" #n ")" ::: "memory")
; #define PG8_WAIT_L(n) asm volatile("s_waitcnt lgkmcnt(" #n ")" ::: "memory")
; template <class Epi, class Sched, bool ALIGN_EPI = false, bool SP2 = false>
; __device__ __forceinline__ void gemm_phase(PG8_LAS unsigned char* lds, const Gemm g, const Sched& S, const Epi& E) {
;     ...
;             const bool last = (t == nt - 2);
;             const char* a1 = cA + (size_t)(t + 1) * kstep;
;             const char* a2 = last ? nA : cA + (size_t)(t + 2) * kstep; const char* b2 = last ? nB : cB + (size_t)(t + 2) * kstep;
;             const char* a3 = a2 + kstep; const char* b3 = b2 + kstep;
;             if (last && has_next) S.a_ready(nxt);
;             if constexpr (SP2) {
;             PG8_LDB(B0, 0, 0); PG8_LDB(B1, 0, 1); PG8_SCHED; PG8_LDA(At, 0, 0); PG8_STAGE(PG8_SA(1, 1), a1 + hstep, voffA);
;             PG8_WAIT_V(8); PG8_WAIT_L(0); PG8_BAR; PG8_MMA(0, 0, At, B0); PG8_MMA(0, 1, At, B1); PG8_BAR; PG8_SCHED;
;             PG8_LDA(At, 0, 1); PG8_STAGE(PG8_SB(0, 0), b2, voffB); PG8_STAGE(PG8_SB(0, 1), b2 + hstep, voffB); PG8_STAGE(PG8_SA(0, 0), a2, voffA);
;             PG8_WAIT_V(8); PG8_WAIT_L(0); PG8_BAR; PG8_MMA(1, 0, At, B0); PG8_MMA(1, 1, At, B1); PG8_BAR; PG8_SCHED;
.LBB0_673:
	ds_read_b128 v[148:151], v241 offset:0
	ds_read_b128 v[156:159], v241 offset:1024
	ds_read_b128 v[166:169], v241 offset:2048
	ds_read_b128 v[170:173], v241 offset:3072
	ds_read_b128 v[174:177], v241 offset:16384
	ds_read_b128 v[178:181], v241 offset:17408
	ds_read_b128 v[182:185], v241 offset:18432
	ds_read_b128 v[186:189], v241 offset:19456
	s_add_u32 s20, s22, 0xfff00080
	s_addc_u32 s21, s23, -1
	s_cmp_eq_u32 s35, 60
	s_cselect_b32 s25, s11, s21
	s_cselect_b32 s24, s52, s20
	s_cselect_b32 s21, s13, s34
	s_cselect_b32 s20, s53, s62
	s_add_i32 m0, s19, 0xc000
	ds_read_b128 v[190:193], v161
	ds_read_b128 v[194:197], v161 offset:1024
	ds_read_b128 v[198:201], v161 offset:2048
	ds_read_b128 v[202:205], v161 offset:3072
	ds_read_b128 v[206:209], v161 offset:4096
	ds_read_b128 v[210:213], v161 offset:5120
	ds_read_b128 v[214:217], v161 offset:6144
	ds_read_b128 v[218:221], v161 offset:7168
	global_load_lds_dwordx4 v138, s[22:23]
	s_add_i32 m0, s19, 0xe000
	s_nop 0
	global_load_lds_dwordx4 v140, s[22:23]
	s_waitcnt vmcnt(8)
	s_waitcnt lgkmcnt(0)
	s_barrier
	s_setprio 1
	s_waitcnt lgkmcnt(0)
	v_mfma_f32_16x16x32_bf16 v[118:121], v[148:151], v[190:193], v[118:121]
	v_mfma_f32_16x16x32_bf16 v[114:117], v[166:169], v[190:193], v[114:117]
	v_mfma_f32_16x16x32_bf16 v[102:105], v[148:151], v[198:201], v[102:105]
	v_mfma_f32_16x16x32_bf16 v[98:101], v[166:169], v[198:201], v[98:101]
	v_mfma_f32_16x16x32_bf16 v[86:89], v[148:151], v[206:209], v[86:89]
	v_mfma_f32_16x16x32_bf16 v[82:85], v[166:169], v[206:209], v[82:85]
	v_mfma_f32_16x16x32_bf16 v[70:73], v[148:151], v[214:217], v[70:73]
	v_mfma_f32_16x16x32_bf16 v[66:69], v[166:169], v[214:217], v[66:69]
	v_mfma_f32_16x16x32_bf16 v[118:121], v[156:159], v[194:197], v[118:121]
	v_mfma_f32_16x16x32_bf16 v[114:117], v[170:173], v[194:197], v[114:117]
	v_mfma_f32_16x16x32_bf16 v[102:105], v[156:159], v[202:205], v[102:105]
	v_mfma_f32_16x16x32_bf16 v[98:101], v[170:173], v[202:205], v[98:101]
	v_mfma_f32_16x16x32_bf16 v[86:89], v[156:159], v[210:213], v[86:89]
	v_mfma_f32_16x16x32_bf16 v[82:85], v[170:173], v[210:213], v[82:85]
	v_mfma_f32_16x16x32_bf16 v[70:73], v[156:159], v[218:221], v[70:73]
	v_mfma_f32_16x16x32_bf16 v[66:69], v[170:173], v[218:221], v[66:69]
	s_setprio 0
	s_setprio 1
	v_mfma_f32_16x16x32_bf16 v[126:129], v[174:177], v[190:193], v[126:129]
	v_mfma_f32_16x16x32_bf16 v[122:125], v[182:185], v[190:193], v[122:125]
	v_mfma_f32_16x16x32_bf16 v[110:113], v[174:177], v[198:201], v[110:113]
	v_mfma_f32_16x16x32_bf16 v[106:109], v[182:185], v[198:201], v[106:109]
	v_mfma_f32_16x16x32_bf16 v[94:97], v[174:177], v[206:209], v[94:97]
	v_mfma_f32_16x16x32_bf16 v[90:93], v[182:185], v[206:209], v[90:93]
	v_mfma_f32_16x16x32_bf16 v[78:81], v[174:177], v[214:217], v[78:81]
	v_mfma_f32_16x16x32_bf16 v[74:77], v[182:185], v[214:217], v[74:77]
	v_mfma_f32_16x16x32_bf16 v[126:129], v[178:181], v[194:197], v[126:129]
	v_mfma_f32_16x16x32_bf16 v[122:125], v[186:189], v[194:197], v[122:125]
	v_mfma_f32_16x16x32_bf16 v[110:113], v[178:181], v[202:205], v[110:113]
	v_mfma_f32_16x16x32_bf16 v[106:109], v[186:189], v[202:205], v[106:109]
	v_mfma_f32_16x16x32_bf16 v[94:97], v[178:181], v[210:213], v[94:97]
	v_mfma_f32_16x16x32_bf16 v[90:93], v[186:189], v[210:213], v[90:93]
	v_mfma_f32_16x16x32_bf16 v[78:81], v[178:181], v[218:221], v[78:81]
	v_mfma_f32_16x16x32_bf16 v[74:77], v[186:189], v[218:221], v[74:77]
	s_setprio 0
	s_barrier
	s_add_i32 s63, s43, s26
	s_mov_b32 m0, s63
	ds_read_b128 v[190:193], v161 offset:16384
	ds_read_b128 v[194:197], v161 offset:17408
	ds_read_b128 v[198:201], v161 offset:18432
	ds_read_b128 v[202:205], v161 offset:19456
	ds_read_b128 v[206:209], v161 offset:20480
	ds_read_b128 v[210:213], v161 offset:21504
	ds_read_b128 v[214:217], v161 offset:22528
	ds_read_b128 v[218:221], v161 offset:23552
	global_load_lds_dwordx4 v132, s[20:21]
	s_add_i32 m0, s63, 0x2000
	s_add_u32 s64, s20, 0x100000
	s_addc_u32 s65, s21, 0
	s_add_i32 s63, s46, s26
	global_load_lds_dwordx4 v136, s[20:21]
	s_mov_b32 m0, s63
	s_add_u32 s100, s24, 0x80
	s_addc_u32 s101, s25, 0
	global_load_lds_dwordx4 v132, s[64:65]
	s_add_i32 m0, s63, 0x2000
	s_nop 0
	global_load_lds_dwordx4 v136, s[64:65]
	s_mov_b32 m0, s19
	s_nop 0
	global_load_lds_dwordx4 v130, s[24:25]
	s_mov_b32 m0, s29
	s_nop 0
	global_load_lds_dwordx4 v134, s[24:25]
	s_waitcnt vmcnt(8)
	s_waitcnt lgkmcnt(0)
	s_barrier
	s_setprio 1
	s_waitcnt lgkmcnt(0)
	v_mfma_f32_16x16x32_bf16 v[54:57], v[148:151], v[190:193], v[54:57]
	v_mfma_f32_16x16x32_bf16 v[50:53], v[166:169], v[190:193], v[50:53]
	v_mfma_f32_16x16x32_bf16 v[38:41], v[148:151], v[198:201], v[38:41]
	v_mfma_f32_16x16x32_bf16 v[34:37], v[166:169], v[198:201], v[34:37]
	v_mfma_f32_16x16x32_bf16 v[22:25], v[148:151], v[206:209], v[22:25]
	v_mfma_f32_16x16x32_bf16 v[18:21], v[166:169], v[206:209], v[18:21]
	v_mfma_f32_16x16x32_bf16 v[6:9], v[148:151], v[214:217], v[6:9]
	v_mfma_f32_16x16x32_bf16 v[2:5], v[166:169], v[214:217], v[2:5]
	v_mfma_f32_16x16x32_bf16 v[54:57], v[156:159], v[194:197], v[54:57]
	v_mfma_f32_16x16x32_bf16 v[50:53], v[170:173], v[194:197], v[50:53]
	v_mfma_f32_16x16x32_bf16 v[38:41], v[156:159], v[202:205], v[38:41]
	v_mfma_f32_16x16x32_bf16 v[34:37], v[170:173], v[202:205], v[34:37]
	v_mfma_f32_16x16x32_bf16 v[22:25], v[156:159], v[210:213], v[22:25]
	v_mfma_f32_16x16x32_bf16 v[18:21], v[170:173], v[210:213], v[18:21]
	v_mfma_f32_16x16x32_bf16 v[6:9], v[156:159], v[218:221], v[6:9]
	v_mfma_f32_16x16x32_bf16 v[2:5], v[170:173], v[218:221], v[2:5]
	s_setprio 0
	s_setprio 1
	v_mfma_f32_16x16x32_bf16 v[62:65], v[174:177], v[190:193], v[62:65]
	v_mfma_f32_16x16x32_bf16 v[58:61], v[182:185], v[190:193], v[58:61]
	v_mfma_f32_16x16x32_bf16 v[46:49], v[174:177], v[198:201], v[46:49]
	v_mfma_f32_16x16x32_bf16 v[42:45], v[182:185], v[198:201], v[42:45]
	v_mfma_f32_16x16x32_bf16 v[30:33], v[174:177], v[206:209], v[30:33]
	v_mfma_f32_16x16x32_bf16 v[26:29], v[182:185], v[206:209], v[26:29]
	v_mfma_f32_16x16x32_bf16 v[10:13], v[174:177], v[214:217], v[10:13]
	v_mfma_f32_16x16x32_bf16 v[14:17], v[182:185], v[214:217], v[14:17]
	v_mfma_f32_16x16x32_bf16 v[62:65], v[178:181], v[194:197], v[62:65]
	v_mfma_f32_16x16x32_bf16 v[58:61], v[186:189], v[194:197], v[58:61]
	v_mfma_f32_16x16x32_bf16 v[46:49], v[178:181], v[202:205], v[46:49]
	v_mfma_f32_16x16x32_bf16 v[42:45], v[186:189], v[202:205], v[42:45]
	v_mfma_f32_16x16x32_bf16 v[30:33], v[178:181], v[210:213], v[30:33]
	v_mfma_f32_16x16x32_bf16 v[26:29], v[186:189], v[210:213], v[26:29]
	v_mfma_f32_16x16x32_bf16 v[10:13], v[178:181], v[218:221], v[10:13]
	v_mfma_f32_16x16x32_bf16 v[14:17], v[186:189], v[218:221], v[14:17]
	s_setprio 0
	s_barrier
; #define PG8_STAGE(bufoff, gbase, voff) do { _Pragma("unroll") for (int _i = 0; _i < 2; ++_i) \
;         __builtin_amdgcn_global_load_lds((const unsigned*)((const char*)(gbase) + (voff)[_i]), (PG8_LAS unsigned*)(lds + (bufoff) + ldsw + _i * 8192), 16, 0, 0); } while (0)
; #define PG8_LDA(dst, b, h) do { _Pragma("unroll") for (int m = 0; m < 4; ++m) _Pragma("unroll") for (int k = 0; k < 2; ++k) dst[m][k] = *(const PG8_LAS bf16x8*)(lds + PG8_SA(b, h) + aoff + m * 2048 + k * 1024); } while (0)
; #define PG8_LDB(dst, b, h) do { _Pragma("unroll") for (int n = 0; n < 2; ++n) _Pragma("unroll") for (int k = 0; k < 2; ++k) dst[n][k] = *(const PG8_LAS bf16x8*)(lds + PG8_SB(b, h) + boff + n * 2048 + k * 1024); } while (0)
; #define PG8_MMA(ai, bj, At, Bt) do { __builtin_amdgcn_s_setprio(1); _Pragma("unroll") for (int m = 0; m < 4; ++m) _Pragma("unroll") for (int n = 0; n < 2; ++n) _Pragma("unroll") for (int k = 0; k < 2; ++k) \
;         acc[ai][bj][m][n] = __builtin_amdgcn_mfma_f32_16x16x32_bf16(Bt[n][k], At[m][k], acc[ai][bj][m][n], 0, 0, 0); __builtin_amdgcn_s_setprio(0); } while (0)
; #define PG8_WAIT_V(n) asm volatile("s_waitcnt vmcnt(" #n ")" ::: "memory")
; #define PG8_WAIT_L(n) asm volatile("s_waitcnt lgkmcnt(" #n ")" ::: "memory")
; #define PG8_BAR __builtin_amdgcn_s_barrier()
; #define PG8_SCHED __builtin_amdgcn_sched_barrier(0)
; template <class Epi, class Sched, bool ALIGN_EPI = false, bool SP2 = false>
; __device__ __forceinline__ void gemm_phase(PG8_LAS unsigned char* lds, const Gemm g, const Sched& S, const Epi& E) {
;     ...
;             PG8_LDB(B0, 1, 0); PG8_LDB(B1, 1, 1); PG8_SCHED; PG8_LDA(At, 1, 0); PG8_STAGE(PG8_SA(0, 1), a2 + hstep, voffA);
;             PG8_WAIT_V(8); PG8_WAIT_L(0); PG8_BAR; PG8_MMA(0, 0, At, B0); PG8_MMA(0, 1, At, B1); PG8_BAR; PG8_SCHED;
;             PG8_LDA(At, 1, 1); PG8_STAGE(PG8_SB(1, 0), b3, voffB); PG8_STAGE(PG8_SB(1, 1), b3 + hstep, voffB); PG8_STAGE(PG8_SA(1, 0), a3, voffA);
;             PG8_WAIT_V(8); PG8_WAIT_L(0); PG8_BAR; PG8_MMA(1, 0, At, B0); PG8_MMA(1, 1, At, B1); PG8_BAR; PG8_SCHED;
;     ...
;         }
;         if constexpr (ALIGN_EPI) { if (wr == 0) PG8_BAR; }
	s_add_i32 s63, 0, 0x18000
	s_add_i32 s64, 0, 0x1c000
	ds_read_b128 v[148:151], v241 offset:32768
	ds_read_b128 v[156:159], v241 offset:33792
	ds_read_b128 v[166:169], v241 offset:34816
	ds_read_b128 v[170:173], v241 offset:35840
	ds_read_b128 v[174:177], v241 offset:49152
	ds_read_b128 v[178:181], v241 offset:50176
	ds_read_b128 v[182:185], v241 offset:51200
	ds_read_b128 v[186:189], v241 offset:52224
	s_add_u32 s24, s24, 0x100000
	s_addc_u32 s25, s25, 0
	s_mov_b32 m0, s30
	ds_read_b128 v[190:193], v161 offset:32768
	ds_read_b128 v[194:197], v161 offset:33792
	ds_read_b128 v[198:201], v161 offset:34816
	ds_read_b128 v[202:205], v161 offset:35840
	ds_read_b128 v[206:209], v161 offset:36864
	ds_read_b128 v[210:213], v161 offset:37888
	ds_read_b128 v[214:217], v161 offset:38912
	ds_read_b128 v[218:221], v161 offset:39936
	global_load_lds_dwordx4 v130, s[24:25]
	s_mov_b32 m0, s31
	s_nop 0
	global_load_lds_dwordx4 v134, s[24:25]
	s_waitcnt vmcnt(8)
	s_waitcnt lgkmcnt(0)
	s_barrier
	s_setprio 1
	s_waitcnt lgkmcnt(0)
	v_mfma_f32_16x16x32_bf16 v[118:121], v[148:151], v[190:193], v[118:121]
	v_mfma_f32_16x16x32_bf16 v[114:117], v[166:169], v[190:193], v[114:117]
	v_mfma_f32_16x16x32_bf16 v[102:105], v[148:151], v[198:201], v[102:105]
	v_mfma_f32_16x16x32_bf16 v[98:101], v[166:169], v[198:201], v[98:101]
	v_mfma_f32_16x16x32_bf16 v[86:89], v[148:151], v[206:209], v[86:89]
	v_mfma_f32_16x16x32_bf16 v[82:85], v[166:169], v[206:209], v[82:85]
	v_mfma_f32_16x16x32_bf16 v[70:73], v[148:151], v[214:217], v[70:73]
	v_mfma_f32_16x16x32_bf16 v[66:69], v[166:169], v[214:217], v[66:69]
	v_mfma_f32_16x16x32_bf16 v[118:121], v[156:159], v[194:197], v[118:121]
	v_mfma_f32_16x16x32_bf16 v[114:117], v[170:173], v[194:197], v[114:117]
	v_mfma_f32_16x16x32_bf16 v[102:105], v[156:159], v[202:205], v[102:105]
	v_mfma_f32_16x16x32_bf16 v[98:101], v[170:173], v[202:205], v[98:101]
	v_mfma_f32_16x16x32_bf16 v[86:89], v[156:159], v[210:213], v[86:89]
	v_mfma_f32_16x16x32_bf16 v[82:85], v[170:173], v[210:213], v[82:85]
	v_mfma_f32_16x16x32_bf16 v[70:73], v[156:159], v[218:221], v[70:73]
	v_mfma_f32_16x16x32_bf16 v[66:69], v[170:173], v[218:221], v[66:69]
	s_setprio 0
	s_setprio 1
	v_mfma_f32_16x16x32_bf16 v[126:129], v[174:177], v[190:193], v[126:129]
	v_mfma_f32_16x16x32_bf16 v[122:125], v[182:185], v[190:193], v[122:125]
	v_mfma_f32_16x16x32_bf16 v[110:113], v[174:177], v[198:201], v[110:113]
	v_mfma_f32_16x16x32_bf16 v[106:109], v[182:185], v[198:201], v[106:109]
	v_mfma_f32_16x16x32_bf16 v[94:97], v[174:177], v[206:209], v[94:97]
	v_mfma_f32_16x16x32_bf16 v[90:93], v[182:185], v[206:209], v[90:93]
	v_mfma_f32_16x16x32_bf16 v[78:81], v[174:177], v[214:217], v[78:81]
	v_mfma_f32_16x16x32_bf16 v[74:77], v[182:185], v[214:217], v[74:77]
	v_mfma_f32_16x16x32_bf16 v[126:129], v[178:181], v[194:197], v[126:129]
	v_mfma_f32_16x16x32_bf16 v[122:125], v[186:189], v[194:197], v[122:125]
	v_mfma_f32_16x16x32_bf16 v[110:113], v[178:181], v[202:205], v[110:113]
	v_mfma_f32_16x16x32_bf16 v[106:109], v[186:189], v[202:205], v[106:109]
	v_mfma_f32_16x16x32_bf16 v[94:97], v[178:181], v[210:213], v[94:97]
	v_mfma_f32_16x16x32_bf16 v[90:93], v[186:189], v[210:213], v[90:93]
	v_mfma_f32_16x16x32_bf16 v[78:81], v[178:181], v[218:221], v[78:81]
	v_mfma_f32_16x16x32_bf16 v[74:77], v[186:189], v[218:221], v[74:77]
	s_setprio 0
	s_barrier
	s_add_i32 s24, s63, s26
	s_add_i32 m0, s24, 0xffffff80
	ds_read_b128 v[190:193], v161 offset:49152
	ds_read_b128 v[194:197], v161 offset:50176
	ds_read_b128 v[198:201], v161 offset:51200
	ds_read_b128 v[202:205], v161 offset:52224
	ds_read_b128 v[206:209], v161 offset:53248
	ds_read_b128 v[210:213], v161 offset:54272
	ds_read_b128 v[214:217], v161 offset:55296
	ds_read_b128 v[218:221], v161 offset:56320
	global_load_lds_dwordx4 v132, s[20:21] offset:128
	s_add_i32 m0, s24, 0x1f80
	s_add_i32 s24, s64, s26
	global_load_lds_dwordx4 v136, s[20:21] offset:128
	s_add_u32 s20, s20, 0x100080
	s_addc_u32 s21, s21, 0
	s_mov_b32 m0, s24
	s_nop 0
	global_load_lds_dwordx4 v132, s[20:21]
	s_add_i32 m0, s24, 0x2000
	s_nop 0
	global_load_lds_dwordx4 v136, s[20:21]
	s_mov_b32 m0, s40
	s_nop 0
	global_load_lds_dwordx4 v130, s[100:101]
	s_mov_b32 m0, s41
	s_nop 0
	global_load_lds_dwordx4 v134, s[100:101]
	s_waitcnt vmcnt(8)
	s_waitcnt lgkmcnt(0)
	s_barrier
	s_setprio 1
	s_waitcnt lgkmcnt(0)
	v_mfma_f32_16x16x32_bf16 v[54:57], v[148:151], v[190:193], v[54:57]
	v_mfma_f32_16x16x32_bf16 v[50:53], v[166:169], v[190:193], v[50:53]
	v_mfma_f32_16x16x32_bf16 v[38:41], v[148:151], v[198:201], v[38:41]
	v_mfma_f32_16x16x32_bf16 v[34:37], v[166:169], v[198:201], v[34:37]
	v_mfma_f32_16x16x32_bf16 v[22:25], v[148:151], v[206:209], v[22:25]
	v_mfma_f32_16x16x32_bf16 v[18:21], v[166:169], v[206:209], v[18:21]
	v_mfma_f32_16x16x32_bf16 v[6:9], v[148:151], v[214:217], v[6:9]
	v_mfma_f32_16x16x32_bf16 v[2:5], v[166:169], v[214:217], v[2:5]
	v_mfma_f32_16x16x32_bf16 v[54:57], v[156:159], v[194:197], v[54:57]
	v_mfma_f32_16x16x32_bf16 v[50:53], v[170:173], v[194:197], v[50:53]
	v_mfma_f32_16x16x32_bf16 v[38:41], v[156:159], v[202:205], v[38:41]
	v_mfma_f32_16x16x32_bf16 v[34:37], v[170:173], v[202:205], v[34:37]
	v_mfma_f32_16x16x32_bf16 v[22:25], v[156:159], v[210:213], v[22:25]
	v_mfma_f32_16x16x32_bf16 v[18:21], v[170:173], v[210:213], v[18:21]
	v_mfma_f32_16x16x32_bf16 v[6:9], v[156:159], v[218:221], v[6:9]
	v_mfma_f32_16x16x32_bf16 v[2:5], v[170:173], v[218:221], v[2:5]
	s_setprio 0
	s_setprio 1
	v_mfma_f32_16x16x32_bf16 v[62:65], v[174:177], v[190:193], v[62:65]
	v_mfma_f32_16x16x32_bf16 v[58:61], v[182:185], v[190:193], v[58:61]
	v_mfma_f32_16x16x32_bf16 v[46:49], v[174:177], v[198:201], v[46:49]
	v_mfma_f32_16x16x32_bf16 v[42:45], v[182:185], v[198:201], v[42:45]
	v_mfma_f32_16x16x32_bf16 v[30:33], v[174:177], v[206:209], v[30:33]
	v_mfma_f32_16x16x32_bf16 v[26:29], v[182:185], v[206:209], v[26:29]
	v_mfma_f32_16x16x32_bf16 v[10:13], v[174:177], v[214:217], v[10:13]
	v_mfma_f32_16x16x32_bf16 v[14:17], v[182:185], v[214:217], v[14:17]
	v_mfma_f32_16x16x32_bf16 v[62:65], v[178:181], v[194:197], v[62:65]
	v_mfma_f32_16x16x32_bf16 v[58:61], v[186:189], v[194:197], v[58:61]
	v_mfma_f32_16x16x32_bf16 v[46:49], v[178:181], v[202:205], v[46:49]
	v_mfma_f32_16x16x32_bf16 v[42:45], v[186:189], v[202:205], v[42:45]
	v_mfma_f32_16x16x32_bf16 v[30:33], v[178:181], v[210:213], v[30:33]
	v_mfma_f32_16x16x32_bf16 v[26:29], v[186:189], v[210:213], v[26:29]
	v_mfma_f32_16x16x32_bf16 v[10:13], v[178:181], v[218:221], v[10:13]
	v_mfma_f32_16x16x32_bf16 v[14:17], v[186:189], v[218:221], v[14:17]
	s_setprio 0
	s_barrier
	s_add_i32 s35, s35, 2
	s_add_u32 s22, s22, 0x100
	s_addc_u32 s23, s23, 0
	s_add_u32 s62, s62, 0x100
	s_addc_u32 s34, s34, 0
	s_cmp_gt_u32 s35, 61
	s_cbranch_scc0 .LBB0_673
	s_and_b64 vcc, exec, s[8:9]
	s_cbranch_vccz .LBB0_676
	s_barrier

; #define PG8_STAGE(bufoff, gbase, voff) do { _Pragma("unroll") for (int _i = 0; _i < 2; ++_i) \
;         __builtin_amdgcn_global_load_lds((const unsigned*)((const char*)(gbase) + (voff)[_i]), (PG8_LAS unsigned*)(lds + (bufoff) + ldsw + _i * 8192), 16, 0, 0); } while (0)
; #define PG8_LDA(dst, b, h) do { _Pragma("unroll") for (int m = 0; m < 4; ++m) _Pragma("unroll") for (int k = 0; k < 2; ++k) dst[m][k] = *(const PG8_LAS bf16x8*)(lds + PG8_SA(b, h) + aoff + m * 2048 + k * 1024); } while (0)
; #define PG8_LDB(dst, b, h) do { _Pragma("unroll") for (int n = 0; n < 2; ++n) _Pragma("unroll") for (int k = 0; k < 2; ++k) dst[n][k] = *(const PG8_LAS bf16x8*)(lds + PG8_SB(b, h) + boff + n * 2048 + k * 1024); } while (0)
; #define PG8_MMA(ai, bj, At, Bt) do { __builtin_amdgcn_s_setprio(1); _Pragma("unroll") for (int m = 0; m < 4; ++m) _Pragma("unroll") for (int n = 0; n < 2; ++n) _Pragma("unroll") for (int k = 0; k < 2; ++k) \
;         acc[ai][bj][m][n] = __builtin_amdgcn_mfma_f32_16x16x32_bf16(Bt[n][k], At[m][k], acc[ai][bj][m][n], 0, 0, 0); __builtin_amdgcn_s_setprio(0); } while (0)
; #define PG8_WAIT_V(n) asm volatile("s_waitcnt vmcnt(" #n ")" ::: "memory")
; #define PG8_WAIT_L(n) asm volatile("s_waitcnt lgkmcnt(" #n ")" ::: "memory")
; template <class Epi, class Sched, bool ALIGN_EPI = false, bool SP2 = false>
; __device__ __forceinline__ void gemm_phase(PG8_LAS unsigned char* lds, const Gemm g, const Sched& S, const Epi& E) {
;     ...
;             const bool last = (t == nt - 2);
;             const char* a1 = cA + (size_t)(t + 1) * kstep;
;             const char* a2 = last ? nA : cA + (size_t)(t + 2) * kstep; const char* b2 = last ? nB : cB + (size_t)(t + 2) * kstep;
;             const char* a3 = a2 + kstep; const char* b3 = b2 + kstep;
;             if (last && has_next) S.a_ready(nxt);
;             if constexpr (SP2) {
;             PG8_LDB(B0, 0, 0); PG8_LDB(B1, 0, 1); PG8_SCHED; PG8_LDA(At, 0, 0); PG8_STAGE(PG8_SA(1, 1), a1 + hstep, voffA);
;             PG8_WAIT_V(8); PG8_WAIT_L(0); PG8_BAR; PG8_MMA(0, 0, At, B0); PG8_MMA(0, 1, At, B1); PG8_BAR; PG8_SCHED;
;             PG8_LDA(At, 0, 1); PG8_STAGE(PG8_SB(0, 0), b2, voffB); PG8_STAGE(PG8_SB(0, 1), b2 + hstep, voffB); PG8_STAGE(PG8_SA(0, 0), a2, voffA);
;             PG8_WAIT_V(8); PG8_WAIT_L(0); PG8_BAR; PG8_MMA(1, 0, At, B0); PG8_MMA(1, 1, At, B1); PG8_BAR; PG8_SCHED;
.LBB0_1039:
	ds_read_b128 v[130:133], v241 offset:0
	ds_read_b128 v[134:137], v241 offset:1024
	ds_read_b128 v[138:141], v241 offset:2048
	ds_read_b128 v[142:145], v241 offset:3072
	ds_read_b128 v[146:149], v241 offset:16384
	ds_read_b128 v[150:153], v241 offset:17408
	ds_read_b128 v[172:175], v241 offset:18432
	ds_read_b128 v[176:179], v241 offset:19456
	s_add_u32 s24, s26, 0xfff00080
	s_addc_u32 s25, s27, -1
	s_cmp_eq_u32 s68, 60
	s_cselect_b32 s29, s15, s25
	s_cselect_b32 s28, s21, s24
	s_cselect_b32 s25, s13, s67
	s_cselect_b32 s24, s65, s66
	s_add_i32 m0, s23, 0xc000
	ds_read_b128 v[180:183], v185
	ds_read_b128 v[188:191], v185 offset:1024
	ds_read_b128 v[192:195], v185 offset:2048
	ds_read_b128 v[196:199], v185 offset:3072
	ds_read_b128 v[200:203], v185 offset:4096
	ds_read_b128 v[204:207], v185 offset:5120
	ds_read_b128 v[208:211], v185 offset:6144
	ds_read_b128 v[212:215], v185 offset:7168
	global_load_lds_dwordx4 v162, s[26:27]
	s_add_i32 m0, s23, 0xe000
	s_nop 0
	global_load_lds_dwordx4 v166, s[26:27]
	s_waitcnt vmcnt(8)
	s_waitcnt lgkmcnt(0)
	s_barrier
	s_setprio 1
	s_waitcnt lgkmcnt(0)
	v_mfma_f32_16x16x32_bf16 v[114:117], v[130:133], v[180:183], v[114:117]
	v_mfma_f32_16x16x32_bf16 v[118:121], v[138:141], v[180:183], v[118:121]
	v_mfma_f32_16x16x32_bf16 v[106:109], v[130:133], v[192:195], v[106:109]
	v_mfma_f32_16x16x32_bf16 v[98:101], v[138:141], v[192:195], v[98:101]
	v_mfma_f32_16x16x32_bf16 v[90:93], v[130:133], v[200:203], v[90:93]
	v_mfma_f32_16x16x32_bf16 v[82:85], v[138:141], v[200:203], v[82:85]
	v_mfma_f32_16x16x32_bf16 v[74:77], v[130:133], v[208:211], v[74:77]
	v_mfma_f32_16x16x32_bf16 v[66:69], v[138:141], v[208:211], v[66:69]
	v_mfma_f32_16x16x32_bf16 v[114:117], v[134:137], v[188:191], v[114:117]
	v_mfma_f32_16x16x32_bf16 v[118:121], v[142:145], v[188:191], v[118:121]
	v_mfma_f32_16x16x32_bf16 v[106:109], v[134:137], v[196:199], v[106:109]
	v_mfma_f32_16x16x32_bf16 v[98:101], v[142:145], v[196:199], v[98:101]
	v_mfma_f32_16x16x32_bf16 v[90:93], v[134:137], v[204:207], v[90:93]
	v_mfma_f32_16x16x32_bf16 v[82:85], v[142:145], v[204:207], v[82:85]
	v_mfma_f32_16x16x32_bf16 v[74:77], v[134:137], v[212:215], v[74:77]
	v_mfma_f32_16x16x32_bf16 v[66:69], v[142:145], v[212:215], v[66:69]
	s_setprio 0
	s_setprio 1
	v_mfma_f32_16x16x32_bf16 v[122:125], v[146:149], v[180:183], v[122:125]
	v_mfma_f32_16x16x32_bf16 v[126:129], v[172:175], v[180:183], v[126:129]
	v_mfma_f32_16x16x32_bf16 v[110:113], v[146:149], v[192:195], v[110:113]
	v_mfma_f32_16x16x32_bf16 v[102:105], v[172:175], v[192:195], v[102:105]
	v_mfma_f32_16x16x32_bf16 v[94:97], v[146:149], v[200:203], v[94:97]
	v_mfma_f32_16x16x32_bf16 v[86:89], v[172:175], v[200:203], v[86:89]
	v_mfma_f32_16x16x32_bf16 v[78:81], v[146:149], v[208:211], v[78:81]
	v_mfma_f32_16x16x32_bf16 v[70:73], v[172:175], v[208:211], v[70:73]
	v_mfma_f32_16x16x32_bf16 v[122:125], v[150:153], v[188:191], v[122:125]
	v_mfma_f32_16x16x32_bf16 v[126:129], v[176:179], v[188:191], v[126:129]
	v_mfma_f32_16x16x32_bf16 v[110:113], v[150:153], v[196:199], v[110:113]
	v_mfma_f32_16x16x32_bf16 v[102:105], v[176:179], v[196:199], v[102:105]
	v_mfma_f32_16x16x32_bf16 v[94:97], v[150:153], v[204:207], v[94:97]
	v_mfma_f32_16x16x32_bf16 v[86:89], v[176:179], v[204:207], v[86:89]
	v_mfma_f32_16x16x32_bf16 v[78:81], v[150:153], v[212:215], v[78:81]
	v_mfma_f32_16x16x32_bf16 v[70:73], v[176:179], v[212:215], v[70:73]
	s_setprio 0
	s_barrier
	s_add_i32 s33, s62, s36
	s_mov_b32 m0, s33
	ds_read_b128 v[180:183], v185 offset:16384
	ds_read_b128 v[188:191], v185 offset:17408
	ds_read_b128 v[192:195], v185 offset:18432
	ds_read_b128 v[196:199], v185 offset:19456
	ds_read_b128 v[200:203], v185 offset:20480
	ds_read_b128 v[204:207], v185 offset:21504
	ds_read_b128 v[208:211], v185 offset:22528
	ds_read_b128 v[212:215], v185 offset:23552
	global_load_lds_dwordx4 v156, s[24:25]
	s_add_i32 m0, s33, 0x2000
	s_add_u32 s72, s24, 0x100000
	s_addc_u32 s73, s25, 0
	s_add_i32 s33, s63, s36
	global_load_lds_dwordx4 v160, s[24:25]
	s_mov_b32 m0, s33
	s_add_u32 s100, s28, 0x80
	s_addc_u32 s101, s29, 0
	global_load_lds_dwordx4 v156, s[72:73]
	s_add_i32 m0, s33, 0x2000
	s_nop 0
	global_load_lds_dwordx4 v160, s[72:73]
	s_mov_b32 m0, s23
	s_nop 0
	global_load_lds_dwordx4 v154, s[28:29]
	s_mov_b32 m0, s37
	s_nop 0
	global_load_lds_dwordx4 v158, s[28:29]
	s_waitcnt vmcnt(8)
	s_waitcnt lgkmcnt(0)
	s_barrier
	s_setprio 1
	s_waitcnt lgkmcnt(0)
	v_mfma_f32_16x16x32_bf16 v[58:61], v[130:133], v[180:183], v[58:61]
	v_mfma_f32_16x16x32_bf16 v[54:57], v[138:141], v[180:183], v[54:57]
	v_mfma_f32_16x16x32_bf16 v[42:45], v[130:133], v[192:195], v[42:45]
	v_mfma_f32_16x16x32_bf16 v[34:37], v[138:141], v[192:195], v[34:37]
	v_mfma_f32_16x16x32_bf16 v[26:29], v[130:133], v[200:203], v[26:29]
	v_mfma_f32_16x16x32_bf16 v[18:21], v[138:141], v[200:203], v[18:21]
	v_mfma_f32_16x16x32_bf16 v[6:9], v[130:133], v[208:211], v[6:9]
	v_mfma_f32_16x16x32_bf16 v[2:5], v[138:141], v[208:211], v[2:5]
	v_mfma_f32_16x16x32_bf16 v[58:61], v[134:137], v[188:191], v[58:61]
	v_mfma_f32_16x16x32_bf16 v[54:57], v[142:145], v[188:191], v[54:57]
	v_mfma_f32_16x16x32_bf16 v[42:45], v[134:137], v[196:199], v[42:45]
	v_mfma_f32_16x16x32_bf16 v[34:37], v[142:145], v[196:199], v[34:37]
	v_mfma_f32_16x16x32_bf16 v[26:29], v[134:137], v[204:207], v[26:29]
	v_mfma_f32_16x16x32_bf16 v[18:21], v[142:145], v[204:207], v[18:21]
	v_mfma_f32_16x16x32_bf16 v[6:9], v[134:137], v[212:215], v[6:9]
	v_mfma_f32_16x16x32_bf16 v[2:5], v[142:145], v[212:215], v[2:5]
	s_setprio 0
	s_setprio 1
	v_mfma_f32_16x16x32_bf16 v[62:65], v[146:149], v[180:183], v[62:65]
	v_mfma_f32_16x16x32_bf16 v[50:53], v[172:175], v[180:183], v[50:53]
	v_mfma_f32_16x16x32_bf16 v[46:49], v[146:149], v[192:195], v[46:49]
	v_mfma_f32_16x16x32_bf16 v[38:41], v[172:175], v[192:195], v[38:41]
	v_mfma_f32_16x16x32_bf16 v[30:33], v[146:149], v[200:203], v[30:33]
	v_mfma_f32_16x16x32_bf16 v[22:25], v[172:175], v[200:203], v[22:25]
	v_mfma_f32_16x16x32_bf16 v[10:13], v[146:149], v[208:211], v[10:13]
	v_mfma_f32_16x16x32_bf16 v[14:17], v[172:175], v[208:211], v[14:17]
	v_mfma_f32_16x16x32_bf16 v[62:65], v[150:153], v[188:191], v[62:65]
	v_mfma_f32_16x16x32_bf16 v[50:53], v[176:179], v[188:191], v[50:53]
	v_mfma_f32_16x16x32_bf16 v[46:49], v[150:153], v[196:199], v[46:49]
	v_mfma_f32_16x16x32_bf16 v[38:41], v[176:179], v[196:199], v[38:41]
	v_mfma_f32_16x16x32_bf16 v[30:33], v[150:153], v[204:207], v[30:33]
	v_mfma_f32_16x16x32_bf16 v[22:25], v[176:179], v[204:207], v[22:25]
	v_mfma_f32_16x16x32_bf16 v[10:13], v[150:153], v[212:215], v[10:13]
	v_mfma_f32_16x16x32_bf16 v[14:17], v[176:179], v[212:215], v[14:17]
	s_setprio 0
	s_barrier
; #define PG8_STAGE(bufoff, gbase, voff) do { _Pragma("unroll") for (int _i = 0; _i < 2; ++_i) \
;         __builtin_amdgcn_global_load_lds((const unsigned*)((const char*)(gbase) + (voff)[_i]), (PG8_LAS unsigned*)(lds + (bufoff) + ldsw + _i * 8192), 16, 0, 0); } while (0)
; #define PG8_LDA(dst, b, h) do { _Pragma("unroll") for (int m = 0; m < 4; ++m) _Pragma("unroll") for (int k = 0; k < 2; ++k) dst[m][k] = *(const PG8_LAS bf16x8*)(lds + PG8_SA(b, h) + aoff + m * 2048 + k * 1024); } while (0)
; #define PG8_LDB(dst, b, h) do { _Pragma("unroll") for (int n = 0; n < 2; ++n) _Pragma("unroll") for (int k = 0; k < 2; ++k) dst[n][k] = *(const PG8_LAS bf16x8*)(lds + PG8_SB(b, h) + boff + n * 2048 + k * 1024); } while (0)
; #define PG8_MMA(ai, bj, At, Bt) do { __builtin_amdgcn_s_setprio(1); _Pragma("unroll") for (int m = 0; m < 4; ++m) _Pragma("unroll") for (int n = 0; n < 2; ++n) _Pragma("unroll") for (int k = 0; k < 2; ++k) \
;         acc[ai][bj][m][n] = __builtin_amdgcn_mfma_f32_16x16x32_bf16(Bt[n][k], At[m][k], acc[ai][bj][m][n], 0, 0, 0); __builtin_amdgcn_s_setprio(0); } while (0)
; #define PG8_WAIT_V(n) asm volatile("s_waitcnt vmcnt(" #n ")" ::: "memory")
; #define PG8_WAIT_L(n) asm volatile("s_waitcnt lgkmcnt(" #n ")" ::: "memory")
; #define PG8_BAR __builtin_amdgcn_s_barrier()
; #define PG8_SCHED __builtin_amdgcn_sched_barrier(0)
; template <class Epi, class Sched, bool ALIGN_EPI = false, bool SP2 = false>
; __device__ __forceinline__ void gemm_phase(PG8_LAS unsigned char* lds, const Gemm g, const Sched& S, const Epi& E) {
;     ...
;             PG8_LDB(B0, 1, 0); PG8_LDB(B1, 1, 1); PG8_SCHED; PG8_LDA(At, 1, 0); PG8_STAGE(PG8_SA(0, 1), a2 + hstep, voffA);
;             PG8_WAIT_V(8); PG8_WAIT_L(0); PG8_BAR; PG8_MMA(0, 0, At, B0); PG8_MMA(0, 1, At, B1); PG8_BAR; PG8_SCHED;
;             PG8_LDA(At, 1, 1); PG8_STAGE(PG8_SB(1, 0), b3, voffB); PG8_STAGE(PG8_SB(1, 1), b3 + hstep, voffB); PG8_STAGE(PG8_SA(1, 0), a3, voffA);
;             PG8_WAIT_V(8); PG8_WAIT_L(0); PG8_BAR; PG8_MMA(1, 0, At, B0); PG8_MMA(1, 1, At, B1); PG8_BAR; PG8_SCHED;
;     ...
;         }
;         if constexpr (ALIGN_EPI) { if (wr == 0) PG8_BAR; }
	s_add_i32 s33, 0, 0x18000
	s_add_i32 s42, 0, 0x1c000
	ds_read_b128 v[130:133], v241 offset:32768
	ds_read_b128 v[134:137], v241 offset:33792
	ds_read_b128 v[138:141], v241 offset:34816
	ds_read_b128 v[142:145], v241 offset:35840
	ds_read_b128 v[146:149], v241 offset:49152
	ds_read_b128 v[150:153], v241 offset:50176
	ds_read_b128 v[172:175], v241 offset:51200
	ds_read_b128 v[176:179], v241 offset:52224
	s_add_u32 s28, s28, 0x100000
	s_addc_u32 s29, s29, 0
	s_mov_b32 m0, s40
	ds_read_b128 v[180:183], v185 offset:32768
	ds_read_b128 v[188:191], v185 offset:33792
	ds_read_b128 v[192:195], v185 offset:34816
	ds_read_b128 v[196:199], v185 offset:35840
	ds_read_b128 v[200:203], v185 offset:36864
	ds_read_b128 v[204:207], v185 offset:37888
	ds_read_b128 v[208:211], v185 offset:38912
	ds_read_b128 v[212:215], v185 offset:39936
	global_load_lds_dwordx4 v154, s[28:29]
	s_mov_b32 m0, s41
	s_nop 0
	global_load_lds_dwordx4 v158, s[28:29]
	s_waitcnt vmcnt(8)
	s_waitcnt lgkmcnt(0)
	s_barrier
	s_setprio 1
	s_waitcnt lgkmcnt(0)
	v_mfma_f32_16x16x32_bf16 v[114:117], v[130:133], v[180:183], v[114:117]
	v_mfma_f32_16x16x32_bf16 v[118:121], v[138:141], v[180:183], v[118:121]
	v_mfma_f32_16x16x32_bf16 v[106:109], v[130:133], v[192:195], v[106:109]
	v_mfma_f32_16x16x32_bf16 v[98:101], v[138:141], v[192:195], v[98:101]
	v_mfma_f32_16x16x32_bf16 v[90:93], v[130:133], v[200:203], v[90:93]
	v_mfma_f32_16x16x32_bf16 v[82:85], v[138:141], v[200:203], v[82:85]
	v_mfma_f32_16x16x32_bf16 v[74:77], v[130:133], v[208:211], v[74:77]
	v_mfma_f32_16x16x32_bf16 v[66:69], v[138:141], v[208:211], v[66:69]
	v_mfma_f32_16x16x32_bf16 v[114:117], v[134:137], v[188:191], v[114:117]
	v_mfma_f32_16x16x32_bf16 v[118:121], v[142:145], v[188:191], v[118:121]
	v_mfma_f32_16x16x32_bf16 v[106:109], v[134:137], v[196:199], v[106:109]
	v_mfma_f32_16x16x32_bf16 v[98:101], v[142:145], v[196:199], v[98:101]
	v_mfma_f32_16x16x32_bf16 v[90:93], v[134:137], v[204:207], v[90:93]
	v_mfma_f32_16x16x32_bf16 v[82:85], v[142:145], v[204:207], v[82:85]
	v_mfma_f32_16x16x32_bf16 v[74:77], v[134:137], v[212:215], v[74:77]
	v_mfma_f32_16x16x32_bf16 v[66:69], v[142:145], v[212:215], v[66:69]
	s_setprio 0
	s_setprio 1
	v_mfma_f32_16x16x32_bf16 v[122:125], v[146:149], v[180:183], v[122:125]
	v_mfma_f32_16x16x32_bf16 v[126:129], v[172:175], v[180:183], v[126:129]
	v_mfma_f32_16x16x32_bf16 v[110:113], v[146:149], v[192:195], v[110:113]
	v_mfma_f32_16x16x32_bf16 v[102:105], v[172:175], v[192:195], v[102:105]
	v_mfma_f32_16x16x32_bf16 v[94:97], v[146:149], v[200:203], v[94:97]
	v_mfma_f32_16x16x32_bf16 v[86:89], v[172:175], v[200:203], v[86:89]
	v_mfma_f32_16x16x32_bf16 v[78:81], v[146:149], v[208:211], v[78:81]
	v_mfma_f32_16x16x32_bf16 v[70:73], v[172:175], v[208:211], v[70:73]
	v_mfma_f32_16x16x32_bf16 v[122:125], v[150:153], v[188:191], v[122:125]
	v_mfma_f32_16x16x32_bf16 v[126:129], v[176:179], v[188:191], v[126:129]
	v_mfma_f32_16x16x32_bf16 v[110:113], v[150:153], v[196:199], v[110:113]
	v_mfma_f32_16x16x32_bf16 v[102:105], v[176:179], v[196:199], v[102:105]
	v_mfma_f32_16x16x32_bf16 v[94:97], v[150:153], v[204:207], v[94:97]
	v_mfma_f32_16x16x32_bf16 v[86:89], v[176:179], v[204:207], v[86:89]
	v_mfma_f32_16x16x32_bf16 v[78:81], v[150:153], v[212:215], v[78:81]
	v_mfma_f32_16x16x32_bf16 v[70:73], v[176:179], v[212:215], v[70:73]
	s_setprio 0
	s_barrier
	s_add_i32 s28, s33, s36
	s_add_i32 m0, s28, 0xffffff80
	ds_read_b128 v[180:183], v185 offset:49152
	ds_read_b128 v[188:191], v185 offset:50176
	ds_read_b128 v[192:195], v185 offset:51200
	ds_read_b128 v[196:199], v185 offset:52224
	ds_read_b128 v[200:203], v185 offset:53248
	ds_read_b128 v[204:207], v185 offset:54272
	ds_read_b128 v[208:211], v185 offset:55296
	ds_read_b128 v[212:215], v185 offset:56320
	global_load_lds_dwordx4 v156, s[24:25] offset:128
	s_add_i32 m0, s28, 0x1f80
	s_add_i32 s28, s42, s36
	global_load_lds_dwordx4 v160, s[24:25] offset:128
	s_add_u32 s24, s24, 0x100080
	s_addc_u32 s25, s25, 0
	s_mov_b32 m0, s28
	s_nop 0
	global_load_lds_dwordx4 v156, s[24:25]
	s_add_i32 m0, s28, 0x2000
	s_nop 0
	global_load_lds_dwordx4 v160, s[24:25]
	s_mov_b32 m0, s46
	s_nop 0
	global_load_lds_dwordx4 v154, s[100:101]
	s_mov_b32 m0, s47
	s_nop 0
	global_load_lds_dwordx4 v158, s[100:101]
	s_waitcnt vmcnt(8)
	s_waitcnt lgkmcnt(0)
	s_barrier
	s_setprio 1
	s_waitcnt lgkmcnt(0)
	v_mfma_f32_16x16x32_bf16 v[58:61], v[130:133], v[180:183], v[58:61]
	v_mfma_f32_16x16x32_bf16 v[54:57], v[138:141], v[180:183], v[54:57]
	v_mfma_f32_16x16x32_bf16 v[42:45], v[130:133], v[192:195], v[42:45]
	v_mfma_f32_16x16x32_bf16 v[34:37], v[138:141], v[192:195], v[34:37]
	v_mfma_f32_16x16x32_bf16 v[26:29], v[130:133], v[200:203], v[26:29]
	v_mfma_f32_16x16x32_bf16 v[18:21], v[138:141], v[200:203], v[18:21]
	v_mfma_f32_16x16x32_bf16 v[6:9], v[130:133], v[208:211], v[6:9]
	v_mfma_f32_16x16x32_bf16 v[2:5], v[138:141], v[208:211], v[2:5]
	v_mfma_f32_16x16x32_bf16 v[58:61], v[134:137], v[188:191], v[58:61]
	v_mfma_f32_16x16x32_bf16 v[54:57], v[142:145], v[188:191], v[54:57]
	v_mfma_f32_16x16x32_bf16 v[42:45], v[134:137], v[196:199], v[42:45]
	v_mfma_f32_16x16x32_bf16 v[34:37], v[142:145], v[196:199], v[34:37]
	v_mfma_f32_16x16x32_bf16 v[26:29], v[134:137], v[204:207], v[26:29]
	v_mfma_f32_16x16x32_bf16 v[18:21], v[142:145], v[204:207], v[18:21]
	v_mfma_f32_16x16x32_bf16 v[6:9], v[134:137], v[212:215], v[6:9]
	v_mfma_f32_16x16x32_bf16 v[2:5], v[142:145], v[212:215], v[2:5]
	s_setprio 0
	s_setprio 1
	v_mfma_f32_16x16x32_bf16 v[62:65], v[146:149], v[180:183], v[62:65]
	v_mfma_f32_16x16x32_bf16 v[50:53], v[172:175], v[180:183], v[50:53]
	v_mfma_f32_16x16x32_bf16 v[46:49], v[146:149], v[192:195], v[46:49]
	v_mfma_f32_16x16x32_bf16 v[38:41], v[172:175], v[192:195], v[38:41]
	v_mfma_f32_16x16x32_bf16 v[30:33], v[146:149], v[200:203], v[30:33]
	v_mfma_f32_16x16x32_bf16 v[22:25], v[172:175], v[200:203], v[22:25]
	v_mfma_f32_16x16x32_bf16 v[10:13], v[146:149], v[208:211], v[10:13]
	v_mfma_f32_16x16x32_bf16 v[14:17], v[172:175], v[208:211], v[14:17]
	v_mfma_f32_16x16x32_bf16 v[62:65], v[150:153], v[188:191], v[62:65]
	v_mfma_f32_16x16x32_bf16 v[50:53], v[176:179], v[188:191], v[50:53]
	v_mfma_f32_16x16x32_bf16 v[46:49], v[150:153], v[196:199], v[46:49]
	v_mfma_f32_16x16x32_bf16 v[38:41], v[176:179], v[196:199], v[38:41]
	v_mfma_f32_16x16x32_bf16 v[30:33], v[150:153], v[204:207], v[30:33]
	v_mfma_f32_16x16x32_bf16 v[22:25], v[176:179], v[204:207], v[22:25]
	v_mfma_f32_16x16x32_bf16 v[10:13], v[150:153], v[212:215], v[10:13]
	v_mfma_f32_16x16x32_bf16 v[14:17], v[176:179], v[212:215], v[14:17]
	s_setprio 0
	s_barrier
	s_add_i32 s68, s68, 2
	s_add_u32 s26, s26, 0x100
	s_addc_u32 s27, s27, 0
	s_add_u32 s66, s66, 0x100
	s_addc_u32 s67, s67, 0
	s_cmp_gt_u32 s68, 61
	s_cbranch_scc0 .LBB0_1039
	s_and_b64 vcc, exec, s[10:11]
	s_cbranch_vccz .LBB0_1042
	s_barrier

; #define PG8_STAGE(bufoff, gbase, voff) do { _Pragma("unroll") for (int _i = 0; _i < 2; ++_i) \
;         __builtin_amdgcn_global_load_lds((const unsigned*)((const char*)(gbase) + (voff)[_i]), (PG8_LAS unsigned*)(lds + (bufoff) + ldsw + _i * 8192), 16, 0, 0); } while (0)
; #define PG8_LDA(dst, b, h) do { _Pragma("unroll") for (int m = 0; m < 4; ++m) _Pragma("unroll") for (int k = 0; k < 2; ++k) dst[m][k] = *(const PG8_LAS bf16x8*)(lds + PG8_SA(b, h) + aoff + m * 2048 + k * 1024); } while (0)
; #define PG8_LDB(dst, b, h) do { _Pragma("unroll") for (int n = 0; n < 2; ++n) _Pragma("unroll") for (int k = 0; k < 2; ++k) dst[n][k] = *(const PG8_LAS bf16x8*)(lds + PG8_SB(b, h) + boff + n * 2048 + k * 1024); } while (0)
; #define PG8_MMA(ai, bj, At, Bt) do { __builtin_amdgcn_s_setprio(1); _Pragma("unroll") for (int m = 0; m < 4; ++m) _Pragma("unroll") for (int n = 0; n < 2; ++n) _Pragma("unroll") for (int k = 0; k < 2; ++k) \
;         acc[ai][bj][m][n] = __builtin_amdgcn_mfma_f32_16x16x32_bf16(Bt[n][k], At[m][k], acc[ai][bj][m][n], 0, 0, 0); __builtin_amdgcn_s_setprio(0); } while (0)
; #define PG8_WAIT_V(n) asm volatile("s_waitcnt vmcnt(" #n ")" ::: "memory")
; #define PG8_WAIT_L(n) asm volatile("s_waitcnt lgkmcnt(" #n ")" ::: "memory")
; template <class Epi, class Sched, bool ALIGN_EPI = false, bool SP2 = false>
; __device__ __forceinline__ void gemm_phase(PG8_LAS unsigned char* lds, const Gemm g, const Sched& S, const Epi& E) {
;     ...
;             const bool last = (t == nt - 2);
;             const char* a1 = cA + (size_t)(t + 1) * kstep;
;             const char* a2 = last ? nA : cA + (size_t)(t + 2) * kstep; const char* b2 = last ? nB : cB + (size_t)(t + 2) * kstep;
;             const char* a3 = a2 + kstep; const char* b3 = b2 + kstep;
;             if (last && has_next) S.a_ready(nxt);
;             if constexpr (SP2) {
;             PG8_LDB(B0, 0, 0); PG8_LDB(B1, 0, 1); PG8_SCHED; PG8_LDA(At, 0, 0); PG8_STAGE(PG8_SA(1, 1), a1 + hstep, voffA);
;             PG8_WAIT_V(8); PG8_WAIT_L(0); PG8_BAR; PG8_MMA(0, 0, At, B0); PG8_MMA(0, 1, At, B1); PG8_BAR; PG8_SCHED;
;             PG8_LDA(At, 0, 1); PG8_STAGE(PG8_SB(0, 0), b2, voffB); PG8_STAGE(PG8_SB(0, 1), b2 + hstep, voffB); PG8_STAGE(PG8_SA(0, 0), a2, voffA);
;             PG8_WAIT_V(8); PG8_WAIT_L(0); PG8_BAR; PG8_MMA(1, 0, At, B0); PG8_MMA(1, 1, At, B1); PG8_BAR; PG8_SCHED;
.LBB0_1126:
	ds_read_b128 v[160:163], v241 offset:0
	ds_read_b128 v[166:169], v241 offset:1024
	ds_read_b128 v[170:173], v241 offset:2048
	ds_read_b128 v[174:177], v241 offset:3072
	ds_read_b128 v[178:181], v241 offset:16384
	ds_read_b128 v[182:185], v241 offset:17408
	ds_read_b128 v[186:189], v241 offset:18432
	ds_read_b128 v[190:193], v241 offset:19456
	s_add_u32 s22, s24, 0xfff00080
	s_addc_u32 s23, s25, -1
	s_cmp_eq_u32 s68, 60
	s_cselect_b32 s27, s15, s23
	s_cselect_b32 s26, s64, s22
	s_cselect_b32 s23, s13, s67
	s_cselect_b32 s22, s65, s66
	s_add_i32 m0, s21, 0xc000
	ds_read_b128 v[194:197], v155
	ds_read_b128 v[198:201], v155 offset:1024
	ds_read_b128 v[202:205], v155 offset:2048
	ds_read_b128 v[206:209], v155 offset:3072
	ds_read_b128 v[210:213], v155 offset:4096
	ds_read_b128 v[214:217], v155 offset:5120
	ds_read_b128 v[218:221], v155 offset:6144
	ds_read_b128 v[222:225], v155 offset:7168
	global_load_lds_dwordx4 v138, s[24:25]
	s_add_i32 m0, s21, 0xe000
	s_nop 0
	global_load_lds_dwordx4 v140, s[24:25]
	s_waitcnt vmcnt(8)
	s_waitcnt lgkmcnt(0)
	s_barrier
	s_setprio 1
	s_waitcnt lgkmcnt(0)
	v_mfma_f32_16x16x32_bf16 v[122:125], v[160:163], v[194:197], v[122:125]
	v_mfma_f32_16x16x32_bf16 v[114:117], v[170:173], v[194:197], v[114:117]
	v_mfma_f32_16x16x32_bf16 v[106:109], v[160:163], v[202:205], v[106:109]
	v_mfma_f32_16x16x32_bf16 v[98:101], v[170:173], v[202:205], v[98:101]
	v_mfma_f32_16x16x32_bf16 v[90:93], v[160:163], v[210:213], v[90:93]
	v_mfma_f32_16x16x32_bf16 v[82:85], v[170:173], v[210:213], v[82:85]
	v_mfma_f32_16x16x32_bf16 v[74:77], v[160:163], v[218:221], v[74:77]
	v_mfma_f32_16x16x32_bf16 v[62:65], v[170:173], v[218:221], v[62:65]
	v_mfma_f32_16x16x32_bf16 v[122:125], v[166:169], v[198:201], v[122:125]
	v_mfma_f32_16x16x32_bf16 v[114:117], v[174:177], v[198:201], v[114:117]
	v_mfma_f32_16x16x32_bf16 v[106:109], v[166:169], v[206:209], v[106:109]
	v_mfma_f32_16x16x32_bf16 v[98:101], v[174:177], v[206:209], v[98:101]
	v_mfma_f32_16x16x32_bf16 v[90:93], v[166:169], v[214:217], v[90:93]
	v_mfma_f32_16x16x32_bf16 v[82:85], v[174:177], v[214:217], v[82:85]
	v_mfma_f32_16x16x32_bf16 v[74:77], v[166:169], v[222:225], v[74:77]
	v_mfma_f32_16x16x32_bf16 v[62:65], v[174:177], v[222:225], v[62:65]
	s_setprio 0
	s_setprio 1
	v_mfma_f32_16x16x32_bf16 v[126:129], v[178:181], v[194:197], v[126:129]
	v_mfma_f32_16x16x32_bf16 v[118:121], v[186:189], v[194:197], v[118:121]
	v_mfma_f32_16x16x32_bf16 v[110:113], v[178:181], v[202:205], v[110:113]
	v_mfma_f32_16x16x32_bf16 v[102:105], v[186:189], v[202:205], v[102:105]
	v_mfma_f32_16x16x32_bf16 v[94:97], v[178:181], v[210:213], v[94:97]
	v_mfma_f32_16x16x32_bf16 v[86:89], v[186:189], v[210:213], v[86:89]
	v_mfma_f32_16x16x32_bf16 v[78:81], v[178:181], v[218:221], v[78:81]
	v_mfma_f32_16x16x32_bf16 v[70:73], v[186:189], v[218:221], v[70:73]
	v_mfma_f32_16x16x32_bf16 v[126:129], v[182:185], v[198:201], v[126:129]
	v_mfma_f32_16x16x32_bf16 v[118:121], v[190:193], v[198:201], v[118:121]
	v_mfma_f32_16x16x32_bf16 v[110:113], v[182:185], v[206:209], v[110:113]
	v_mfma_f32_16x16x32_bf16 v[102:105], v[190:193], v[206:209], v[102:105]
	v_mfma_f32_16x16x32_bf16 v[94:97], v[182:185], v[214:217], v[94:97]
	v_mfma_f32_16x16x32_bf16 v[86:89], v[190:193], v[214:217], v[86:89]
	v_mfma_f32_16x16x32_bf16 v[78:81], v[182:185], v[222:225], v[78:81]
	v_mfma_f32_16x16x32_bf16 v[70:73], v[190:193], v[222:225], v[70:73]
	s_setprio 0
	s_barrier
	s_add_i32 s33, s52, s29
	s_mov_b32 m0, s33
	ds_read_b128 v[194:197], v155 offset:16384
	ds_read_b128 v[198:201], v155 offset:17408
	ds_read_b128 v[202:205], v155 offset:18432
	ds_read_b128 v[206:209], v155 offset:19456
	ds_read_b128 v[210:213], v155 offset:20480
	ds_read_b128 v[214:217], v155 offset:21504
	ds_read_b128 v[218:221], v155 offset:22528
	ds_read_b128 v[222:225], v155 offset:23552
	global_load_lds_dwordx4 v132, s[22:23]
	s_add_i32 m0, s33, 0x2000
	s_add_u32 s72, s22, 0x100000
	s_addc_u32 s73, s23, 0
	s_add_i32 s33, s53, s29
	global_load_lds_dwordx4 v136, s[22:23]
	s_mov_b32 m0, s33
	s_add_u32 s100, s26, 0x80
	s_addc_u32 s101, s27, 0
	global_load_lds_dwordx4 v132, s[72:73]
	s_add_i32 m0, s33, 0x2000
	s_nop 0
	global_load_lds_dwordx4 v136, s[72:73]
	s_mov_b32 m0, s21
	s_nop 0
	global_load_lds_dwordx4 v130, s[26:27]
	s_mov_b32 m0, s36
	s_nop 0
	global_load_lds_dwordx4 v134, s[26:27]
	s_waitcnt vmcnt(8)
	s_waitcnt lgkmcnt(0)
	s_barrier
	s_setprio 1
	s_waitcnt lgkmcnt(0)
	v_mfma_f32_16x16x32_bf16 v[58:61], v[160:163], v[194:197], v[58:61]
	v_mfma_f32_16x16x32_bf16 v[50:53], v[170:173], v[194:197], v[50:53]
	v_mfma_f32_16x16x32_bf16 v[42:45], v[160:163], v[202:205], v[42:45]
	v_mfma_f32_16x16x32_bf16 v[34:37], v[170:173], v[202:205], v[34:37]
	v_mfma_f32_16x16x32_bf16 v[26:29], v[160:163], v[210:213], v[26:29]
	v_mfma_f32_16x16x32_bf16 v[18:21], v[170:173], v[210:213], v[18:21]
	v_mfma_f32_16x16x32_bf16 v[10:13], v[160:163], v[218:221], v[10:13]
	v_mfma_f32_16x16x32_bf16 v[2:5], v[170:173], v[218:221], v[2:5]
	v_mfma_f32_16x16x32_bf16 v[58:61], v[166:169], v[198:201], v[58:61]
	v_mfma_f32_16x16x32_bf16 v[50:53], v[174:177], v[198:201], v[50:53]
	v_mfma_f32_16x16x32_bf16 v[42:45], v[166:169], v[206:209], v[42:45]
	v_mfma_f32_16x16x32_bf16 v[34:37], v[174:177], v[206:209], v[34:37]
	v_mfma_f32_16x16x32_bf16 v[26:29], v[166:169], v[214:217], v[26:29]
	v_mfma_f32_16x16x32_bf16 v[18:21], v[174:177], v[214:217], v[18:21]
	v_mfma_f32_16x16x32_bf16 v[10:13], v[166:169], v[222:225], v[10:13]
	v_mfma_f32_16x16x32_bf16 v[2:5], v[174:177], v[222:225], v[2:5]
	s_setprio 0
	s_setprio 1
	v_mfma_f32_16x16x32_bf16 v[66:69], v[178:181], v[194:197], v[66:69]
	v_mfma_f32_16x16x32_bf16 v[54:57], v[186:189], v[194:197], v[54:57]
	v_mfma_f32_16x16x32_bf16 v[46:49], v[178:181], v[202:205], v[46:49]
	v_mfma_f32_16x16x32_bf16 v[38:41], v[186:189], v[202:205], v[38:41]
	v_mfma_f32_16x16x32_bf16 v[30:33], v[178:181], v[210:213], v[30:33]
	v_mfma_f32_16x16x32_bf16 v[22:25], v[186:189], v[210:213], v[22:25]
	v_mfma_f32_16x16x32_bf16 v[14:17], v[178:181], v[218:221], v[14:17]
	v_mfma_f32_16x16x32_bf16 v[6:9], v[186:189], v[218:221], v[6:9]
	v_mfma_f32_16x16x32_bf16 v[66:69], v[182:185], v[198:201], v[66:69]
	v_mfma_f32_16x16x32_bf16 v[54:57], v[190:193], v[198:201], v[54:57]
	v_mfma_f32_16x16x32_bf16 v[46:49], v[182:185], v[206:209], v[46:49]
	v_mfma_f32_16x16x32_bf16 v[38:41], v[190:193], v[206:209], v[38:41]
	v_mfma_f32_16x16x32_bf16 v[30:33], v[182:185], v[214:217], v[30:33]
	v_mfma_f32_16x16x32_bf16 v[22:25], v[190:193], v[214:217], v[22:25]
	v_mfma_f32_16x16x32_bf16 v[14:17], v[182:185], v[222:225], v[14:17]
	v_mfma_f32_16x16x32_bf16 v[6:9], v[190:193], v[222:225], v[6:9]
	s_setprio 0
	s_barrier
; #define PG8_STAGE(bufoff, gbase, voff) do { _Pragma("unroll") for (int _i = 0; _i < 2; ++_i) \
;         __builtin_amdgcn_global_load_lds((const unsigned*)((const char*)(gbase) + (voff)[_i]), (PG8_LAS unsigned*)(lds + (bufoff) + ldsw + _i * 8192), 16, 0, 0); } while (0)
; #define PG8_LDA(dst, b, h) do { _Pragma("unroll") for (int m = 0; m < 4; ++m) _Pragma("unroll") for (int k = 0; k < 2; ++k) dst[m][k] = *(const PG8_LAS bf16x8*)(lds + PG8_SA(b, h) + aoff + m * 2048 + k * 1024); } while (0)
; #define PG8_LDB(dst, b, h) do { _Pragma("unroll") for (int n = 0; n < 2; ++n) _Pragma("unroll") for (int k = 0; k < 2; ++k) dst[n][k] = *(const PG8_LAS bf16x8*)(lds + PG8_SB(b, h) + boff + n * 2048 + k * 1024); } while (0)
; #define PG8_MMA(ai, bj, At, Bt) do { __builtin_amdgcn_s_setprio(1); _Pragma("unroll") for (int m = 0; m < 4; ++m) _Pragma("unroll") for (int n = 0; n < 2; ++n) _Pragma("unroll") for (int k = 0; k < 2; ++k) \
;         acc[ai][bj][m][n] = __builtin_amdgcn_mfma_f32_16x16x32_bf16(Bt[n][k], At[m][k], acc[ai][bj][m][n], 0, 0, 0); __builtin_amdgcn_s_setprio(0); } while (0)
; #define PG8_WAIT_V(n) asm volatile("s_waitcnt vmcnt(" #n ")" ::: "memory")
; #define PG8_WAIT_L(n) asm volatile("s_waitcnt lgkmcnt(" #n ")" ::: "memory")
; #define PG8_BAR __builtin_amdgcn_s_barrier()
; #define PG8_SCHED __builtin_amdgcn_sched_barrier(0)
; template <class Epi, class Sched, bool ALIGN_EPI = false, bool SP2 = false>
; __device__ __forceinline__ void gemm_phase(PG8_LAS unsigned char* lds, const Gemm g, const Sched& S, const Epi& E) {
;     ...
;             PG8_LDB(B0, 1, 0); PG8_LDB(B1, 1, 1); PG8_SCHED; PG8_LDA(At, 1, 0); PG8_STAGE(PG8_SA(0, 1), a2 + hstep, voffA);
;             PG8_WAIT_V(8); PG8_WAIT_L(0); PG8_BAR; PG8_MMA(0, 0, At, B0); PG8_MMA(0, 1, At, B1); PG8_BAR; PG8_SCHED;
;             PG8_LDA(At, 1, 1); PG8_STAGE(PG8_SB(1, 0), b3, voffB); PG8_STAGE(PG8_SB(1, 1), b3 + hstep, voffB); PG8_STAGE(PG8_SA(1, 0), a3, voffA);
;             PG8_WAIT_V(8); PG8_WAIT_L(0); PG8_BAR; PG8_MMA(1, 0, At, B0); PG8_MMA(1, 1, At, B1); PG8_BAR; PG8_SCHED;
;     ...
;         }
;         if constexpr (ALIGN_EPI) { if (wr == 0) PG8_BAR; }
	s_add_i32 s33, 0, 0x18000
	s_add_i32 s42, 0, 0x1c000
	ds_read_b128 v[160:163], v241 offset:32768
	ds_read_b128 v[166:169], v241 offset:33792
	ds_read_b128 v[170:173], v241 offset:34816
	ds_read_b128 v[174:177], v241 offset:35840
	ds_read_b128 v[178:181], v241 offset:49152
	ds_read_b128 v[182:185], v241 offset:50176
	ds_read_b128 v[186:189], v241 offset:51200
	ds_read_b128 v[190:193], v241 offset:52224
	s_add_u32 s26, s26, 0x100000
	s_addc_u32 s27, s27, 0
	s_mov_b32 m0, s37
	ds_read_b128 v[194:197], v155 offset:32768
	ds_read_b128 v[198:201], v155 offset:33792
	ds_read_b128 v[202:205], v155 offset:34816
	ds_read_b128 v[206:209], v155 offset:35840
	ds_read_b128 v[210:213], v155 offset:36864
	ds_read_b128 v[214:217], v155 offset:37888
	ds_read_b128 v[218:221], v155 offset:38912
	ds_read_b128 v[222:225], v155 offset:39936
	global_load_lds_dwordx4 v130, s[26:27]
	s_mov_b32 m0, s40
	s_nop 0
	global_load_lds_dwordx4 v134, s[26:27]
	s_waitcnt vmcnt(8)
	s_waitcnt lgkmcnt(0)
	s_barrier
	s_setprio 1
	s_waitcnt lgkmcnt(0)
	v_mfma_f32_16x16x32_bf16 v[122:125], v[160:163], v[194:197], v[122:125]
	v_mfma_f32_16x16x32_bf16 v[114:117], v[170:173], v[194:197], v[114:117]
	v_mfma_f32_16x16x32_bf16 v[106:109], v[160:163], v[202:205], v[106:109]
	v_mfma_f32_16x16x32_bf16 v[98:101], v[170:173], v[202:205], v[98:101]
	v_mfma_f32_16x16x32_bf16 v[90:93], v[160:163], v[210:213], v[90:93]
	v_mfma_f32_16x16x32_bf16 v[82:85], v[170:173], v[210:213], v[82:85]
	v_mfma_f32_16x16x32_bf16 v[74:77], v[160:163], v[218:221], v[74:77]
	v_mfma_f32_16x16x32_bf16 v[62:65], v[170:173], v[218:221], v[62:65]
	v_mfma_f32_16x16x32_bf16 v[122:125], v[166:169], v[198:201], v[122:125]
	v_mfma_f32_16x16x32_bf16 v[114:117], v[174:177], v[198:201], v[114:117]
	v_mfma_f32_16x16x32_bf16 v[106:109], v[166:169], v[206:209], v[106:109]
	v_mfma_f32_16x16x32_bf16 v[98:101], v[174:177], v[206:209], v[98:101]
	v_mfma_f32_16x16x32_bf16 v[90:93], v[166:169], v[214:217], v[90:93]
	v_mfma_f32_16x16x32_bf16 v[82:85], v[174:177], v[214:217], v[82:85]
	v_mfma_f32_16x16x32_bf16 v[74:77], v[166:169], v[222:225], v[74:77]
	v_mfma_f32_16x16x32_bf16 v[62:65], v[174:177], v[222:225], v[62:65]
	s_setprio 0
	s_setprio 1
	v_mfma_f32_16x16x32_bf16 v[126:129], v[178:181], v[194:197], v[126:129]
	v_mfma_f32_16x16x32_bf16 v[118:121], v[186:189], v[194:197], v[118:121]
	v_mfma_f32_16x16x32_bf16 v[110:113], v[178:181], v[202:205], v[110:113]
	v_mfma_f32_16x16x32_bf16 v[102:105], v[186:189], v[202:205], v[102:105]
	v_mfma_f32_16x16x32_bf16 v[94:97], v[178:181], v[210:213], v[94:97]
	v_mfma_f32_16x16x32_bf16 v[86:89], v[186:189], v[210:213], v[86:89]
	v_mfma_f32_16x16x32_bf16 v[78:81], v[178:181], v[218:221], v[78:81]
	v_mfma_f32_16x16x32_bf16 v[70:73], v[186:189], v[218:221], v[70:73]
	v_mfma_f32_16x16x32_bf16 v[126:129], v[182:185], v[198:201], v[126:129]
	v_mfma_f32_16x16x32_bf16 v[118:121], v[190:193], v[198:201], v[118:121]
	v_mfma_f32_16x16x32_bf16 v[110:113], v[182:185], v[206:209], v[110:113]
	v_mfma_f32_16x16x32_bf16 v[102:105], v[190:193], v[206:209], v[102:105]
	v_mfma_f32_16x16x32_bf16 v[94:97], v[182:185], v[214:217], v[94:97]
	v_mfma_f32_16x16x32_bf16 v[86:89], v[190:193], v[214:217], v[86:89]
	v_mfma_f32_16x16x32_bf16 v[78:81], v[182:185], v[222:225], v[78:81]
	v_mfma_f32_16x16x32_bf16 v[70:73], v[190:193], v[222:225], v[70:73]
	s_setprio 0
	s_barrier
	s_add_i32 s26, s33, s29
	s_add_i32 m0, s26, 0xffffff80
	ds_read_b128 v[194:197], v155 offset:49152
	ds_read_b128 v[198:201], v155 offset:50176
	ds_read_b128 v[202:205], v155 offset:51200
	ds_read_b128 v[206:209], v155 offset:52224
	ds_read_b128 v[210:213], v155 offset:53248
	ds_read_b128 v[214:217], v155 offset:54272
	ds_read_b128 v[218:221], v155 offset:55296
	ds_read_b128 v[222:225], v155 offset:56320
	global_load_lds_dwordx4 v132, s[22:23] offset:128
	s_add_i32 m0, s26, 0x1f80
	s_add_i32 s26, s42, s29
	global_load_lds_dwordx4 v136, s[22:23] offset:128
	s_add_u32 s22, s22, 0x100080
	s_addc_u32 s23, s23, 0
	s_mov_b32 m0, s26
	s_nop 0
	global_load_lds_dwordx4 v132, s[22:23]
	s_add_i32 m0, s26, 0x2000
	s_nop 0
	global_load_lds_dwordx4 v136, s[22:23]
	s_mov_b32 m0, s46
	s_nop 0
	global_load_lds_dwordx4 v130, s[100:101]
	s_mov_b32 m0, s47
	s_nop 0
	global_load_lds_dwordx4 v134, s[100:101]
	s_waitcnt vmcnt(8)
	s_waitcnt lgkmcnt(0)
	s_barrier
	s_setprio 1
	s_waitcnt lgkmcnt(0)
	v_mfma_f32_16x16x32_bf16 v[58:61], v[160:163], v[194:197], v[58:61]
	v_mfma_f32_16x16x32_bf16 v[50:53], v[170:173], v[194:197], v[50:53]
	v_mfma_f32_16x16x32_bf16 v[42:45], v[160:163], v[202:205], v[42:45]
	v_mfma_f32_16x16x32_bf16 v[34:37], v[170:173], v[202:205], v[34:37]
	v_mfma_f32_16x16x32_bf16 v[26:29], v[160:163], v[210:213], v[26:29]
	v_mfma_f32_16x16x32_bf16 v[18:21], v[170:173], v[210:213], v[18:21]
	v_mfma_f32_16x16x32_bf16 v[10:13], v[160:163], v[218:221], v[10:13]
	v_mfma_f32_16x16x32_bf16 v[2:5], v[170:173], v[218:221], v[2:5]
	v_mfma_f32_16x16x32_bf16 v[58:61], v[166:169], v[198:201], v[58:61]
	v_mfma_f32_16x16x32_bf16 v[50:53], v[174:177], v[198:201], v[50:53]
	v_mfma_f32_16x16x32_bf16 v[42:45], v[166:169], v[206:209], v[42:45]
	v_mfma_f32_16x16x32_bf16 v[34:37], v[174:177], v[206:209], v[34:37]
	v_mfma_f32_16x16x32_bf16 v[26:29], v[166:169], v[214:217], v[26:29]
	v_mfma_f32_16x16x32_bf16 v[18:21], v[174:177], v[214:217], v[18:21]
	v_mfma_f32_16x16x32_bf16 v[10:13], v[166:169], v[222:225], v[10:13]
	v_mfma_f32_16x16x32_bf16 v[2:5], v[174:177], v[222:225], v[2:5]
	s_setprio 0
	s_setprio 1
	v_mfma_f32_16x16x32_bf16 v[66:69], v[178:181], v[194:197], v[66:69]
	v_mfma_f32_16x16x32_bf16 v[54:57], v[186:189], v[194:197], v[54:57]
	v_mfma_f32_16x16x32_bf16 v[46:49], v[178:181], v[202:205], v[46:49]
	v_mfma_f32_16x16x32_bf16 v[38:41], v[186:189], v[202:205], v[38:41]
	v_mfma_f32_16x16x32_bf16 v[30:33], v[178:181], v[210:213], v[30:33]
	v_mfma_f32_16x16x32_bf16 v[22:25], v[186:189], v[210:213], v[22:25]
	v_mfma_f32_16x16x32_bf16 v[14:17], v[178:181], v[218:221], v[14:17]
	v_mfma_f32_16x16x32_bf16 v[6:9], v[186:189], v[218:221], v[6:9]
	v_mfma_f32_16x16x32_bf16 v[66:69], v[182:185], v[198:201], v[66:69]
	v_mfma_f32_16x16x32_bf16 v[54:57], v[190:193], v[198:201], v[54:57]
	v_mfma_f32_16x16x32_bf16 v[46:49], v[182:185], v[206:209], v[46:49]
	v_mfma_f32_16x16x32_bf16 v[38:41], v[190:193], v[206:209], v[38:41]
	v_mfma_f32_16x16x32_bf16 v[30:33], v[182:185], v[214:217], v[30:33]
	v_mfma_f32_16x16x32_bf16 v[22:25], v[190:193], v[214:217], v[22:25]
	v_mfma_f32_16x16x32_bf16 v[14:17], v[182:185], v[222:225], v[14:17]
	v_mfma_f32_16x16x32_bf16 v[6:9], v[190:193], v[222:225], v[6:9]
	s_setprio 0
	s_barrier
	s_add_i32 s68, s68, 2
	s_add_u32 s24, s24, 0x100
	s_addc_u32 s25, s25, 0
	s_add_u32 s66, s66, 0x100
	s_addc_u32 s67, s67, 0
	s_cmp_gt_u32 s68, 61
	s_cbranch_scc0 .LBB0_1126
	s_and_b64 vcc, exec, s[8:9]
	s_cbranch_vccz .LBB0_1129
	s_barrier

; #define PG8_STAGE(bufoff, gbase, voff) do { _Pragma("unroll") for (int _i = 0; _i < 2; ++_i) \
;         __builtin_amdgcn_global_load_lds((const unsigned*)((const char*)(gbase) + (voff)[_i]), (PG8_LAS unsigned*)(lds + (bufoff) + ldsw + _i * 8192), 16, 0, 0); } while (0)
; #define PG8_LDA(dst, b, h) do { _Pragma("unroll") for (int m = 0; m < 4; ++m) _Pragma("unroll") for (int k = 0; k < 2; ++k) dst[m][k] = *(const PG8_LAS bf16x8*)(lds + PG8_SA(b, h) + aoff + m * 2048 + k * 1024); } while (0)
; #define PG8_LDB(dst, b, h) do { _Pragma("unroll") for (int n = 0; n < 2; ++n) _Pragma("unroll") for (int k = 0; k < 2; ++k) dst[n][k] = *(const PG8_LAS bf16x8*)(lds + PG8_SB(b, h) + boff + n * 2048 + k * 1024); } while (0)
; #define PG8_MMA(ai, bj, At, Bt) do { __builtin_amdgcn_s_setprio(1); _Pragma("unroll") for (int m = 0; m < 4; ++m) _Pragma("unroll") for (int n = 0; n < 2; ++n) _Pragma("unroll") for (int k = 0; k < 2; ++k) \
;         acc[ai][bj][m][n] = __builtin_amdgcn_mfma_f32_16x16x32_bf16(Bt[n][k], At[m][k], acc[ai][bj][m][n], 0, 0, 0); __builtin_amdgcn_s_setprio(0); } while (0)
; #define PG8_WAIT_V(n) asm volatile("s_waitcnt vmcnt(" #n ")" ::: "memory")
; #define PG8_WAIT_L(n) asm volatile("s_waitcnt lgkmcnt(" #n ")" ::: "memory")
; template <class Epi, class Sched, bool ALIGN_EPI = false, bool SP2 = false>
; __device__ __forceinline__ void gemm_phase(PG8_LAS unsigned char* lds, const Gemm g, const Sched& S, const Epi& E) {
;     ...
;             const bool last = (t == nt - 2);
;             const char* a1 = cA + (size_t)(t + 1) * kstep;
;             const char* a2 = last ? nA : cA + (size_t)(t + 2) * kstep; const char* b2 = last ? nB : cB + (size_t)(t + 2) * kstep;
;             const char* a3 = a2 + kstep; const char* b3 = b2 + kstep;
;             if (last && has_next) S.a_ready(nxt);
;             if constexpr (SP2) {
;             PG8_LDB(B0, 0, 0); PG8_LDB(B1, 0, 1); PG8_SCHED; PG8_LDA(At, 0, 0); PG8_STAGE(PG8_SA(1, 1), a1 + hstep, voffA);
;             PG8_WAIT_V(8); PG8_WAIT_L(0); PG8_BAR; PG8_MMA(0, 0, At, B0); PG8_MMA(0, 1, At, B1); PG8_BAR; PG8_SCHED;
;             PG8_LDA(At, 0, 1); PG8_STAGE(PG8_SB(0, 0), b2, voffB); PG8_STAGE(PG8_SB(0, 1), b2 + hstep, voffB); PG8_STAGE(PG8_SA(0, 0), a2, voffA);
;             PG8_WAIT_V(8); PG8_WAIT_L(0); PG8_BAR; PG8_MMA(1, 0, At, B0); PG8_MMA(1, 1, At, B1); PG8_BAR; PG8_SCHED;
.LBB0_1245:
	ds_read_b128 v[130:133], v241 offset:0
	ds_read_b128 v[134:137], v241 offset:1024
	ds_read_b128 v[138:141], v241 offset:2048
	ds_read_b128 v[142:145], v241 offset:3072
	ds_read_b128 v[146:149], v241 offset:16384
	ds_read_b128 v[150:153], v241 offset:17408
	ds_read_b128 v[172:175], v241 offset:18432
	ds_read_b128 v[176:179], v241 offset:19456
	s_add_u32 s16, s18, 0xffd50080
	s_addc_u32 s17, s19, -1
	s_cmpk_eq_i32 s64, 0xa8
	s_cselect_b32 s21, s5, s17
	s_cselect_b32 s20, s4, s16
	s_cselect_b32 s17, s15, s63
	s_cselect_b32 s16, s14, s62
	s_add_i32 m0, s25, 0xc000
	ds_read_b128 v[180:183], v185
	ds_read_b128 v[188:191], v185 offset:1024
	ds_read_b128 v[192:195], v185 offset:2048
	ds_read_b128 v[196:199], v185 offset:3072
	ds_read_b128 v[200:203], v185 offset:4096
	ds_read_b128 v[204:207], v185 offset:5120
	ds_read_b128 v[208:211], v185 offset:6144
	ds_read_b128 v[212:215], v185 offset:7168
	global_load_lds_dwordx4 v162, s[18:19]
	s_add_i32 m0, s25, 0xe000
	s_nop 0
	global_load_lds_dwordx4 v166, s[18:19]
	s_waitcnt vmcnt(8)
	s_waitcnt lgkmcnt(0)
	s_barrier
	s_setprio 1
	s_waitcnt lgkmcnt(0)
	v_mfma_f32_16x16x32_bf16 v[114:117], v[130:133], v[180:183], v[114:117]
	v_mfma_f32_16x16x32_bf16 v[118:121], v[138:141], v[180:183], v[118:121]
	v_mfma_f32_16x16x32_bf16 v[106:109], v[130:133], v[192:195], v[106:109]
	v_mfma_f32_16x16x32_bf16 v[98:101], v[138:141], v[192:195], v[98:101]
	v_mfma_f32_16x16x32_bf16 v[90:93], v[130:133], v[200:203], v[90:93]
	v_mfma_f32_16x16x32_bf16 v[82:85], v[138:141], v[200:203], v[82:85]
	v_mfma_f32_16x16x32_bf16 v[74:77], v[130:133], v[208:211], v[74:77]
	v_mfma_f32_16x16x32_bf16 v[66:69], v[138:141], v[208:211], v[66:69]
	v_mfma_f32_16x16x32_bf16 v[114:117], v[134:137], v[188:191], v[114:117]
	v_mfma_f32_16x16x32_bf16 v[118:121], v[142:145], v[188:191], v[118:121]
	v_mfma_f32_16x16x32_bf16 v[106:109], v[134:137], v[196:199], v[106:109]
	v_mfma_f32_16x16x32_bf16 v[98:101], v[142:145], v[196:199], v[98:101]
	v_mfma_f32_16x16x32_bf16 v[90:93], v[134:137], v[204:207], v[90:93]
	v_mfma_f32_16x16x32_bf16 v[82:85], v[142:145], v[204:207], v[82:85]
	v_mfma_f32_16x16x32_bf16 v[74:77], v[134:137], v[212:215], v[74:77]
	v_mfma_f32_16x16x32_bf16 v[66:69], v[142:145], v[212:215], v[66:69]
	s_setprio 0
	s_setprio 1
	v_mfma_f32_16x16x32_bf16 v[122:125], v[146:149], v[180:183], v[122:125]
	v_mfma_f32_16x16x32_bf16 v[126:129], v[172:175], v[180:183], v[126:129]
	v_mfma_f32_16x16x32_bf16 v[110:113], v[146:149], v[192:195], v[110:113]
	v_mfma_f32_16x16x32_bf16 v[102:105], v[172:175], v[192:195], v[102:105]
	v_mfma_f32_16x16x32_bf16 v[94:97], v[146:149], v[200:203], v[94:97]
	v_mfma_f32_16x16x32_bf16 v[86:89], v[172:175], v[200:203], v[86:89]
	v_mfma_f32_16x16x32_bf16 v[78:81], v[146:149], v[208:211], v[78:81]
	v_mfma_f32_16x16x32_bf16 v[70:73], v[172:175], v[208:211], v[70:73]
	v_mfma_f32_16x16x32_bf16 v[122:125], v[150:153], v[188:191], v[122:125]
	v_mfma_f32_16x16x32_bf16 v[126:129], v[176:179], v[188:191], v[126:129]
	v_mfma_f32_16x16x32_bf16 v[110:113], v[150:153], v[196:199], v[110:113]
	v_mfma_f32_16x16x32_bf16 v[102:105], v[176:179], v[196:199], v[102:105]
	v_mfma_f32_16x16x32_bf16 v[94:97], v[150:153], v[204:207], v[94:97]
	v_mfma_f32_16x16x32_bf16 v[86:89], v[176:179], v[204:207], v[86:89]
	v_mfma_f32_16x16x32_bf16 v[78:81], v[150:153], v[212:215], v[78:81]
	v_mfma_f32_16x16x32_bf16 v[70:73], v[176:179], v[212:215], v[70:73]
	s_setprio 0
	s_barrier
	s_add_i32 s33, s40, s24
	s_mov_b32 m0, s33
	ds_read_b128 v[180:183], v185 offset:16384
	ds_read_b128 v[188:191], v185 offset:17408
	ds_read_b128 v[192:195], v185 offset:18432
	ds_read_b128 v[196:199], v185 offset:19456
	ds_read_b128 v[200:203], v185 offset:20480
	ds_read_b128 v[204:207], v185 offset:21504
	ds_read_b128 v[208:211], v185 offset:22528
	ds_read_b128 v[212:215], v185 offset:23552
	global_load_lds_dwordx4 v156, s[16:17]
	s_add_i32 m0, s33, 0x2000
	s_add_u32 s66, s16, 0x2b0000
	s_addc_u32 s67, s17, 0
	s_add_i32 s33, s41, s24
	global_load_lds_dwordx4 v160, s[16:17]
	s_mov_b32 m0, s33
	s_add_u32 s100, s20, 0x80
	s_addc_u32 s101, s21, 0
	global_load_lds_dwordx4 v156, s[66:67]
	s_add_i32 m0, s33, 0x2000
	s_nop 0
	global_load_lds_dwordx4 v160, s[66:67]
	s_mov_b32 m0, s25
	s_nop 0
	global_load_lds_dwordx4 v154, s[20:21]
	s_mov_b32 m0, s26
	s_nop 0
	global_load_lds_dwordx4 v158, s[20:21]
	s_waitcnt vmcnt(8)
	s_waitcnt lgkmcnt(0)
	s_barrier
	s_setprio 1
	s_waitcnt lgkmcnt(0)
	v_mfma_f32_16x16x32_bf16 v[58:61], v[130:133], v[180:183], v[58:61]
	v_mfma_f32_16x16x32_bf16 v[54:57], v[138:141], v[180:183], v[54:57]
	v_mfma_f32_16x16x32_bf16 v[42:45], v[130:133], v[192:195], v[42:45]
	v_mfma_f32_16x16x32_bf16 v[34:37], v[138:141], v[192:195], v[34:37]
	v_mfma_f32_16x16x32_bf16 v[26:29], v[130:133], v[200:203], v[26:29]
	v_mfma_f32_16x16x32_bf16 v[18:21], v[138:141], v[200:203], v[18:21]
	v_mfma_f32_16x16x32_bf16 v[6:9], v[130:133], v[208:211], v[6:9]
	v_mfma_f32_16x16x32_bf16 v[2:5], v[138:141], v[208:211], v[2:5]
	v_mfma_f32_16x16x32_bf16 v[58:61], v[134:137], v[188:191], v[58:61]
	v_mfma_f32_16x16x32_bf16 v[54:57], v[142:145], v[188:191], v[54:57]
	v_mfma_f32_16x16x32_bf16 v[42:45], v[134:137], v[196:199], v[42:45]
	v_mfma_f32_16x16x32_bf16 v[34:37], v[142:145], v[196:199], v[34:37]
	v_mfma_f32_16x16x32_bf16 v[26:29], v[134:137], v[204:207], v[26:29]
	v_mfma_f32_16x16x32_bf16 v[18:21], v[142:145], v[204:207], v[18:21]
	v_mfma_f32_16x16x32_bf16 v[6:9], v[134:137], v[212:215], v[6:9]
	v_mfma_f32_16x16x32_bf16 v[2:5], v[142:145], v[212:215], v[2:5]
	s_setprio 0
	s_setprio 1
	v_mfma_f32_16x16x32_bf16 v[62:65], v[146:149], v[180:183], v[62:65]
	v_mfma_f32_16x16x32_bf16 v[50:53], v[172:175], v[180:183], v[50:53]
	v_mfma_f32_16x16x32_bf16 v[46:49], v[146:149], v[192:195], v[46:49]
	v_mfma_f32_16x16x32_bf16 v[38:41], v[172:175], v[192:195], v[38:41]
	v_mfma_f32_16x16x32_bf16 v[30:33], v[146:149], v[200:203], v[30:33]
	v_mfma_f32_16x16x32_bf16 v[22:25], v[172:175], v[200:203], v[22:25]
	v_mfma_f32_16x16x32_bf16 v[10:13], v[146:149], v[208:211], v[10:13]
	v_mfma_f32_16x16x32_bf16 v[14:17], v[172:175], v[208:211], v[14:17]
	v_mfma_f32_16x16x32_bf16 v[62:65], v[150:153], v[188:191], v[62:65]
	v_mfma_f32_16x16x32_bf16 v[50:53], v[176:179], v[188:191], v[50:53]
	v_mfma_f32_16x16x32_bf16 v[46:49], v[150:153], v[196:199], v[46:49]
	v_mfma_f32_16x16x32_bf16 v[38:41], v[176:179], v[196:199], v[38:41]
	v_mfma_f32_16x16x32_bf16 v[30:33], v[150:153], v[204:207], v[30:33]
	v_mfma_f32_16x16x32_bf16 v[22:25], v[176:179], v[204:207], v[22:25]
	v_mfma_f32_16x16x32_bf16 v[10:13], v[150:153], v[212:215], v[10:13]
	v_mfma_f32_16x16x32_bf16 v[14:17], v[176:179], v[212:215], v[14:17]
	s_setprio 0
	s_barrier
; #define PG8_STAGE(bufoff, gbase, voff) do { _Pragma("unroll") for (int _i = 0; _i < 2; ++_i) \
;         __builtin_amdgcn_global_load_lds((const unsigned*)((const char*)(gbase) + (voff)[_i]), (PG8_LAS unsigned*)(lds + (bufoff) + ldsw + _i * 8192), 16, 0, 0); } while (0)
; #define PG8_LDA(dst, b, h) do { _Pragma("unroll") for (int m = 0; m < 4; ++m) _Pragma("unroll") for (int k = 0; k < 2; ++k) dst[m][k] = *(const PG8_LAS bf16x8*)(lds + PG8_SA(b, h) + aoff + m * 2048 + k * 1024); } while (0)
; #define PG8_LDB(dst, b, h) do { _Pragma("unroll") for (int n = 0; n < 2; ++n) _Pragma("unroll") for (int k = 0; k < 2; ++k) dst[n][k] = *(const PG8_LAS bf16x8*)(lds + PG8_SB(b, h) + boff + n * 2048 + k * 1024); } while (0)
; #define PG8_MMA(ai, bj, At, Bt) do { __builtin_amdgcn_s_setprio(1); _Pragma("unroll") for (int m = 0; m < 4; ++m) _Pragma("unroll") for (int n = 0; n < 2; ++n) _Pragma("unroll") for (int k = 0; k < 2; ++k) \
;         acc[ai][bj][m][n] = __builtin_amdgcn_mfma_f32_16x16x32_bf16(Bt[n][k], At[m][k], acc[ai][bj][m][n], 0, 0, 0); __builtin_amdgcn_s_setprio(0); } while (0)
; #define PG8_WAIT_V(n) asm volatile("s_waitcnt vmcnt(" #n ")" ::: "memory")
; #define PG8_WAIT_L(n) asm volatile("s_waitcnt lgkmcnt(" #n ")" ::: "memory")
; #define PG8_BAR __builtin_amdgcn_s_barrier()
; #define PG8_SCHED __builtin_amdgcn_sched_barrier(0)
; template <class Epi, class Sched, bool ALIGN_EPI = false, bool SP2 = false>
; __device__ __forceinline__ void gemm_phase(PG8_LAS unsigned char* lds, const Gemm g, const Sched& S, const Epi& E) {
;     ...
;             PG8_LDB(B0, 1, 0); PG8_LDB(B1, 1, 1); PG8_SCHED; PG8_LDA(At, 1, 0); PG8_STAGE(PG8_SA(0, 1), a2 + hstep, voffA);
;             PG8_WAIT_V(8); PG8_WAIT_L(0); PG8_BAR; PG8_MMA(0, 0, At, B0); PG8_MMA(0, 1, At, B1); PG8_BAR; PG8_SCHED;
;             PG8_LDA(At, 1, 1); PG8_STAGE(PG8_SB(1, 0), b3, voffB); PG8_STAGE(PG8_SB(1, 1), b3 + hstep, voffB); PG8_STAGE(PG8_SA(1, 0), a3, voffA);
;             PG8_WAIT_V(8); PG8_WAIT_L(0); PG8_BAR; PG8_MMA(1, 0, At, B0); PG8_MMA(1, 1, At, B1); PG8_BAR; PG8_SCHED;
;     ...
;         }
;         if constexpr (ALIGN_EPI) { if (wr == 0) PG8_BAR; }
	s_add_i32 s33, 0, 0x18000
	s_add_i32 s42, 0, 0x1c000
	ds_read_b128 v[130:133], v241 offset:32768
	ds_read_b128 v[134:137], v241 offset:33792
	ds_read_b128 v[138:141], v241 offset:34816
	ds_read_b128 v[142:145], v241 offset:35840
	ds_read_b128 v[146:149], v241 offset:49152
	ds_read_b128 v[150:153], v241 offset:50176
	ds_read_b128 v[172:175], v241 offset:51200
	ds_read_b128 v[176:179], v241 offset:52224
	s_add_u32 s20, s20, 0x2b0000
	s_addc_u32 s21, s21, 0
	s_mov_b32 m0, s27
	ds_read_b128 v[180:183], v185 offset:32768
	ds_read_b128 v[188:191], v185 offset:33792
	ds_read_b128 v[192:195], v185 offset:34816
	ds_read_b128 v[196:199], v185 offset:35840
	ds_read_b128 v[200:203], v185 offset:36864
	ds_read_b128 v[204:207], v185 offset:37888
	ds_read_b128 v[208:211], v185 offset:38912
	ds_read_b128 v[212:215], v185 offset:39936
	global_load_lds_dwordx4 v154, s[20:21]
	s_mov_b32 m0, s28
	s_nop 0
	global_load_lds_dwordx4 v158, s[20:21]
	s_waitcnt vmcnt(8)
	s_waitcnt lgkmcnt(0)
	s_barrier
	s_setprio 1
	s_waitcnt lgkmcnt(0)
	v_mfma_f32_16x16x32_bf16 v[114:117], v[130:133], v[180:183], v[114:117]
	v_mfma_f32_16x16x32_bf16 v[118:121], v[138:141], v[180:183], v[118:121]
	v_mfma_f32_16x16x32_bf16 v[106:109], v[130:133], v[192:195], v[106:109]
	v_mfma_f32_16x16x32_bf16 v[98:101], v[138:141], v[192:195], v[98:101]
	v_mfma_f32_16x16x32_bf16 v[90:93], v[130:133], v[200:203], v[90:93]
	v_mfma_f32_16x16x32_bf16 v[82:85], v[138:141], v[200:203], v[82:85]
	v_mfma_f32_16x16x32_bf16 v[74:77], v[130:133], v[208:211], v[74:77]
	v_mfma_f32_16x16x32_bf16 v[66:69], v[138:141], v[208:211], v[66:69]
	v_mfma_f32_16x16x32_bf16 v[114:117], v[134:137], v[188:191], v[114:117]
	v_mfma_f32_16x16x32_bf16 v[118:121], v[142:145], v[188:191], v[118:121]
	v_mfma_f32_16x16x32_bf16 v[106:109], v[134:137], v[196:199], v[106:109]
	v_mfma_f32_16x16x32_bf16 v[98:101], v[142:145], v[196:199], v[98:101]
	v_mfma_f32_16x16x32_bf16 v[90:93], v[134:137], v[204:207], v[90:93]
	v_mfma_f32_16x16x32_bf16 v[82:85], v[142:145], v[204:207], v[82:85]
	v_mfma_f32_16x16x32_bf16 v[74:77], v[134:137], v[212:215], v[74:77]
	v_mfma_f32_16x16x32_bf16 v[66:69], v[142:145], v[212:215], v[66:69]
	s_setprio 0
	s_setprio 1
	v_mfma_f32_16x16x32_bf16 v[122:125], v[146:149], v[180:183], v[122:125]
	v_mfma_f32_16x16x32_bf16 v[126:129], v[172:175], v[180:183], v[126:129]
	v_mfma_f32_16x16x32_bf16 v[110:113], v[146:149], v[192:195], v[110:113]
	v_mfma_f32_16x16x32_bf16 v[102:105], v[172:175], v[192:195], v[102:105]
	v_mfma_f32_16x16x32_bf16 v[94:97], v[146:149], v[200:203], v[94:97]
	v_mfma_f32_16x16x32_bf16 v[86:89], v[172:175], v[200:203], v[86:89]
	v_mfma_f32_16x16x32_bf16 v[78:81], v[146:149], v[208:211], v[78:81]
	v_mfma_f32_16x16x32_bf16 v[70:73], v[172:175], v[208:211], v[70:73]
	v_mfma_f32_16x16x32_bf16 v[122:125], v[150:153], v[188:191], v[122:125]
	v_mfma_f32_16x16x32_bf16 v[126:129], v[176:179], v[188:191], v[126:129]
	v_mfma_f32_16x16x32_bf16 v[110:113], v[150:153], v[196:199], v[110:113]
	v_mfma_f32_16x16x32_bf16 v[102:105], v[176:179], v[196:199], v[102:105]
	v_mfma_f32_16x16x32_bf16 v[94:97], v[150:153], v[204:207], v[94:97]
	v_mfma_f32_16x16x32_bf16 v[86:89], v[176:179], v[204:207], v[86:89]
	v_mfma_f32_16x16x32_bf16 v[78:81], v[150:153], v[212:215], v[78:81]
	v_mfma_f32_16x16x32_bf16 v[70:73], v[176:179], v[212:215], v[70:73]
	s_setprio 0
	s_barrier
	s_add_i32 s20, s33, s24
	s_add_i32 m0, s20, 0xffffff80
	ds_read_b128 v[180:183], v185 offset:49152
	ds_read_b128 v[188:191], v185 offset:50176
	ds_read_b128 v[192:195], v185 offset:51200
	ds_read_b128 v[196:199], v185 offset:52224
	ds_read_b128 v[200:203], v185 offset:53248
	ds_read_b128 v[204:207], v185 offset:54272
	ds_read_b128 v[208:211], v185 offset:55296
	ds_read_b128 v[212:215], v185 offset:56320
	global_load_lds_dwordx4 v156, s[16:17] offset:128
	s_add_i32 m0, s20, 0x1f80
	s_add_i32 s20, s42, s24
	global_load_lds_dwordx4 v160, s[16:17] offset:128
	s_add_u32 s16, s16, 0x2b0080
	s_addc_u32 s17, s17, 0
	s_mov_b32 m0, s20
	s_nop 0
	global_load_lds_dwordx4 v156, s[16:17]
	s_add_i32 m0, s20, 0x2000
	s_nop 0
	global_load_lds_dwordx4 v160, s[16:17]
	s_mov_b32 m0, s34
	s_nop 0
	global_load_lds_dwordx4 v154, s[100:101]
	s_mov_b32 m0, s35
	s_nop 0
	global_load_lds_dwordx4 v158, s[100:101]
	s_waitcnt vmcnt(8)
	s_waitcnt lgkmcnt(0)
	s_barrier
	s_setprio 1
	s_waitcnt lgkmcnt(0)
	v_mfma_f32_16x16x32_bf16 v[58:61], v[130:133], v[180:183], v[58:61]
	v_mfma_f32_16x16x32_bf16 v[54:57], v[138:141], v[180:183], v[54:57]
	v_mfma_f32_16x16x32_bf16 v[42:45], v[130:133], v[192:195], v[42:45]
	v_mfma_f32_16x16x32_bf16 v[34:37], v[138:141], v[192:195], v[34:37]
	v_mfma_f32_16x16x32_bf16 v[26:29], v[130:133], v[200:203], v[26:29]
	v_mfma_f32_16x16x32_bf16 v[18:21], v[138:141], v[200:203], v[18:21]
	v_mfma_f32_16x16x32_bf16 v[6:9], v[130:133], v[208:211], v[6:9]
	v_mfma_f32_16x16x32_bf16 v[2:5], v[138:141], v[208:211], v[2:5]
	v_mfma_f32_16x16x32_bf16 v[58:61], v[134:137], v[188:191], v[58:61]
	v_mfma_f32_16x16x32_bf16 v[54:57], v[142:145], v[188:191], v[54:57]
	v_mfma_f32_16x16x32_bf16 v[42:45], v[134:137], v[196:199], v[42:45]
	v_mfma_f32_16x16x32_bf16 v[34:37], v[142:145], v[196:199], v[34:37]
	v_mfma_f32_16x16x32_bf16 v[26:29], v[134:137], v[204:207], v[26:29]
	v_mfma_f32_16x16x32_bf16 v[18:21], v[142:145], v[204:207], v[18:21]
	v_mfma_f32_16x16x32_bf16 v[6:9], v[134:137], v[212:215], v[6:9]
	v_mfma_f32_16x16x32_bf16 v[2:5], v[142:145], v[212:215], v[2:5]
	s_setprio 0
	s_setprio 1
	v_mfma_f32_16x16x32_bf16 v[62:65], v[146:149], v[180:183], v[62:65]
	v_mfma_f32_16x16x32_bf16 v[50:53], v[172:175], v[180:183], v[50:53]
	v_mfma_f32_16x16x32_bf16 v[46:49], v[146:149], v[192:195], v[46:49]
	v_mfma_f32_16x16x32_bf16 v[38:41], v[172:175], v[192:195], v[38:41]
	v_mfma_f32_16x16x32_bf16 v[30:33], v[146:149], v[200:203], v[30:33]
	v_mfma_f32_16x16x32_bf16 v[22:25], v[172:175], v[200:203], v[22:25]
	v_mfma_f32_16x16x32_bf16 v[10:13], v[146:149], v[208:211], v[10:13]
	v_mfma_f32_16x16x32_bf16 v[14:17], v[172:175], v[208:211], v[14:17]
	v_mfma_f32_16x16x32_bf16 v[62:65], v[150:153], v[188:191], v[62:65]
	v_mfma_f32_16x16x32_bf16 v[50:53], v[176:179], v[188:191], v[50:53]
	v_mfma_f32_16x16x32_bf16 v[46:49], v[150:153], v[196:199], v[46:49]
	v_mfma_f32_16x16x32_bf16 v[38:41], v[176:179], v[196:199], v[38:41]
	v_mfma_f32_16x16x32_bf16 v[30:33], v[150:153], v[204:207], v[30:33]
	v_mfma_f32_16x16x32_bf16 v[22:25], v[176:179], v[204:207], v[22:25]
	v_mfma_f32_16x16x32_bf16 v[10:13], v[150:153], v[212:215], v[10:13]
	v_mfma_f32_16x16x32_bf16 v[14:17], v[176:179], v[212:215], v[14:17]
	s_setprio 0
	s_barrier
	s_add_i32 s64, s64, 2
	s_add_u32 s18, s18, 0x100
	s_addc_u32 s19, s19, 0
	s_add_u32 s62, s62, 0x100
	s_addc_u32 s63, s63, 0
	s_cmpk_gt_u32 s64, 0xa9
	s_cbranch_scc0 .LBB0_1245
	s_and_b64 vcc, exec, s[12:13]
	s_cbranch_vccz .LBB0_1248
	s_barrier

; #define PG8_STAGE(bufoff, gbase, voff) do { _Pragma("unroll") for (int _i = 0; _i < 2; ++_i) \
;         __builtin_amdgcn_global_load_lds((const unsigned*)((const char*)(gbase) + (voff)[_i]), (PG8_LAS unsigned*)(lds + (bufoff) + ldsw + _i * 8192), 16, 0, 0); } while (0)
; #define PG8_LDA(dst, b, h) do { _Pragma("unroll") for (int m = 0; m < 4; ++m) _Pragma("unroll") for (int k = 0; k < 2; ++k) dst[m][k] = *(const PG8_LAS bf16x8*)(lds + PG8_SA(b, h) + aoff + m * 2048 + k * 1024); } while (0)
; #define PG8_LDB(dst, b, h) do { _Pragma("unroll") for (int n = 0; n < 2; ++n) _Pragma("unroll") for (int k = 0; k < 2; ++k) dst[n][k] = *(const PG8_LAS bf16x8*)(lds + PG8_SB(b, h) + boff + n * 2048 + k * 1024); } while (0)
; #define PG8_MMA(ai, bj, At, Bt) do { __builtin_amdgcn_s_setprio(1); _Pragma("unroll") for (int m = 0; m < 4; ++m) _Pragma("unroll") for (int n = 0; n < 2; ++n) _Pragma("unroll") for (int k = 0; k < 2; ++k) \
;         acc[ai][bj][m][n] = __builtin_amdgcn_mfma_f32_16x16x32_bf16(Bt[n][k], At[m][k], acc[ai][bj][m][n], 0, 0, 0); __builtin_amdgcn_s_setprio(0); } while (0)
; #define PG8_WAIT_V(n) asm volatile("s_waitcnt vmcnt(" #n ")" ::: "memory")
; #define PG8_WAIT_L(n) asm volatile("s_waitcnt lgkmcnt(" #n ")" ::: "memory")
; template <class Epi, class Sched, bool ALIGN_EPI = false, bool SP2 = false>
; __device__ __forceinline__ void gemm_phase(PG8_LAS unsigned char* lds, const Gemm g, const Sched& S, const Epi& E) {
;     ...
;             const bool last = (t == nt - 2);
;             const char* a1 = cA + (size_t)(t + 1) * kstep;
;             const char* a2 = last ? nA : cA + (size_t)(t + 2) * kstep; const char* b2 = last ? nB : cB + (size_t)(t + 2) * kstep;
;             const char* a3 = a2 + kstep; const char* b3 = b2 + kstep;
;             if (last && has_next) S.a_ready(nxt);
;             if constexpr (SP2) {
;             PG8_LDB(B0, 0, 0); PG8_LDB(B1, 0, 1); PG8_SCHED; PG8_LDA(At, 0, 0); PG8_STAGE(PG8_SA(1, 1), a1 + hstep, voffA);
;             PG8_WAIT_V(8); PG8_WAIT_L(0); PG8_BAR; PG8_MMA(0, 0, At, B0); PG8_MMA(0, 1, At, B1); PG8_BAR; PG8_SCHED;
;             PG8_LDA(At, 0, 1); PG8_STAGE(PG8_SB(0, 0), b2, voffB); PG8_STAGE(PG8_SB(0, 1), b2 + hstep, voffB); PG8_STAGE(PG8_SA(0, 0), a2, voffA);
;             PG8_WAIT_V(8); PG8_WAIT_L(0); PG8_BAR; PG8_MMA(1, 0, At, B0); PG8_MMA(1, 1, At, B1); PG8_BAR; PG8_SCHED;
.LBB0_1332:
	ds_read_b128 v[148:151], v241 offset:0
	ds_read_b128 v[156:159], v241 offset:1024
	ds_read_b128 v[166:169], v241 offset:2048
	ds_read_b128 v[170:173], v241 offset:3072
	ds_read_b128 v[174:177], v241 offset:16384
	ds_read_b128 v[178:181], v241 offset:17408
	ds_read_b128 v[182:185], v241 offset:18432
	ds_read_b128 v[186:189], v241 offset:19456
	s_add_u32 s20, s22, 0xfff00080
	s_addc_u32 s21, s23, -1
	s_cmp_eq_u32 s67, 60
	s_cselect_b32 s25, s13, s21
	s_cselect_b32 s24, s63, s20
	s_cselect_b32 s21, s11, s66
	s_cselect_b32 s20, s64, s65
	s_add_i32 m0, s19, 0xc000
	ds_read_b128 v[190:193], v155
	ds_read_b128 v[194:197], v155 offset:1024
	ds_read_b128 v[198:201], v155 offset:2048
	ds_read_b128 v[202:205], v155 offset:3072
	ds_read_b128 v[206:209], v155 offset:4096
	ds_read_b128 v[210:213], v155 offset:5120
	ds_read_b128 v[214:217], v155 offset:6144
	ds_read_b128 v[218:221], v155 offset:7168
	global_load_lds_dwordx4 v138, s[22:23]
	s_add_i32 m0, s19, 0xe000
	s_nop 0
	global_load_lds_dwordx4 v140, s[22:23]
	s_waitcnt vmcnt(8)
	s_waitcnt lgkmcnt(0)
	s_barrier
	s_setprio 1
	s_waitcnt lgkmcnt(0)
	v_mfma_f32_16x16x32_bf16 v[118:121], v[148:151], v[190:193], v[118:121]
	v_mfma_f32_16x16x32_bf16 v[114:117], v[166:169], v[190:193], v[114:117]
	v_mfma_f32_16x16x32_bf16 v[102:105], v[148:151], v[198:201], v[102:105]
	v_mfma_f32_16x16x32_bf16 v[98:101], v[166:169], v[198:201], v[98:101]
	v_mfma_f32_16x16x32_bf16 v[86:89], v[148:151], v[206:209], v[86:89]
	v_mfma_f32_16x16x32_bf16 v[82:85], v[166:169], v[206:209], v[82:85]
	v_mfma_f32_16x16x32_bf16 v[70:73], v[148:151], v[214:217], v[70:73]
	v_mfma_f32_16x16x32_bf16 v[66:69], v[166:169], v[214:217], v[66:69]
	v_mfma_f32_16x16x32_bf16 v[118:121], v[156:159], v[194:197], v[118:121]
	v_mfma_f32_16x16x32_bf16 v[114:117], v[170:173], v[194:197], v[114:117]
	v_mfma_f32_16x16x32_bf16 v[102:105], v[156:159], v[202:205], v[102:105]
	v_mfma_f32_16x16x32_bf16 v[98:101], v[170:173], v[202:205], v[98:101]
	v_mfma_f32_16x16x32_bf16 v[86:89], v[156:159], v[210:213], v[86:89]
	v_mfma_f32_16x16x32_bf16 v[82:85], v[170:173], v[210:213], v[82:85]
	v_mfma_f32_16x16x32_bf16 v[70:73], v[156:159], v[218:221], v[70:73]
	v_mfma_f32_16x16x32_bf16 v[66:69], v[170:173], v[218:221], v[66:69]
	s_setprio 0
	s_setprio 1
	v_mfma_f32_16x16x32_bf16 v[126:129], v[174:177], v[190:193], v[126:129]
	v_mfma_f32_16x16x32_bf16 v[122:125], v[182:185], v[190:193], v[122:125]
	v_mfma_f32_16x16x32_bf16 v[110:113], v[174:177], v[198:201], v[110:113]
	v_mfma_f32_16x16x32_bf16 v[106:109], v[182:185], v[198:201], v[106:109]
	v_mfma_f32_16x16x32_bf16 v[94:97], v[174:177], v[206:209], v[94:97]
	v_mfma_f32_16x16x32_bf16 v[90:93], v[182:185], v[206:209], v[90:93]
	v_mfma_f32_16x16x32_bf16 v[78:81], v[174:177], v[214:217], v[78:81]
	v_mfma_f32_16x16x32_bf16 v[74:77], v[182:185], v[214:217], v[74:77]
	v_mfma_f32_16x16x32_bf16 v[126:129], v[178:181], v[194:197], v[126:129]
	v_mfma_f32_16x16x32_bf16 v[122:125], v[186:189], v[194:197], v[122:125]
	v_mfma_f32_16x16x32_bf16 v[110:113], v[178:181], v[202:205], v[110:113]
	v_mfma_f32_16x16x32_bf16 v[106:109], v[186:189], v[202:205], v[106:109]
	v_mfma_f32_16x16x32_bf16 v[94:97], v[178:181], v[210:213], v[94:97]
	v_mfma_f32_16x16x32_bf16 v[90:93], v[186:189], v[210:213], v[90:93]
	v_mfma_f32_16x16x32_bf16 v[78:81], v[178:181], v[218:221], v[78:81]
	v_mfma_f32_16x16x32_bf16 v[74:77], v[186:189], v[218:221], v[74:77]
	s_setprio 0
	s_barrier
	s_add_i32 s33, s47, s28
	s_mov_b32 m0, s33
	ds_read_b128 v[190:193], v155 offset:16384
	ds_read_b128 v[194:197], v155 offset:17408
	ds_read_b128 v[198:201], v155 offset:18432
	ds_read_b128 v[202:205], v155 offset:19456
	ds_read_b128 v[206:209], v155 offset:20480
	ds_read_b128 v[210:213], v155 offset:21504
	ds_read_b128 v[214:217], v155 offset:22528
	ds_read_b128 v[218:221], v155 offset:23552
	global_load_lds_dwordx4 v132, s[20:21]
	s_add_i32 m0, s33, 0x2000
	s_add_u32 s68, s20, 0x100000
	s_addc_u32 s69, s21, 0
	s_add_i32 s33, s52, s28
	global_load_lds_dwordx4 v136, s[20:21]
	s_mov_b32 m0, s33
	s_add_u32 s100, s24, 0x80
	s_addc_u32 s101, s25, 0
	global_load_lds_dwordx4 v132, s[68:69]
	s_add_i32 m0, s33, 0x2000
	s_nop 0
	global_load_lds_dwordx4 v136, s[68:69]
	s_mov_b32 m0, s19
	s_nop 0
	global_load_lds_dwordx4 v130, s[24:25]
	s_mov_b32 m0, s35
	s_nop 0
	global_load_lds_dwordx4 v134, s[24:25]
	s_waitcnt vmcnt(8)
	s_waitcnt lgkmcnt(0)
	s_barrier
	s_setprio 1
	s_waitcnt lgkmcnt(0)
	v_mfma_f32_16x16x32_bf16 v[54:57], v[148:151], v[190:193], v[54:57]
	v_mfma_f32_16x16x32_bf16 v[50:53], v[166:169], v[190:193], v[50:53]
	v_mfma_f32_16x16x32_bf16 v[38:41], v[148:151], v[198:201], v[38:41]
	v_mfma_f32_16x16x32_bf16 v[34:37], v[166:169], v[198:201], v[34:37]
	v_mfma_f32_16x16x32_bf16 v[22:25], v[148:151], v[206:209], v[22:25]
	v_mfma_f32_16x16x32_bf16 v[18:21], v[166:169], v[206:209], v[18:21]
	v_mfma_f32_16x16x32_bf16 v[6:9], v[148:151], v[214:217], v[6:9]
	v_mfma_f32_16x16x32_bf16 v[2:5], v[166:169], v[214:217], v[2:5]
	v_mfma_f32_16x16x32_bf16 v[54:57], v[156:159], v[194:197], v[54:57]
	v_mfma_f32_16x16x32_bf16 v[50:53], v[170:173], v[194:197], v[50:53]
	v_mfma_f32_16x16x32_bf16 v[38:41], v[156:159], v[202:205], v[38:41]
	v_mfma_f32_16x16x32_bf16 v[34:37], v[170:173], v[202:205], v[34:37]
	v_mfma_f32_16x16x32_bf16 v[22:25], v[156:159], v[210:213], v[22:25]
	v_mfma_f32_16x16x32_bf16 v[18:21], v[170:173], v[210:213], v[18:21]
	v_mfma_f32_16x16x32_bf16 v[6:9], v[156:159], v[218:221], v[6:9]
	v_mfma_f32_16x16x32_bf16 v[2:5], v[170:173], v[218:221], v[2:5]
	s_setprio 0
	s_setprio 1
	v_mfma_f32_16x16x32_bf16 v[62:65], v[174:177], v[190:193], v[62:65]
	v_mfma_f32_16x16x32_bf16 v[58:61], v[182:185], v[190:193], v[58:61]
	v_mfma_f32_16x16x32_bf16 v[46:49], v[174:177], v[198:201], v[46:49]
	v_mfma_f32_16x16x32_bf16 v[42:45], v[182:185], v[198:201], v[42:45]
	v_mfma_f32_16x16x32_bf16 v[30:33], v[174:177], v[206:209], v[30:33]
	v_mfma_f32_16x16x32_bf16 v[26:29], v[182:185], v[206:209], v[26:29]
	v_mfma_f32_16x16x32_bf16 v[10:13], v[174:177], v[214:217], v[10:13]
	v_mfma_f32_16x16x32_bf16 v[14:17], v[182:185], v[214:217], v[14:17]
	v_mfma_f32_16x16x32_bf16 v[62:65], v[178:181], v[194:197], v[62:65]
	v_mfma_f32_16x16x32_bf16 v[58:61], v[186:189], v[194:197], v[58:61]
	v_mfma_f32_16x16x32_bf16 v[46:49], v[178:181], v[202:205], v[46:49]
	v_mfma_f32_16x16x32_bf16 v[42:45], v[186:189], v[202:205], v[42:45]
	v_mfma_f32_16x16x32_bf16 v[30:33], v[178:181], v[210:213], v[30:33]
	v_mfma_f32_16x16x32_bf16 v[26:29], v[186:189], v[210:213], v[26:29]
	v_mfma_f32_16x16x32_bf16 v[10:13], v[178:181], v[218:221], v[10:13]
	v_mfma_f32_16x16x32_bf16 v[14:17], v[186:189], v[218:221], v[14:17]
	s_setprio 0
	s_barrier
; #define PG8_STAGE(bufoff, gbase, voff) do { _Pragma("unroll") for (int _i = 0; _i < 2; ++_i) \
;         __builtin_amdgcn_global_load_lds((const unsigned*)((const char*)(gbase) + (voff)[_i]), (PG8_LAS unsigned*)(lds + (bufoff) + ldsw + _i * 8192), 16, 0, 0); } while (0)
; #define PG8_LDA(dst, b, h) do { _Pragma("unroll") for (int m = 0; m < 4; ++m) _Pragma("unroll") for (int k = 0; k < 2; ++k) dst[m][k] = *(const PG8_LAS bf16x8*)(lds + PG8_SA(b, h) + aoff + m * 2048 + k * 1024); } while (0)
; #define PG8_LDB(dst, b, h) do { _Pragma("unroll") for (int n = 0; n < 2; ++n) _Pragma("unroll") for (int k = 0; k < 2; ++k) dst[n][k] = *(const PG8_LAS bf16x8*)(lds + PG8_SB(b, h) + boff + n * 2048 + k * 1024); } while (0)
; #define PG8_MMA(ai, bj, At, Bt) do { __builtin_amdgcn_s_setprio(1); _Pragma("unroll") for (int m = 0; m < 4; ++m) _Pragma("unroll") for (int n = 0; n < 2; ++n) _Pragma("unroll") for (int k = 0; k < 2; ++k) \
;         acc[ai][bj][m][n] = __builtin_amdgcn_mfma_f32_16x16x32_bf16(Bt[n][k], At[m][k], acc[ai][bj][m][n], 0, 0, 0); __builtin_amdgcn_s_setprio(0); } while (0)
; #define PG8_WAIT_V(n) asm volatile("s_waitcnt vmcnt(" #n ")" ::: "memory")
; #define PG8_WAIT_L(n) asm volatile("s_waitcnt lgkmcnt(" #n ")" ::: "memory")
; #define PG8_BAR __builtin_amdgcn_s_barrier()
; #define PG8_SCHED __builtin_amdgcn_sched_barrier(0)
; template <class Epi, class Sched, bool ALIGN_EPI = false, bool SP2 = false>
; __device__ __forceinline__ void gemm_phase(PG8_LAS unsigned char* lds, const Gemm g, const Sched& S, const Epi& E) {
;     ...
;             PG8_LDB(B0, 1, 0); PG8_LDB(B1, 1, 1); PG8_SCHED; PG8_LDA(At, 1, 0); PG8_STAGE(PG8_SA(0, 1), a2 + hstep, voffA);
;             PG8_WAIT_V(8); PG8_WAIT_L(0); PG8_BAR; PG8_MMA(0, 0, At, B0); PG8_MMA(0, 1, At, B1); PG8_BAR; PG8_SCHED;
;             PG8_LDA(At, 1, 1); PG8_STAGE(PG8_SB(1, 0), b3, voffB); PG8_STAGE(PG8_SB(1, 1), b3 + hstep, voffB); PG8_STAGE(PG8_SA(1, 0), a3, voffA);
;             PG8_WAIT_V(8); PG8_WAIT_L(0); PG8_BAR; PG8_MMA(1, 0, At, B0); PG8_MMA(1, 1, At, B1); PG8_BAR; PG8_SCHED;
;     ...
;         }
;         if constexpr (ALIGN_EPI) { if (wr == 0) PG8_BAR; }
	s_add_i32 s33, 0, 0x18000
	s_add_i32 s42, 0, 0x1c000
	ds_read_b128 v[148:151], v241 offset:32768
	ds_read_b128 v[156:159], v241 offset:33792
	ds_read_b128 v[166:169], v241 offset:34816
	ds_read_b128 v[170:173], v241 offset:35840
	ds_read_b128 v[174:177], v241 offset:49152
	ds_read_b128 v[178:181], v241 offset:50176
	ds_read_b128 v[182:185], v241 offset:51200
	ds_read_b128 v[186:189], v241 offset:52224
	s_add_u32 s24, s24, 0x100000
	s_addc_u32 s25, s25, 0
	s_mov_b32 m0, s36
	ds_read_b128 v[190:193], v155 offset:32768
	ds_read_b128 v[194:197], v155 offset:33792
	ds_read_b128 v[198:201], v155 offset:34816
	ds_read_b128 v[202:205], v155 offset:35840
	ds_read_b128 v[206:209], v155 offset:36864
	ds_read_b128 v[210:213], v155 offset:37888
	ds_read_b128 v[214:217], v155 offset:38912
	ds_read_b128 v[218:221], v155 offset:39936
	global_load_lds_dwordx4 v130, s[24:25]
	s_mov_b32 m0, s37
	s_nop 0
	global_load_lds_dwordx4 v134, s[24:25]
	s_waitcnt vmcnt(8)
	s_waitcnt lgkmcnt(0)
	s_barrier
	s_setprio 1
	s_waitcnt lgkmcnt(0)
	v_mfma_f32_16x16x32_bf16 v[118:121], v[148:151], v[190:193], v[118:121]
	v_mfma_f32_16x16x32_bf16 v[114:117], v[166:169], v[190:193], v[114:117]
	v_mfma_f32_16x16x32_bf16 v[102:105], v[148:151], v[198:201], v[102:105]
	v_mfma_f32_16x16x32_bf16 v[98:101], v[166:169], v[198:201], v[98:101]
	v_mfma_f32_16x16x32_bf16 v[86:89], v[148:151], v[206:209], v[86:89]
	v_mfma_f32_16x16x32_bf16 v[82:85], v[166:169], v[206:209], v[82:85]
	v_mfma_f32_16x16x32_bf16 v[70:73], v[148:151], v[214:217], v[70:73]
	v_mfma_f32_16x16x32_bf16 v[66:69], v[166:169], v[214:217], v[66:69]
	v_mfma_f32_16x16x32_bf16 v[118:121], v[156:159], v[194:197], v[118:121]
	v_mfma_f32_16x16x32_bf16 v[114:117], v[170:173], v[194:197], v[114:117]
	v_mfma_f32_16x16x32_bf16 v[102:105], v[156:159], v[202:205], v[102:105]
	v_mfma_f32_16x16x32_bf16 v[98:101], v[170:173], v[202:205], v[98:101]
	v_mfma_f32_16x16x32_bf16 v[86:89], v[156:159], v[210:213], v[86:89]
	v_mfma_f32_16x16x32_bf16 v[82:85], v[170:173], v[210:213], v[82:85]
	v_mfma_f32_16x16x32_bf16 v[70:73], v[156:159], v[218:221], v[70:73]
	v_mfma_f32_16x16x32_bf16 v[66:69], v[170:173], v[218:221], v[66:69]
	s_setprio 0
	s_setprio 1
	v_mfma_f32_16x16x32_bf16 v[126:129], v[174:177], v[190:193], v[126:129]
	v_mfma_f32_16x16x32_bf16 v[122:125], v[182:185], v[190:193], v[122:125]
	v_mfma_f32_16x16x32_bf16 v[110:113], v[174:177], v[198:201], v[110:113]
	v_mfma_f32_16x16x32_bf16 v[106:109], v[182:185], v[198:201], v[106:109]
	v_mfma_f32_16x16x32_bf16 v[94:97], v[174:177], v[206:209], v[94:97]
	v_mfma_f32_16x16x32_bf16 v[90:93], v[182:185], v[206:209], v[90:93]
	v_mfma_f32_16x16x32_bf16 v[78:81], v[174:177], v[214:217], v[78:81]
	v_mfma_f32_16x16x32_bf16 v[74:77], v[182:185], v[214:217], v[74:77]
	v_mfma_f32_16x16x32_bf16 v[126:129], v[178:181], v[194:197], v[126:129]
	v_mfma_f32_16x16x32_bf16 v[122:125], v[186:189], v[194:197], v[122:125]
	v_mfma_f32_16x16x32_bf16 v[110:113], v[178:181], v[202:205], v[110:113]
	v_mfma_f32_16x16x32_bf16 v[106:109], v[186:189], v[202:205], v[106:109]
	v_mfma_f32_16x16x32_bf16 v[94:97], v[178:181], v[210:213], v[94:97]
	v_mfma_f32_16x16x32_bf16 v[90:93], v[186:189], v[210:213], v[90:93]
	v_mfma_f32_16x16x32_bf16 v[78:81], v[178:181], v[218:221], v[78:81]
	v_mfma_f32_16x16x32_bf16 v[74:77], v[186:189], v[218:221], v[74:77]
	s_setprio 0
	s_barrier
	s_add_i32 s24, s33, s28
	s_add_i32 m0, s24, 0xffffff80
	ds_read_b128 v[190:193], v155 offset:49152
	ds_read_b128 v[194:197], v155 offset:50176
	ds_read_b128 v[198:201], v155 offset:51200
	ds_read_b128 v[202:205], v155 offset:52224
	ds_read_b128 v[206:209], v155 offset:53248
	ds_read_b128 v[210:213], v155 offset:54272
	ds_read_b128 v[214:217], v155 offset:55296
	ds_read_b128 v[218:221], v155 offset:56320
	global_load_lds_dwordx4 v132, s[20:21] offset:128
	s_add_i32 m0, s24, 0x1f80
	s_add_i32 s24, s42, s28
	global_load_lds_dwordx4 v136, s[20:21] offset:128
	s_add_u32 s20, s20, 0x100080
	s_addc_u32 s21, s21, 0
	s_mov_b32 m0, s24
	s_nop 0
	global_load_lds_dwordx4 v132, s[20:21]
	s_add_i32 m0, s24, 0x2000
	s_nop 0
	global_load_lds_dwordx4 v136, s[20:21]
	s_mov_b32 m0, s43
	s_nop 0
	global_load_lds_dwordx4 v130, s[100:101]
	s_mov_b32 m0, s46
	s_nop 0
	global_load_lds_dwordx4 v134, s[100:101]
	s_waitcnt vmcnt(8)
	s_waitcnt lgkmcnt(0)
	s_barrier
	s_setprio 1
	s_waitcnt lgkmcnt(0)
	v_mfma_f32_16x16x32_bf16 v[54:57], v[148:151], v[190:193], v[54:57]
	v_mfma_f32_16x16x32_bf16 v[50:53], v[166:169], v[190:193], v[50:53]
	v_mfma_f32_16x16x32_bf16 v[38:41], v[148:151], v[198:201], v[38:41]
	v_mfma_f32_16x16x32_bf16 v[34:37], v[166:169], v[198:201], v[34:37]
	v_mfma_f32_16x16x32_bf16 v[22:25], v[148:151], v[206:209], v[22:25]
	v_mfma_f32_16x16x32_bf16 v[18:21], v[166:169], v[206:209], v[18:21]
	v_mfma_f32_16x16x32_bf16 v[6:9], v[148:151], v[214:217], v[6:9]
	v_mfma_f32_16x16x32_bf16 v[2:5], v[166:169], v[214:217], v[2:5]
	v_mfma_f32_16x16x32_bf16 v[54:57], v[156:159], v[194:197], v[54:57]
	v_mfma_f32_16x16x32_bf16 v[50:53], v[170:173], v[194:197], v[50:53]
	v_mfma_f32_16x16x32_bf16 v[38:41], v[156:159], v[202:205], v[38:41]
	v_mfma_f32_16x16x32_bf16 v[34:37], v[170:173], v[202:205], v[34:37]
	v_mfma_f32_16x16x32_bf16 v[22:25], v[156:159], v[210:213], v[22:25]
	v_mfma_f32_16x16x32_bf16 v[18:21], v[170:173], v[210:213], v[18:21]
	v_mfma_f32_16x16x32_bf16 v[6:9], v[156:159], v[218:221], v[6:9]
	v_mfma_f32_16x16x32_bf16 v[2:5], v[170:173], v[218:221], v[2:5]
	s_setprio 0
	s_setprio 1
	v_mfma_f32_16x16x32_bf16 v[62:65], v[174:177], v[190:193], v[62:65]
	v_mfma_f32_16x16x32_bf16 v[58:61], v[182:185], v[190:193], v[58:61]
	v_mfma_f32_16x16x32_bf16 v[46:49], v[174:177], v[198:201], v[46:49]
	v_mfma_f32_16x16x32_bf16 v[42:45], v[182:185], v[198:201], v[42:45]
	v_mfma_f32_16x16x32_bf16 v[30:33], v[174:177], v[206:209], v[30:33]
	v_mfma_f32_16x16x32_bf16 v[26:29], v[182:185], v[206:209], v[26:29]
	v_mfma_f32_16x16x32_bf16 v[10:13], v[174:177], v[214:217], v[10:13]
	v_mfma_f32_16x16x32_bf16 v[14:17], v[182:185], v[214:217], v[14:17]
	v_mfma_f32_16x16x32_bf16 v[62:65], v[178:181], v[194:197], v[62:65]
	v_mfma_f32_16x16x32_bf16 v[58:61], v[186:189], v[194:197], v[58:61]
	v_mfma_f32_16x16x32_bf16 v[46:49], v[178:181], v[202:205], v[46:49]
	v_mfma_f32_16x16x32_bf16 v[42:45], v[186:189], v[202:205], v[42:45]
	v_mfma_f32_16x16x32_bf16 v[30:33], v[178:181], v[210:213], v[30:33]
	v_mfma_f32_16x16x32_bf16 v[26:29], v[186:189], v[210:213], v[26:29]
	v_mfma_f32_16x16x32_bf16 v[10:13], v[178:181], v[218:221], v[10:13]
	v_mfma_f32_16x16x32_bf16 v[14:17], v[186:189], v[218:221], v[14:17]
	s_setprio 0
	s_barrier
	s_add_i32 s67, s67, 2
	s_add_u32 s22, s22, 0x100
	s_addc_u32 s23, s23, 0
	s_add_u32 s65, s65, 0x100
	s_addc_u32 s66, s66, 0
	s_cmp_gt_u32 s67, 61
	s_cbranch_scc0 .LBB0_1332
	s_and_b64 vcc, exec, s[8:9]
	s_cbranch_vccz .LBB0_1335
	s_barrier

; #define PG8_STAGE(bufoff, gbase, voff) do { _Pragma("unroll") for (int _i = 0; _i < 2; ++_i) \
;         __builtin_amdgcn_global_load_lds((const unsigned*)((const char*)(gbase) + (voff)[_i]), (PG8_LAS unsigned*)(lds + (bufoff) + ldsw + _i * 8192), 16, 0, 0); } while (0)
; #define PG8_LDA(dst, b, h) do { _Pragma("unroll") for (int m = 0; m < 4; ++m) _Pragma("unroll") for (int k = 0; k < 2; ++k) dst[m][k] = *(const PG8_LAS bf16x8*)(lds + PG8_SA(b, h) + aoff + m * 2048 + k * 1024); } while (0)
; #define PG8_LDB(dst, b, h) do { _Pragma("unroll") for (int n = 0; n < 2; ++n) _Pragma("unroll") for (int k = 0; k < 2; ++k) dst[n][k] = *(const PG8_LAS bf16x8*)(lds + PG8_SB(b, h) + boff + n * 2048 + k * 1024); } while (0)
; #define PG8_MMA(ai, bj, At, Bt) do { __builtin_amdgcn_s_setprio(1); _Pragma("unroll") for (int m = 0; m < 4; ++m) _Pragma("unroll") for (int n = 0; n < 2; ++n) _Pragma("unroll") for (int k = 0; k < 2; ++k) \
;         acc[ai][bj][m][n] = __builtin_amdgcn_mfma_f32_16x16x32_bf16(Bt[n][k], At[m][k], acc[ai][bj][m][n], 0, 0, 0); __builtin_amdgcn_s_setprio(0); } while (0)
; #define PG8_WAIT_V(n) asm volatile("s_waitcnt vmcnt(" #n ")" ::: "memory")
; #define PG8_WAIT_L(n) asm volatile("s_waitcnt lgkmcnt(" #n ")" ::: "memory")
; template <class Epi, class Sched, bool ALIGN_EPI = false, bool SP2 = false>
; __device__ __forceinline__ void gemm_phase(PG8_LAS unsigned char* lds, const Gemm g, const Sched& S, const Epi& E) {
;     ...
;             const bool last = (t == nt - 2);
;             const char* a1 = cA + (size_t)(t + 1) * kstep;
;             const char* a2 = last ? nA : cA + (size_t)(t + 2) * kstep; const char* b2 = last ? nB : cB + (size_t)(t + 2) * kstep;
;             const char* a3 = a2 + kstep; const char* b3 = b2 + kstep;
;             if (last && has_next) S.a_ready(nxt);
;             if constexpr (SP2) {
;             PG8_LDB(B0, 0, 0); PG8_LDB(B1, 0, 1); PG8_SCHED; PG8_LDA(At, 0, 0); PG8_STAGE(PG8_SA(1, 1), a1 + hstep, voffA);
;             PG8_WAIT_V(8); PG8_WAIT_L(0); PG8_BAR; PG8_MMA(0, 0, At, B0); PG8_MMA(0, 1, At, B1); PG8_BAR; PG8_SCHED;
;             PG8_LDA(At, 0, 1); PG8_STAGE(PG8_SB(0, 0), b2, voffB); PG8_STAGE(PG8_SB(0, 1), b2 + hstep, voffB); PG8_STAGE(PG8_SA(0, 0), a2, voffA);
;             PG8_WAIT_V(8); PG8_WAIT_L(0); PG8_BAR; PG8_MMA(1, 0, At, B0); PG8_MMA(1, 1, At, B1); PG8_BAR; PG8_SCHED;
.LBB0_1595:
	ds_read_b128 v[130:133], v241 offset:0
	ds_read_b128 v[134:137], v241 offset:1024
	ds_read_b128 v[138:141], v241 offset:2048
	ds_read_b128 v[142:145], v241 offset:3072
	ds_read_b128 v[146:149], v241 offset:16384
	ds_read_b128 v[150:153], v241 offset:17408
	ds_read_b128 v[172:175], v241 offset:18432
	ds_read_b128 v[176:179], v241 offset:19456
	s_add_u32 s24, s26, 0xfff00080
	s_addc_u32 s25, s27, -1
	s_cmp_eq_u32 s62, 60
	s_cselect_b32 s29, s15, s25
	s_cselect_b32 s28, s21, s24
	s_cselect_b32 s25, s13, s53
	s_cselect_b32 s24, s51, s52
	s_add_i32 m0, s23, 0xc000
	ds_read_b128 v[180:183], v185
	ds_read_b128 v[188:191], v185 offset:1024
	ds_read_b128 v[192:195], v185 offset:2048
	ds_read_b128 v[196:199], v185 offset:3072
	ds_read_b128 v[200:203], v185 offset:4096
	ds_read_b128 v[204:207], v185 offset:5120
	ds_read_b128 v[208:211], v185 offset:6144
	ds_read_b128 v[212:215], v185 offset:7168
	global_load_lds_dwordx4 v162, s[26:27]
	s_add_i32 m0, s23, 0xe000
	s_nop 0
	global_load_lds_dwordx4 v166, s[26:27]
	s_waitcnt vmcnt(8)
	s_waitcnt lgkmcnt(0)
	s_barrier
	s_setprio 1
	s_waitcnt lgkmcnt(0)
	v_mfma_f32_16x16x32_bf16 v[114:117], v[130:133], v[180:183], v[114:117]
	v_mfma_f32_16x16x32_bf16 v[118:121], v[138:141], v[180:183], v[118:121]
	v_mfma_f32_16x16x32_bf16 v[106:109], v[130:133], v[192:195], v[106:109]
	v_mfma_f32_16x16x32_bf16 v[98:101], v[138:141], v[192:195], v[98:101]
	v_mfma_f32_16x16x32_bf16 v[90:93], v[130:133], v[200:203], v[90:93]
	v_mfma_f32_16x16x32_bf16 v[82:85], v[138:141], v[200:203], v[82:85]
	v_mfma_f32_16x16x32_bf16 v[74:77], v[130:133], v[208:211], v[74:77]
	v_mfma_f32_16x16x32_bf16 v[66:69], v[138:141], v[208:211], v[66:69]
	v_mfma_f32_16x16x32_bf16 v[114:117], v[134:137], v[188:191], v[114:117]
	v_mfma_f32_16x16x32_bf16 v[118:121], v[142:145], v[188:191], v[118:121]
	v_mfma_f32_16x16x32_bf16 v[106:109], v[134:137], v[196:199], v[106:109]
	v_mfma_f32_16x16x32_bf16 v[98:101], v[142:145], v[196:199], v[98:101]
	v_mfma_f32_16x16x32_bf16 v[90:93], v[134:137], v[204:207], v[90:93]
	v_mfma_f32_16x16x32_bf16 v[82:85], v[142:145], v[204:207], v[82:85]
	v_mfma_f32_16x16x32_bf16 v[74:77], v[134:137], v[212:215], v[74:77]
	v_mfma_f32_16x16x32_bf16 v[66:69], v[142:145], v[212:215], v[66:69]
	s_setprio 0
	s_setprio 1
	v_mfma_f32_16x16x32_bf16 v[122:125], v[146:149], v[180:183], v[122:125]
	v_mfma_f32_16x16x32_bf16 v[126:129], v[172:175], v[180:183], v[126:129]
	v_mfma_f32_16x16x32_bf16 v[110:113], v[146:149], v[192:195], v[110:113]
	v_mfma_f32_16x16x32_bf16 v[102:105], v[172:175], v[192:195], v[102:105]
	v_mfma_f32_16x16x32_bf16 v[94:97], v[146:149], v[200:203], v[94:97]
	v_mfma_f32_16x16x32_bf16 v[86:89], v[172:175], v[200:203], v[86:89]
	v_mfma_f32_16x16x32_bf16 v[78:81], v[146:149], v[208:211], v[78:81]
	v_mfma_f32_16x16x32_bf16 v[70:73], v[172:175], v[208:211], v[70:73]
	v_mfma_f32_16x16x32_bf16 v[122:125], v[150:153], v[188:191], v[122:125]
	v_mfma_f32_16x16x32_bf16 v[126:129], v[176:179], v[188:191], v[126:129]
	v_mfma_f32_16x16x32_bf16 v[110:113], v[150:153], v[196:199], v[110:113]
	v_mfma_f32_16x16x32_bf16 v[102:105], v[176:179], v[196:199], v[102:105]
	v_mfma_f32_16x16x32_bf16 v[94:97], v[150:153], v[204:207], v[94:97]
	v_mfma_f32_16x16x32_bf16 v[86:89], v[176:179], v[204:207], v[86:89]
	v_mfma_f32_16x16x32_bf16 v[78:81], v[150:153], v[212:215], v[78:81]
	v_mfma_f32_16x16x32_bf16 v[70:73], v[176:179], v[212:215], v[70:73]
	s_setprio 0
	s_barrier
	s_add_i32 s33, s48, s36
	s_mov_b32 m0, s33
	ds_read_b128 v[180:183], v185 offset:16384
	ds_read_b128 v[188:191], v185 offset:17408
	ds_read_b128 v[192:195], v185 offset:18432
	ds_read_b128 v[196:199], v185 offset:19456
	ds_read_b128 v[200:203], v185 offset:20480
	ds_read_b128 v[204:207], v185 offset:21504
	ds_read_b128 v[208:211], v185 offset:22528
	ds_read_b128 v[212:215], v185 offset:23552
	global_load_lds_dwordx4 v156, s[24:25]
	s_add_i32 m0, s33, 0x2000
	s_add_u32 s64, s24, 0x100000
	s_addc_u32 s65, s25, 0
	s_add_i32 s33, s49, s36
	global_load_lds_dwordx4 v160, s[24:25]
	s_mov_b32 m0, s33
	s_add_u32 s100, s28, 0x80
	s_addc_u32 s101, s29, 0
	global_load_lds_dwordx4 v156, s[64:65]
	s_add_i32 m0, s33, 0x2000
	s_nop 0
	global_load_lds_dwordx4 v160, s[64:65]
	s_mov_b32 m0, s23
	s_nop 0
	global_load_lds_dwordx4 v154, s[28:29]
	s_mov_b32 m0, s37
	s_nop 0
	global_load_lds_dwordx4 v158, s[28:29]
	s_waitcnt vmcnt(8)
	s_waitcnt lgkmcnt(0)
	s_barrier
	s_setprio 1
	s_waitcnt lgkmcnt(0)
	v_mfma_f32_16x16x32_bf16 v[58:61], v[130:133], v[180:183], v[58:61]
	v_mfma_f32_16x16x32_bf16 v[54:57], v[138:141], v[180:183], v[54:57]
	v_mfma_f32_16x16x32_bf16 v[42:45], v[130:133], v[192:195], v[42:45]
	v_mfma_f32_16x16x32_bf16 v[34:37], v[138:141], v[192:195], v[34:37]
	v_mfma_f32_16x16x32_bf16 v[26:29], v[130:133], v[200:203], v[26:29]
	v_mfma_f32_16x16x32_bf16 v[18:21], v[138:141], v[200:203], v[18:21]
	v_mfma_f32_16x16x32_bf16 v[6:9], v[130:133], v[208:211], v[6:9]
	v_mfma_f32_16x16x32_bf16 v[2:5], v[138:141], v[208:211], v[2:5]
	v_mfma_f32_16x16x32_bf16 v[58:61], v[134:137], v[188:191], v[58:61]
	v_mfma_f32_16x16x32_bf16 v[54:57], v[142:145], v[188:191], v[54:57]
	v_mfma_f32_16x16x32_bf16 v[42:45], v[134:137], v[196:199], v[42:45]
	v_mfma_f32_16x16x32_bf16 v[34:37], v[142:145], v[196:199], v[34:37]
	v_mfma_f32_16x16x32_bf16 v[26:29], v[134:137], v[204:207], v[26:29]
	v_mfma_f32_16x16x32_bf16 v[18:21], v[142:145], v[204:207], v[18:21]
	v_mfma_f32_16x16x32_bf16 v[6:9], v[134:137], v[212:215], v[6:9]
	v_mfma_f32_16x16x32_bf16 v[2:5], v[142:145], v[212:215], v[2:5]
	s_setprio 0
	s_setprio 1
	v_mfma_f32_16x16x32_bf16 v[62:65], v[146:149], v[180:183], v[62:65]
	v_mfma_f32_16x16x32_bf16 v[50:53], v[172:175], v[180:183], v[50:53]
	v_mfma_f32_16x16x32_bf16 v[46:49], v[146:149], v[192:195], v[46:49]
	v_mfma_f32_16x16x32_bf16 v[38:41], v[172:175], v[192:195], v[38:41]
	v_mfma_f32_16x16x32_bf16 v[30:33], v[146:149], v[200:203], v[30:33]
	v_mfma_f32_16x16x32_bf16 v[22:25], v[172:175], v[200:203], v[22:25]
	v_mfma_f32_16x16x32_bf16 v[10:13], v[146:149], v[208:211], v[10:13]
	v_mfma_f32_16x16x32_bf16 v[14:17], v[172:175], v[208:211], v[14:17]
	v_mfma_f32_16x16x32_bf16 v[62:65], v[150:153], v[188:191], v[62:65]
	v_mfma_f32_16x16x32_bf16 v[50:53], v[176:179], v[188:191], v[50:53]
	v_mfma_f32_16x16x32_bf16 v[46:49], v[150:153], v[196:199], v[46:49]
	v_mfma_f32_16x16x32_bf16 v[38:41], v[176:179], v[196:199], v[38:41]
	v_mfma_f32_16x16x32_bf16 v[30:33], v[150:153], v[204:207], v[30:33]
	v_mfma_f32_16x16x32_bf16 v[22:25], v[176:179], v[204:207], v[22:25]
	v_mfma_f32_16x16x32_bf16 v[10:13], v[150:153], v[212:215], v[10:13]
	v_mfma_f32_16x16x32_bf16 v[14:17], v[176:179], v[212:215], v[14:17]
	s_setprio 0
	s_barrier
; #define PG8_STAGE(bufoff, gbase, voff) do { _Pragma("unroll") for (int _i = 0; _i < 2; ++_i) \
;         __builtin_amdgcn_global_load_lds((const unsigned*)((const char*)(gbase) + (voff)[_i]), (PG8_LAS unsigned*)(lds + (bufoff) + ldsw + _i * 8192), 16, 0, 0); } while (0)
; #define PG8_LDA(dst, b, h) do { _Pragma("unroll") for (int m = 0; m < 4; ++m) _Pragma("unroll") for (int k = 0; k < 2; ++k) dst[m][k] = *(const PG8_LAS bf16x8*)(lds + PG8_SA(b, h) + aoff + m * 2048 + k * 1024); } while (0)
; #define PG8_LDB(dst, b, h) do { _Pragma("unroll") for (int n = 0; n < 2; ++n) _Pragma("unroll") for (int k = 0; k < 2; ++k) dst[n][k] = *(const PG8_LAS bf16x8*)(lds + PG8_SB(b, h) + boff + n * 2048 + k * 1024); } while (0)
; #define PG8_MMA(ai, bj, At, Bt) do { __builtin_amdgcn_s_setprio(1); _Pragma("unroll") for (int m = 0; m < 4; ++m) _Pragma("unroll") for (int n = 0; n < 2; ++n) _Pragma("unroll") for (int k = 0; k < 2; ++k) \
;         acc[ai][bj][m][n] = __builtin_amdgcn_mfma_f32_16x16x32_bf16(Bt[n][k], At[m][k], acc[ai][bj][m][n], 0, 0, 0); __builtin_amdgcn_s_setprio(0); } while (0)
; #define PG8_WAIT_V(n) asm volatile("s_waitcnt vmcnt(" #n ")" ::: "memory")
; #define PG8_WAIT_L(n) asm volatile("s_waitcnt lgkmcnt(" #n ")" ::: "memory")
; #define PG8_BAR __builtin_amdgcn_s_barrier()
; #define PG8_SCHED __builtin_amdgcn_sched_barrier(0)
; template <class Epi, class Sched, bool ALIGN_EPI = false, bool SP2 = false>
; __device__ __forceinline__ void gemm_phase(PG8_LAS unsigned char* lds, const Gemm g, const Sched& S, const Epi& E) {
;     ...
;             PG8_LDB(B0, 1, 0); PG8_LDB(B1, 1, 1); PG8_SCHED; PG8_LDA(At, 1, 0); PG8_STAGE(PG8_SA(0, 1), a2 + hstep, voffA);
;             PG8_WAIT_V(8); PG8_WAIT_L(0); PG8_BAR; PG8_MMA(0, 0, At, B0); PG8_MMA(0, 1, At, B1); PG8_BAR; PG8_SCHED;
;             PG8_LDA(At, 1, 1); PG8_STAGE(PG8_SB(1, 0), b3, voffB); PG8_STAGE(PG8_SB(1, 1), b3 + hstep, voffB); PG8_STAGE(PG8_SA(1, 0), a3, voffA);
;             PG8_WAIT_V(8); PG8_WAIT_L(0); PG8_BAR; PG8_MMA(1, 0, At, B0); PG8_MMA(1, 1, At, B1); PG8_BAR; PG8_SCHED;
;     ...
;         }
;         if constexpr (ALIGN_EPI) { if (wr == 0) PG8_BAR; }
	s_add_i32 s33, 0, 0x18000
	s_add_i32 s42, 0, 0x1c000
	ds_read_b128 v[130:133], v241 offset:32768
	ds_read_b128 v[134:137], v241 offset:33792
	ds_read_b128 v[138:141], v241 offset:34816
	ds_read_b128 v[142:145], v241 offset:35840
	ds_read_b128 v[146:149], v241 offset:49152
	ds_read_b128 v[150:153], v241 offset:50176
	ds_read_b128 v[172:175], v241 offset:51200
	ds_read_b128 v[176:179], v241 offset:52224
	s_add_u32 s28, s28, 0x100000
	s_addc_u32 s29, s29, 0
	s_mov_b32 m0, s40
	ds_read_b128 v[180:183], v185 offset:32768
	ds_read_b128 v[188:191], v185 offset:33792
	ds_read_b128 v[192:195], v185 offset:34816
	ds_read_b128 v[196:199], v185 offset:35840
	ds_read_b128 v[200:203], v185 offset:36864
	ds_read_b128 v[204:207], v185 offset:37888
	ds_read_b128 v[208:211], v185 offset:38912
	ds_read_b128 v[212:215], v185 offset:39936
	global_load_lds_dwordx4 v154, s[28:29]
	s_mov_b32 m0, s41
	s_nop 0
	global_load_lds_dwordx4 v158, s[28:29]
	s_waitcnt vmcnt(8)
	s_waitcnt lgkmcnt(0)
	s_barrier
	s_setprio 1
	s_waitcnt lgkmcnt(0)
	v_mfma_f32_16x16x32_bf16 v[114:117], v[130:133], v[180:183], v[114:117]
	v_mfma_f32_16x16x32_bf16 v[118:121], v[138:141], v[180:183], v[118:121]
	v_mfma_f32_16x16x32_bf16 v[106:109], v[130:133], v[192:195], v[106:109]
	v_mfma_f32_16x16x32_bf16 v[98:101], v[138:141], v[192:195], v[98:101]
	v_mfma_f32_16x16x32_bf16 v[90:93], v[130:133], v[200:203], v[90:93]
	v_mfma_f32_16x16x32_bf16 v[82:85], v[138:141], v[200:203], v[82:85]
	v_mfma_f32_16x16x32_bf16 v[74:77], v[130:133], v[208:211], v[74:77]
	v_mfma_f32_16x16x32_bf16 v[66:69], v[138:141], v[208:211], v[66:69]
	v_mfma_f32_16x16x32_bf16 v[114:117], v[134:137], v[188:191], v[114:117]
	v_mfma_f32_16x16x32_bf16 v[118:121], v[142:145], v[188:191], v[118:121]
	v_mfma_f32_16x16x32_bf16 v[106:109], v[134:137], v[196:199], v[106:109]
	v_mfma_f32_16x16x32_bf16 v[98:101], v[142:145], v[196:199], v[98:101]
	v_mfma_f32_16x16x32_bf16 v[90:93], v[134:137], v[204:207], v[90:93]
	v_mfma_f32_16x16x32_bf16 v[82:85], v[142:145], v[204:207], v[82:85]
	v_mfma_f32_16x16x32_bf16 v[74:77], v[134:137], v[212:215], v[74:77]
	v_mfma_f32_16x16x32_bf16 v[66:69], v[142:145], v[212:215], v[66:69]
	s_setprio 0
	s_setprio 1
	v_mfma_f32_16x16x32_bf16 v[122:125], v[146:149], v[180:183], v[122:125]
	v_mfma_f32_16x16x32_bf16 v[126:129], v[172:175], v[180:183], v[126:129]
	v_mfma_f32_16x16x32_bf16 v[110:113], v[146:149], v[192:195], v[110:113]
	v_mfma_f32_16x16x32_bf16 v[102:105], v[172:175], v[192:195], v[102:105]
	v_mfma_f32_16x16x32_bf16 v[94:97], v[146:149], v[200:203], v[94:97]
	v_mfma_f32_16x16x32_bf16 v[86:89], v[172:175], v[200:203], v[86:89]
	v_mfma_f32_16x16x32_bf16 v[78:81], v[146:149], v[208:211], v[78:81]
	v_mfma_f32_16x16x32_bf16 v[70:73], v[172:175], v[208:211], v[70:73]
	v_mfma_f32_16x16x32_bf16 v[122:125], v[150:153], v[188:191], v[122:125]
	v_mfma_f32_16x16x32_bf16 v[126:129], v[176:179], v[188:191], v[126:129]
	v_mfma_f32_16x16x32_bf16 v[110:113], v[150:153], v[196:199], v[110:113]
	v_mfma_f32_16x16x32_bf16 v[102:105], v[176:179], v[196:199], v[102:105]
	v_mfma_f32_16x16x32_bf16 v[94:97], v[150:153], v[204:207], v[94:97]
	v_mfma_f32_16x16x32_bf16 v[86:89], v[176:179], v[204:207], v[86:89]
	v_mfma_f32_16x16x32_bf16 v[78:81], v[150:153], v[212:215], v[78:81]
	v_mfma_f32_16x16x32_bf16 v[70:73], v[176:179], v[212:215], v[70:73]
	s_setprio 0
	s_barrier
	s_add_i32 s28, s33, s36
	s_add_i32 m0, s28, 0xffffff80
	ds_read_b128 v[180:183], v185 offset:49152
	ds_read_b128 v[188:191], v185 offset:50176
	ds_read_b128 v[192:195], v185 offset:51200
	ds_read_b128 v[196:199], v185 offset:52224
	ds_read_b128 v[200:203], v185 offset:53248
	ds_read_b128 v[204:207], v185 offset:54272
	ds_read_b128 v[208:211], v185 offset:55296
	ds_read_b128 v[212:215], v185 offset:56320
	global_load_lds_dwordx4 v156, s[24:25] offset:128
	s_add_i32 m0, s28, 0x1f80
	s_add_i32 s28, s42, s36
	global_load_lds_dwordx4 v160, s[24:25] offset:128
	s_add_u32 s24, s24, 0x100080
	s_addc_u32 s25, s25, 0
	s_mov_b32 m0, s28
	s_nop 0
	global_load_lds_dwordx4 v156, s[24:25]
	s_add_i32 m0, s28, 0x2000
	s_nop 0
	global_load_lds_dwordx4 v160, s[24:25]
	s_mov_b32 m0, s44
	s_nop 0
	global_load_lds_dwordx4 v154, s[100:101]
	s_mov_b32 m0, s45
	s_nop 0
	global_load_lds_dwordx4 v158, s[100:101]
	s_waitcnt vmcnt(8)
	s_waitcnt lgkmcnt(0)
	s_barrier
	s_setprio 1
	s_waitcnt lgkmcnt(0)
	v_mfma_f32_16x16x32_bf16 v[58:61], v[130:133], v[180:183], v[58:61]
	v_mfma_f32_16x16x32_bf16 v[54:57], v[138:141], v[180:183], v[54:57]
	v_mfma_f32_16x16x32_bf16 v[42:45], v[130:133], v[192:195], v[42:45]
	v_mfma_f32_16x16x32_bf16 v[34:37], v[138:141], v[192:195], v[34:37]
	v_mfma_f32_16x16x32_bf16 v[26:29], v[130:133], v[200:203], v[26:29]
	v_mfma_f32_16x16x32_bf16 v[18:21], v[138:141], v[200:203], v[18:21]
	v_mfma_f32_16x16x32_bf16 v[6:9], v[130:133], v[208:211], v[6:9]
	v_mfma_f32_16x16x32_bf16 v[2:5], v[138:141], v[208:211], v[2:5]
	v_mfma_f32_16x16x32_bf16 v[58:61], v[134:137], v[188:191], v[58:61]
	v_mfma_f32_16x16x32_bf16 v[54:57], v[142:145], v[188:191], v[54:57]
	v_mfma_f32_16x16x32_bf16 v[42:45], v[134:137], v[196:199], v[42:45]
	v_mfma_f32_16x16x32_bf16 v[34:37], v[142:145], v[196:199], v[34:37]
	v_mfma_f32_16x16x32_bf16 v[26:29], v[134:137], v[204:207], v[26:29]
	v_mfma_f32_16x16x32_bf16 v[18:21], v[142:145], v[204:207], v[18:21]
	v_mfma_f32_16x16x32_bf16 v[6:9], v[134:137], v[212:215], v[6:9]
	v_mfma_f32_16x16x32_bf16 v[2:5], v[142:145], v[212:215], v[2:5]
	s_setprio 0
	s_setprio 1
	v_mfma_f32_16x16x32_bf16 v[62:65], v[146:149], v[180:183], v[62:65]
	v_mfma_f32_16x16x32_bf16 v[50:53], v[172:175], v[180:183], v[50:53]
	v_mfma_f32_16x16x32_bf16 v[46:49], v[146:149], v[192:195], v[46:49]
	v_mfma_f32_16x16x32_bf16 v[38:41], v[172:175], v[192:195], v[38:41]
	v_mfma_f32_16x16x32_bf16 v[30:33], v[146:149], v[200:203], v[30:33]
	v_mfma_f32_16x16x32_bf16 v[22:25], v[172:175], v[200:203], v[22:25]
	v_mfma_f32_16x16x32_bf16 v[10:13], v[146:149], v[208:211], v[10:13]
	v_mfma_f32_16x16x32_bf16 v[14:17], v[172:175], v[208:211], v[14:17]
	v_mfma_f32_16x16x32_bf16 v[62:65], v[150:153], v[188:191], v[62:65]
	v_mfma_f32_16x16x32_bf16 v[50:53], v[176:179], v[188:191], v[50:53]
	v_mfma_f32_16x16x32_bf16 v[46:49], v[150:153], v[196:199], v[46:49]
	v_mfma_f32_16x16x32_bf16 v[38:41], v[176:179], v[196:199], v[38:41]
	v_mfma_f32_16x16x32_bf16 v[30:33], v[150:153], v[204:207], v[30:33]
	v_mfma_f32_16x16x32_bf16 v[22:25], v[176:179], v[204:207], v[22:25]
	v_mfma_f32_16x16x32_bf16 v[10:13], v[150:153], v[212:215], v[10:13]
	v_mfma_f32_16x16x32_bf16 v[14:17], v[176:179], v[212:215], v[14:17]
	s_setprio 0
	s_barrier
	s_add_i32 s62, s62, 2
	s_add_u32 s26, s26, 0x100
	s_addc_u32 s27, s27, 0
	s_add_u32 s52, s52, 0x100
	s_addc_u32 s53, s53, 0
	s_cmp_gt_u32 s62, 61
	s_cbranch_scc0 .LBB0_1595
	s_and_b64 vcc, exec, s[10:11]
	s_cbranch_vccz .LBB0_1598
	s_barrier

; #define PG8_STAGE(bufoff, gbase, voff) do { _Pragma("unroll") for (int _i = 0; _i < 2; ++_i) \
;         __builtin_amdgcn_global_load_lds((const unsigned*)((const char*)(gbase) + (voff)[_i]), (PG8_LAS unsigned*)(lds + (bufoff) + ldsw + _i * 8192), 16, 0, 0); } while (0)
; #define PG8_LDA(dst, b, h) do { _Pragma("unroll") for (int m = 0; m < 4; ++m) _Pragma("unroll") for (int k = 0; k < 2; ++k) dst[m][k] = *(const PG8_LAS bf16x8*)(lds + PG8_SA(b, h) + aoff + m * 2048 + k * 1024); } while (0)
; #define PG8_LDB(dst, b, h) do { _Pragma("unroll") for (int n = 0; n < 2; ++n) _Pragma("unroll") for (int k = 0; k < 2; ++k) dst[n][k] = *(const PG8_LAS bf16x8*)(lds + PG8_SB(b, h) + boff + n * 2048 + k * 1024); } while (0)
; #define PG8_MMA(ai, bj, At, Bt) do { __builtin_amdgcn_s_setprio(1); _Pragma("unroll") for (int m = 0; m < 4; ++m) _Pragma("unroll") for (int n = 0; n < 2; ++n) _Pragma("unroll") for (int k = 0; k < 2; ++k) \
;         acc[ai][bj][m][n] = __builtin_amdgcn_mfma_f32_16x16x32_bf16(Bt[n][k], At[m][k], acc[ai][bj][m][n], 0, 0, 0); __builtin_amdgcn_s_setprio(0); } while (0)
; #define PG8_WAIT_V(n) asm volatile("s_waitcnt vmcnt(" #n ")" ::: "memory")
; #define PG8_WAIT_L(n) asm volatile("s_waitcnt lgkmcnt(" #n ")" ::: "memory")
; template <class Epi, class Sched, bool ALIGN_EPI = false, bool SP2 = false>
; __device__ __forceinline__ void gemm_phase(PG8_LAS unsigned char* lds, const Gemm g, const Sched& S, const Epi& E) {
;     ...
;             const bool last = (t == nt - 2);
;             const char* a1 = cA + (size_t)(t + 1) * kstep;
;             const char* a2 = last ? nA : cA + (size_t)(t + 2) * kstep; const char* b2 = last ? nB : cB + (size_t)(t + 2) * kstep;
;             const char* a3 = a2 + kstep; const char* b3 = b2 + kstep;
;             if (last && has_next) S.a_ready(nxt);
;             if constexpr (SP2) {
;             PG8_LDB(B0, 0, 0); PG8_LDB(B1, 0, 1); PG8_SCHED; PG8_LDA(At, 0, 0); PG8_STAGE(PG8_SA(1, 1), a1 + hstep, voffA);
;             PG8_WAIT_V(8); PG8_WAIT_L(0); PG8_BAR; PG8_MMA(0, 0, At, B0); PG8_MMA(0, 1, At, B1); PG8_BAR; PG8_SCHED;
;             PG8_LDA(At, 0, 1); PG8_STAGE(PG8_SB(0, 0), b2, voffB); PG8_STAGE(PG8_SB(0, 1), b2 + hstep, voffB); PG8_STAGE(PG8_SA(0, 0), a2, voffA);
;             PG8_WAIT_V(8); PG8_WAIT_L(0); PG8_BAR; PG8_MMA(1, 0, At, B0); PG8_MMA(1, 1, At, B1); PG8_BAR; PG8_SCHED;
.LBB0_1681:
	ds_read_b128 v[160:163], v241 offset:0
	ds_read_b128 v[166:169], v241 offset:1024
	ds_read_b128 v[170:173], v241 offset:2048
	ds_read_b128 v[174:177], v241 offset:3072
	ds_read_b128 v[178:181], v241 offset:16384
	ds_read_b128 v[182:185], v241 offset:17408
	ds_read_b128 v[186:189], v241 offset:18432
	ds_read_b128 v[190:193], v241 offset:19456
	s_add_u32 s22, s24, 0xfff00080
	s_addc_u32 s23, s25, -1
	s_cmp_eq_u32 s52, 60
	s_cselect_b32 s27, s15, s23
	s_cselect_b32 s26, s48, s22
	s_cselect_b32 s23, s13, s51
	s_cselect_b32 s22, s49, s50
	s_add_i32 m0, s21, 0xc000
	ds_read_b128 v[194:197], v155
	ds_read_b128 v[198:201], v155 offset:1024
	ds_read_b128 v[202:205], v155 offset:2048
	ds_read_b128 v[206:209], v155 offset:3072
	ds_read_b128 v[210:213], v155 offset:4096
	ds_read_b128 v[214:217], v155 offset:5120
	ds_read_b128 v[218:221], v155 offset:6144
	ds_read_b128 v[222:225], v155 offset:7168
	global_load_lds_dwordx4 v138, s[24:25]
	s_add_i32 m0, s21, 0xe000
	s_nop 0
	global_load_lds_dwordx4 v140, s[24:25]
	s_waitcnt vmcnt(8)
	s_waitcnt lgkmcnt(0)
	s_barrier
	s_setprio 1
	s_waitcnt lgkmcnt(0)
	v_mfma_f32_16x16x32_bf16 v[122:125], v[160:163], v[194:197], v[122:125]
	v_mfma_f32_16x16x32_bf16 v[114:117], v[170:173], v[194:197], v[114:117]
	v_mfma_f32_16x16x32_bf16 v[106:109], v[160:163], v[202:205], v[106:109]
	v_mfma_f32_16x16x32_bf16 v[98:101], v[170:173], v[202:205], v[98:101]
	v_mfma_f32_16x16x32_bf16 v[90:93], v[160:163], v[210:213], v[90:93]
	v_mfma_f32_16x16x32_bf16 v[82:85], v[170:173], v[210:213], v[82:85]
	v_mfma_f32_16x16x32_bf16 v[74:77], v[160:163], v[218:221], v[74:77]
	v_mfma_f32_16x16x32_bf16 v[62:65], v[170:173], v[218:221], v[62:65]
	v_mfma_f32_16x16x32_bf16 v[122:125], v[166:169], v[198:201], v[122:125]
	v_mfma_f32_16x16x32_bf16 v[114:117], v[174:177], v[198:201], v[114:117]
	v_mfma_f32_16x16x32_bf16 v[106:109], v[166:169], v[206:209], v[106:109]
	v_mfma_f32_16x16x32_bf16 v[98:101], v[174:177], v[206:209], v[98:101]
	v_mfma_f32_16x16x32_bf16 v[90:93], v[166:169], v[214:217], v[90:93]
	v_mfma_f32_16x16x32_bf16 v[82:85], v[174:177], v[214:217], v[82:85]
	v_mfma_f32_16x16x32_bf16 v[74:77], v[166:169], v[222:225], v[74:77]
	v_mfma_f32_16x16x32_bf16 v[62:65], v[174:177], v[222:225], v[62:65]
	s_setprio 0
	s_setprio 1
	v_mfma_f32_16x16x32_bf16 v[126:129], v[178:181], v[194:197], v[126:129]
	v_mfma_f32_16x16x32_bf16 v[118:121], v[186:189], v[194:197], v[118:121]
	v_mfma_f32_16x16x32_bf16 v[110:113], v[178:181], v[202:205], v[110:113]
	v_mfma_f32_16x16x32_bf16 v[102:105], v[186:189], v[202:205], v[102:105]
	v_mfma_f32_16x16x32_bf16 v[94:97], v[178:181], v[210:213], v[94:97]
	v_mfma_f32_16x16x32_bf16 v[86:89], v[186:189], v[210:213], v[86:89]
	v_mfma_f32_16x16x32_bf16 v[78:81], v[178:181], v[218:221], v[78:81]
	v_mfma_f32_16x16x32_bf16 v[70:73], v[186:189], v[218:221], v[70:73]
	v_mfma_f32_16x16x32_bf16 v[126:129], v[182:185], v[198:201], v[126:129]
	v_mfma_f32_16x16x32_bf16 v[118:121], v[190:193], v[198:201], v[118:121]
	v_mfma_f32_16x16x32_bf16 v[110:113], v[182:185], v[206:209], v[110:113]
	v_mfma_f32_16x16x32_bf16 v[102:105], v[190:193], v[206:209], v[102:105]
	v_mfma_f32_16x16x32_bf16 v[94:97], v[182:185], v[214:217], v[94:97]
	v_mfma_f32_16x16x32_bf16 v[86:89], v[190:193], v[214:217], v[86:89]
	v_mfma_f32_16x16x32_bf16 v[78:81], v[182:185], v[222:225], v[78:81]
	v_mfma_f32_16x16x32_bf16 v[70:73], v[190:193], v[222:225], v[70:73]
	s_setprio 0
	s_barrier
	s_add_i32 s33, s44, s29
	s_mov_b32 m0, s33
	ds_read_b128 v[194:197], v155 offset:16384
	ds_read_b128 v[198:201], v155 offset:17408
	ds_read_b128 v[202:205], v155 offset:18432
	ds_read_b128 v[206:209], v155 offset:19456
	ds_read_b128 v[210:213], v155 offset:20480
	ds_read_b128 v[214:217], v155 offset:21504
	ds_read_b128 v[218:221], v155 offset:22528
	ds_read_b128 v[222:225], v155 offset:23552
	global_load_lds_dwordx4 v132, s[22:23]
	s_add_i32 m0, s33, 0x2000
	s_add_u32 s62, s22, 0x100000
	s_addc_u32 s63, s23, 0
	s_add_i32 s33, s45, s29
	global_load_lds_dwordx4 v136, s[22:23]
	s_mov_b32 m0, s33
	s_add_u32 s100, s26, 0x80
	s_addc_u32 s101, s27, 0
	global_load_lds_dwordx4 v132, s[62:63]
	s_add_i32 m0, s33, 0x2000
	s_nop 0
	global_load_lds_dwordx4 v136, s[62:63]
	s_mov_b32 m0, s21
	s_nop 0
	global_load_lds_dwordx4 v130, s[26:27]
	s_mov_b32 m0, s34
	s_nop 0
	global_load_lds_dwordx4 v134, s[26:27]
	s_waitcnt vmcnt(8)
	s_waitcnt lgkmcnt(0)
	s_barrier
	s_setprio 1
	s_waitcnt lgkmcnt(0)
	v_mfma_f32_16x16x32_bf16 v[58:61], v[160:163], v[194:197], v[58:61]
	v_mfma_f32_16x16x32_bf16 v[50:53], v[170:173], v[194:197], v[50:53]
	v_mfma_f32_16x16x32_bf16 v[42:45], v[160:163], v[202:205], v[42:45]
	v_mfma_f32_16x16x32_bf16 v[34:37], v[170:173], v[202:205], v[34:37]
	v_mfma_f32_16x16x32_bf16 v[26:29], v[160:163], v[210:213], v[26:29]
	v_mfma_f32_16x16x32_bf16 v[18:21], v[170:173], v[210:213], v[18:21]
	v_mfma_f32_16x16x32_bf16 v[10:13], v[160:163], v[218:221], v[10:13]
	v_mfma_f32_16x16x32_bf16 v[2:5], v[170:173], v[218:221], v[2:5]
	v_mfma_f32_16x16x32_bf16 v[58:61], v[166:169], v[198:201], v[58:61]
	v_mfma_f32_16x16x32_bf16 v[50:53], v[174:177], v[198:201], v[50:53]
	v_mfma_f32_16x16x32_bf16 v[42:45], v[166:169], v[206:209], v[42:45]
	v_mfma_f32_16x16x32_bf16 v[34:37], v[174:177], v[206:209], v[34:37]
	v_mfma_f32_16x16x32_bf16 v[26:29], v[166:169], v[214:217], v[26:29]
	v_mfma_f32_16x16x32_bf16 v[18:21], v[174:177], v[214:217], v[18:21]
	v_mfma_f32_16x16x32_bf16 v[10:13], v[166:169], v[222:225], v[10:13]
	v_mfma_f32_16x16x32_bf16 v[2:5], v[174:177], v[222:225], v[2:5]
	s_setprio 0
	s_setprio 1
	v_mfma_f32_16x16x32_bf16 v[66:69], v[178:181], v[194:197], v[66:69]
	v_mfma_f32_16x16x32_bf16 v[54:57], v[186:189], v[194:197], v[54:57]
	v_mfma_f32_16x16x32_bf16 v[46:49], v[178:181], v[202:205], v[46:49]
	v_mfma_f32_16x16x32_bf16 v[38:41], v[186:189], v[202:205], v[38:41]
	v_mfma_f32_16x16x32_bf16 v[30:33], v[178:181], v[210:213], v[30:33]
	v_mfma_f32_16x16x32_bf16 v[22:25], v[186:189], v[210:213], v[22:25]
	v_mfma_f32_16x16x32_bf16 v[14:17], v[178:181], v[218:221], v[14:17]
	v_mfma_f32_16x16x32_bf16 v[6:9], v[186:189], v[218:221], v[6:9]
	v_mfma_f32_16x16x32_bf16 v[66:69], v[182:185], v[198:201], v[66:69]
	v_mfma_f32_16x16x32_bf16 v[54:57], v[190:193], v[198:201], v[54:57]
	v_mfma_f32_16x16x32_bf16 v[46:49], v[182:185], v[206:209], v[46:49]
	v_mfma_f32_16x16x32_bf16 v[38:41], v[190:193], v[206:209], v[38:41]
	v_mfma_f32_16x16x32_bf16 v[30:33], v[182:185], v[214:217], v[30:33]
	v_mfma_f32_16x16x32_bf16 v[22:25], v[190:193], v[214:217], v[22:25]
	v_mfma_f32_16x16x32_bf16 v[14:17], v[182:185], v[222:225], v[14:17]
	v_mfma_f32_16x16x32_bf16 v[6:9], v[190:193], v[222:225], v[6:9]
	s_setprio 0
	s_barrier
; #define PG8_STAGE(bufoff, gbase, voff) do { _Pragma("unroll") for (int _i = 0; _i < 2; ++_i) \
;         __builtin_amdgcn_global_load_lds((const unsigned*)((const char*)(gbase) + (voff)[_i]), (PG8_LAS unsigned*)(lds + (bufoff) + ldsw + _i * 8192), 16, 0, 0); } while (0)
; #define PG8_LDA(dst, b, h) do { _Pragma("unroll") for (int m = 0; m < 4; ++m) _Pragma("unroll") for (int k = 0; k < 2; ++k) dst[m][k] = *(const PG8_LAS bf16x8*)(lds + PG8_SA(b, h) + aoff + m * 2048 + k * 1024); } while (0)
; #define PG8_LDB(dst, b, h) do { _Pragma("unroll") for (int n = 0; n < 2; ++n) _Pragma("unroll") for (int k = 0; k < 2; ++k) dst[n][k] = *(const PG8_LAS bf16x8*)(lds + PG8_SB(b, h) + boff + n * 2048 + k * 1024); } while (0)
; #define PG8_MMA(ai, bj, At, Bt) do { __builtin_amdgcn_s_setprio(1); _Pragma("unroll") for (int m = 0; m < 4; ++m) _Pragma("unroll") for (int n = 0; n < 2; ++n) _Pragma("unroll") for (int k = 0; k < 2; ++k) \
;         acc[ai][bj][m][n] = __builtin_amdgcn_mfma_f32_16x16x32_bf16(Bt[n][k], At[m][k], acc[ai][bj][m][n], 0, 0, 0); __builtin_amdgcn_s_setprio(0); } while (0)
; #define PG8_WAIT_V(n) asm volatile("s_waitcnt vmcnt(" #n ")" ::: "memory")
; #define PG8_WAIT_L(n) asm volatile("s_waitcnt lgkmcnt(" #n ")" ::: "memory")
; #define PG8_BAR __builtin_amdgcn_s_barrier()
; #define PG8_SCHED __builtin_amdgcn_sched_barrier(0)
; template <class Epi, class Sched, bool ALIGN_EPI = false, bool SP2 = false>
; __device__ __forceinline__ void gemm_phase(PG8_LAS unsigned char* lds, const Gemm g, const Sched& S, const Epi& E) {
;     ...
;             PG8_LDB(B0, 1, 0); PG8_LDB(B1, 1, 1); PG8_SCHED; PG8_LDA(At, 1, 0); PG8_STAGE(PG8_SA(0, 1), a2 + hstep, voffA);
;             PG8_WAIT_V(8); PG8_WAIT_L(0); PG8_BAR; PG8_MMA(0, 0, At, B0); PG8_MMA(0, 1, At, B1); PG8_BAR; PG8_SCHED;
;             PG8_LDA(At, 1, 1); PG8_STAGE(PG8_SB(1, 0), b3, voffB); PG8_STAGE(PG8_SB(1, 1), b3 + hstep, voffB); PG8_STAGE(PG8_SA(1, 0), a3, voffA);
;             PG8_WAIT_V(8); PG8_WAIT_L(0); PG8_BAR; PG8_MMA(1, 0, At, B0); PG8_MMA(1, 1, At, B1); PG8_BAR; PG8_SCHED;
;     ...
;         }
;         if constexpr (ALIGN_EPI) { if (wr == 0) PG8_BAR; }
	s_add_i32 s33, 0, 0x18000
	s_add_i32 s42, 0, 0x1c000
	ds_read_b128 v[160:163], v241 offset:32768
	ds_read_b128 v[166:169], v241 offset:33792
	ds_read_b128 v[170:173], v241 offset:34816
	ds_read_b128 v[174:177], v241 offset:35840
	ds_read_b128 v[178:181], v241 offset:49152
	ds_read_b128 v[182:185], v241 offset:50176
	ds_read_b128 v[186:189], v241 offset:51200
	ds_read_b128 v[190:193], v241 offset:52224
	s_add_u32 s26, s26, 0x100000
	s_addc_u32 s27, s27, 0
	s_mov_b32 m0, s35
	ds_read_b128 v[194:197], v155 offset:32768
	ds_read_b128 v[198:201], v155 offset:33792
	ds_read_b128 v[202:205], v155 offset:34816
	ds_read_b128 v[206:209], v155 offset:35840
	ds_read_b128 v[210:213], v155 offset:36864
	ds_read_b128 v[214:217], v155 offset:37888
	ds_read_b128 v[218:221], v155 offset:38912
	ds_read_b128 v[222:225], v155 offset:39936
	global_load_lds_dwordx4 v130, s[26:27]
	s_mov_b32 m0, s36
	s_nop 0
	global_load_lds_dwordx4 v134, s[26:27]
	s_waitcnt vmcnt(8)
	s_waitcnt lgkmcnt(0)
	s_barrier
	s_setprio 1
	s_waitcnt lgkmcnt(0)
	v_mfma_f32_16x16x32_bf16 v[122:125], v[160:163], v[194:197], v[122:125]
	v_mfma_f32_16x16x32_bf16 v[114:117], v[170:173], v[194:197], v[114:117]
	v_mfma_f32_16x16x32_bf16 v[106:109], v[160:163], v[202:205], v[106:109]
	v_mfma_f32_16x16x32_bf16 v[98:101], v[170:173], v[202:205], v[98:101]
	v_mfma_f32_16x16x32_bf16 v[90:93], v[160:163], v[210:213], v[90:93]
	v_mfma_f32_16x16x32_bf16 v[82:85], v[170:173], v[210:213], v[82:85]
	v_mfma_f32_16x16x32_bf16 v[74:77], v[160:163], v[218:221], v[74:77]
	v_mfma_f32_16x16x32_bf16 v[62:65], v[170:173], v[218:221], v[62:65]
	v_mfma_f32_16x16x32_bf16 v[122:125], v[166:169], v[198:201], v[122:125]
	v_mfma_f32_16x16x32_bf16 v[114:117], v[174:177], v[198:201], v[114:117]
	v_mfma_f32_16x16x32_bf16 v[106:109], v[166:169], v[206:209], v[106:109]
	v_mfma_f32_16x16x32_bf16 v[98:101], v[174:177], v[206:209], v[98:101]
	v_mfma_f32_16x16x32_bf16 v[90:93], v[166:169], v[214:217], v[90:93]
	v_mfma_f32_16x16x32_bf16 v[82:85], v[174:177], v[214:217], v[82:85]
	v_mfma_f32_16x16x32_bf16 v[74:77], v[166:169], v[222:225], v[74:77]
	v_mfma_f32_16x16x32_bf16 v[62:65], v[174:177], v[222:225], v[62:65]
	s_setprio 0
	s_setprio 1
	v_mfma_f32_16x16x32_bf16 v[126:129], v[178:181], v[194:197], v[126:129]
	v_mfma_f32_16x16x32_bf16 v[118:121], v[186:189], v[194:197], v[118:121]
	v_mfma_f32_16x16x32_bf16 v[110:113], v[178:181], v[202:205], v[110:113]
	v_mfma_f32_16x16x32_bf16 v[102:105], v[186:189], v[202:205], v[102:105]
	v_mfma_f32_16x16x32_bf16 v[94:97], v[178:181], v[210:213], v[94:97]
	v_mfma_f32_16x16x32_bf16 v[86:89], v[186:189], v[210:213], v[86:89]
	v_mfma_f32_16x16x32_bf16 v[78:81], v[178:181], v[218:221], v[78:81]
	v_mfma_f32_16x16x32_bf16 v[70:73], v[186:189], v[218:221], v[70:73]
	v_mfma_f32_16x16x32_bf16 v[126:129], v[182:185], v[198:201], v[126:129]
	v_mfma_f32_16x16x32_bf16 v[118:121], v[190:193], v[198:201], v[118:121]
	v_mfma_f32_16x16x32_bf16 v[110:113], v[182:185], v[206:209], v[110:113]
	v_mfma_f32_16x16x32_bf16 v[102:105], v[190:193], v[206:209], v[102:105]
	v_mfma_f32_16x16x32_bf16 v[94:97], v[182:185], v[214:217], v[94:97]
	v_mfma_f32_16x16x32_bf16 v[86:89], v[190:193], v[214:217], v[86:89]
	v_mfma_f32_16x16x32_bf16 v[78:81], v[182:185], v[222:225], v[78:81]
	v_mfma_f32_16x16x32_bf16 v[70:73], v[190:193], v[222:225], v[70:73]
	s_setprio 0
	s_barrier
	s_add_i32 s26, s33, s29
	s_add_i32 m0, s26, 0xffffff80
	ds_read_b128 v[194:197], v155 offset:49152
	ds_read_b128 v[198:201], v155 offset:50176
	ds_read_b128 v[202:205], v155 offset:51200
	ds_read_b128 v[206:209], v155 offset:52224
	ds_read_b128 v[210:213], v155 offset:53248
	ds_read_b128 v[214:217], v155 offset:54272
	ds_read_b128 v[218:221], v155 offset:55296
	ds_read_b128 v[222:225], v155 offset:56320
	global_load_lds_dwordx4 v132, s[22:23] offset:128
	s_add_i32 m0, s26, 0x1f80
	s_add_i32 s26, s42, s29
	global_load_lds_dwordx4 v136, s[22:23] offset:128
	s_add_u32 s22, s22, 0x100080
	s_addc_u32 s23, s23, 0
	s_mov_b32 m0, s26
	s_nop 0
	global_load_lds_dwordx4 v132, s[22:23]
	s_add_i32 m0, s26, 0x2000
	s_nop 0
	global_load_lds_dwordx4 v136, s[22:23]
	s_mov_b32 m0, s41
	s_nop 0
	global_load_lds_dwordx4 v130, s[100:101]
	s_mov_b32 m0, s43
	s_nop 0
	global_load_lds_dwordx4 v134, s[100:101]
	s_waitcnt vmcnt(8)
	s_waitcnt lgkmcnt(0)
	s_barrier
	s_setprio 1
	s_waitcnt lgkmcnt(0)
	v_mfma_f32_16x16x32_bf16 v[58:61], v[160:163], v[194:197], v[58:61]
	v_mfma_f32_16x16x32_bf16 v[50:53], v[170:173], v[194:197], v[50:53]
	v_mfma_f32_16x16x32_bf16 v[42:45], v[160:163], v[202:205], v[42:45]
	v_mfma_f32_16x16x32_bf16 v[34:37], v[170:173], v[202:205], v[34:37]
	v_mfma_f32_16x16x32_bf16 v[26:29], v[160:163], v[210:213], v[26:29]
	v_mfma_f32_16x16x32_bf16 v[18:21], v[170:173], v[210:213], v[18:21]
	v_mfma_f32_16x16x32_bf16 v[10:13], v[160:163], v[218:221], v[10:13]
	v_mfma_f32_16x16x32_bf16 v[2:5], v[170:173], v[218:221], v[2:5]
	v_mfma_f32_16x16x32_bf16 v[58:61], v[166:169], v[198:201], v[58:61]
	v_mfma_f32_16x16x32_bf16 v[50:53], v[174:177], v[198:201], v[50:53]
	v_mfma_f32_16x16x32_bf16 v[42:45], v[166:169], v[206:209], v[42:45]
	v_mfma_f32_16x16x32_bf16 v[34:37], v[174:177], v[206:209], v[34:37]
	v_mfma_f32_16x16x32_bf16 v[26:29], v[166:169], v[214:217], v[26:29]
	v_mfma_f32_16x16x32_bf16 v[18:21], v[174:177], v[214:217], v[18:21]
	v_mfma_f32_16x16x32_bf16 v[10:13], v[166:169], v[222:225], v[10:13]
	v_mfma_f32_16x16x32_bf16 v[2:5], v[174:177], v[222:225], v[2:5]
	s_setprio 0
	s_setprio 1
	v_mfma_f32_16x16x32_bf16 v[66:69], v[178:181], v[194:197], v[66:69]
	v_mfma_f32_16x16x32_bf16 v[54:57], v[186:189], v[194:197], v[54:57]
	v_mfma_f32_16x16x32_bf16 v[46:49], v[178:181], v[202:205], v[46:49]
	v_mfma_f32_16x16x32_bf16 v[38:41], v[186:189], v[202:205], v[38:41]
	v_mfma_f32_16x16x32_bf16 v[30:33], v[178:181], v[210:213], v[30:33]
	v_mfma_f32_16x16x32_bf16 v[22:25], v[186:189], v[210:213], v[22:25]
	v_mfma_f32_16x16x32_bf16 v[14:17], v[178:181], v[218:221], v[14:17]
	v_mfma_f32_16x16x32_bf16 v[6:9], v[186:189], v[218:221], v[6:9]
	v_mfma_f32_16x16x32_bf16 v[66:69], v[182:185], v[198:201], v[66:69]
	v_mfma_f32_16x16x32_bf16 v[54:57], v[190:193], v[198:201], v[54:57]
	v_mfma_f32_16x16x32_bf16 v[46:49], v[182:185], v[206:209], v[46:49]
	v_mfma_f32_16x16x32_bf16 v[38:41], v[190:193], v[206:209], v[38:41]
	v_mfma_f32_16x16x32_bf16 v[30:33], v[182:185], v[214:217], v[30:33]
	v_mfma_f32_16x16x32_bf16 v[22:25], v[190:193], v[214:217], v[22:25]
	v_mfma_f32_16x16x32_bf16 v[14:17], v[182:185], v[222:225], v[14:17]
	v_mfma_f32_16x16x32_bf16 v[6:9], v[190:193], v[222:225], v[6:9]
	s_setprio 0
	s_barrier
	s_add_i32 s52, s52, 2
	s_add_u32 s24, s24, 0x100
	s_addc_u32 s25, s25, 0
	s_add_u32 s50, s50, 0x100
	s_addc_u32 s51, s51, 0
	s_cmp_gt_u32 s52, 61
	s_cbranch_scc0 .LBB0_1681
	s_and_b64 vcc, exec, s[8:9]
	s_cbranch_vccz .LBB0_1684
	s_barrier

; #define PG8_STAGE(bufoff, gbase, voff) do { _Pragma("unroll") for (int _i = 0; _i < 2; ++_i) \
;         __builtin_amdgcn_global_load_lds((const unsigned*)((const char*)(gbase) + (voff)[_i]), (PG8_LAS unsigned*)(lds + (bufoff) + ldsw + _i * 8192), 16, 0, 0); } while (0)
; #define PG8_LDA(dst, b, h) do { _Pragma("unroll") for (int m = 0; m < 4; ++m) _Pragma("unroll") for (int k = 0; k < 2; ++k) dst[m][k] = *(const PG8_LAS bf16x8*)(lds + PG8_SA(b, h) + aoff + m * 2048 + k * 1024); } while (0)
; #define PG8_LDB(dst, b, h) do { _Pragma("unroll") for (int n = 0; n < 2; ++n) _Pragma("unroll") for (int k = 0; k < 2; ++k) dst[n][k] = *(const PG8_LAS bf16x8*)(lds + PG8_SB(b, h) + boff + n * 2048 + k * 1024); } while (0)
; #define PG8_MMA(ai, bj, At, Bt) do { __builtin_amdgcn_s_setprio(1); _Pragma("unroll") for (int m = 0; m < 4; ++m) _Pragma("unroll") for (int n = 0; n < 2; ++n) _Pragma("unroll") for (int k = 0; k < 2; ++k) \
;         acc[ai][bj][m][n] = __builtin_amdgcn_mfma_f32_16x16x32_bf16(Bt[n][k], At[m][k], acc[ai][bj][m][n], 0, 0, 0); __builtin_amdgcn_s_setprio(0); } while (0)
; #define PG8_WAIT_V(n) asm volatile("s_waitcnt vmcnt(" #n ")" ::: "memory")
; #define PG8_WAIT_L(n) asm volatile("s_waitcnt lgkmcnt(" #n ")" ::: "memory")
; template <class Epi, class Sched, bool ALIGN_EPI = false, bool SP2 = false>
; __device__ __forceinline__ void gemm_phase(PG8_LAS unsigned char* lds, const Gemm g, const Sched& S, const Epi& E) {
;     ...
;             const bool last = (t == nt - 2);
;             const char* a1 = cA + (size_t)(t + 1) * kstep;
;             const char* a2 = last ? nA : cA + (size_t)(t + 2) * kstep; const char* b2 = last ? nB : cB + (size_t)(t + 2) * kstep;
;             const char* a3 = a2 + kstep; const char* b3 = b2 + kstep;
;             if (last && has_next) S.a_ready(nxt);
;             if constexpr (SP2) {
;             PG8_LDB(B0, 0, 0); PG8_LDB(B1, 0, 1); PG8_SCHED; PG8_LDA(At, 0, 0); PG8_STAGE(PG8_SA(1, 1), a1 + hstep, voffA);
;             PG8_WAIT_V(8); PG8_WAIT_L(0); PG8_BAR; PG8_MMA(0, 0, At, B0); PG8_MMA(0, 1, At, B1); PG8_BAR; PG8_SCHED;
;             PG8_LDA(At, 0, 1); PG8_STAGE(PG8_SB(0, 0), b2, voffB); PG8_STAGE(PG8_SB(0, 1), b2 + hstep, voffB); PG8_STAGE(PG8_SA(0, 0), a2, voffA);
;             PG8_WAIT_V(8); PG8_WAIT_L(0); PG8_BAR; PG8_MMA(1, 0, At, B0); PG8_MMA(1, 1, At, B1); PG8_BAR; PG8_SCHED;
.LBB0_1801:
	ds_read_b128 v[130:133], v241 offset:0
	ds_read_b128 v[134:137], v241 offset:1024
	ds_read_b128 v[138:141], v241 offset:2048
	ds_read_b128 v[142:145], v241 offset:3072
	ds_read_b128 v[146:149], v241 offset:16384
	ds_read_b128 v[150:153], v241 offset:17408
	ds_read_b128 v[170:173], v241 offset:18432
	ds_read_b128 v[174:177], v241 offset:19456
	s_add_u32 s16, s18, 0xffd50080
	s_addc_u32 s17, s19, -1
	s_cmpk_eq_i32 s48, 0xa8
	s_cselect_b32 s21, s5, s17
	s_cselect_b32 s20, s4, s16
	s_cselect_b32 s17, s15, s47
	s_cselect_b32 s16, s14, s46
	s_add_i32 m0, s25, 0xc000
	ds_read_b128 v[178:181], v184
	ds_read_b128 v[186:189], v184 offset:1024
	ds_read_b128 v[190:193], v184 offset:2048
	ds_read_b128 v[194:197], v184 offset:3072
	ds_read_b128 v[198:201], v184 offset:4096
	ds_read_b128 v[202:205], v184 offset:5120
	ds_read_b128 v[206:209], v184 offset:6144
	ds_read_b128 v[210:213], v184 offset:7168
	global_load_lds_dwordx4 v0, s[18:19]
	s_add_i32 m0, s25, 0xe000
	s_nop 0
	global_load_lds_dwordx4 v162, s[18:19]
	s_waitcnt vmcnt(8)
	s_waitcnt lgkmcnt(0)
	s_barrier
	s_setprio 1
	s_waitcnt lgkmcnt(0)
	v_mfma_f32_16x16x32_bf16 v[114:117], v[130:133], v[178:181], v[114:117]
	v_mfma_f32_16x16x32_bf16 v[118:121], v[138:141], v[178:181], v[118:121]
	v_mfma_f32_16x16x32_bf16 v[106:109], v[130:133], v[190:193], v[106:109]
	v_mfma_f32_16x16x32_bf16 v[98:101], v[138:141], v[190:193], v[98:101]
	v_mfma_f32_16x16x32_bf16 v[90:93], v[130:133], v[198:201], v[90:93]
	v_mfma_f32_16x16x32_bf16 v[82:85], v[138:141], v[198:201], v[82:85]
	v_mfma_f32_16x16x32_bf16 v[74:77], v[130:133], v[206:209], v[74:77]
	v_mfma_f32_16x16x32_bf16 v[66:69], v[138:141], v[206:209], v[66:69]
	v_mfma_f32_16x16x32_bf16 v[114:117], v[134:137], v[186:189], v[114:117]
	v_mfma_f32_16x16x32_bf16 v[118:121], v[142:145], v[186:189], v[118:121]
	v_mfma_f32_16x16x32_bf16 v[106:109], v[134:137], v[194:197], v[106:109]
	v_mfma_f32_16x16x32_bf16 v[98:101], v[142:145], v[194:197], v[98:101]
	v_mfma_f32_16x16x32_bf16 v[90:93], v[134:137], v[202:205], v[90:93]
	v_mfma_f32_16x16x32_bf16 v[82:85], v[142:145], v[202:205], v[82:85]
	v_mfma_f32_16x16x32_bf16 v[74:77], v[134:137], v[210:213], v[74:77]
	v_mfma_f32_16x16x32_bf16 v[66:69], v[142:145], v[210:213], v[66:69]
	s_setprio 0
	s_setprio 1
	v_mfma_f32_16x16x32_bf16 v[122:125], v[146:149], v[178:181], v[122:125]
	v_mfma_f32_16x16x32_bf16 v[126:129], v[170:173], v[178:181], v[126:129]
	v_mfma_f32_16x16x32_bf16 v[110:113], v[146:149], v[190:193], v[110:113]
	v_mfma_f32_16x16x32_bf16 v[102:105], v[170:173], v[190:193], v[102:105]
	v_mfma_f32_16x16x32_bf16 v[94:97], v[146:149], v[198:201], v[94:97]
	v_mfma_f32_16x16x32_bf16 v[86:89], v[170:173], v[198:201], v[86:89]
	v_mfma_f32_16x16x32_bf16 v[78:81], v[146:149], v[206:209], v[78:81]
	v_mfma_f32_16x16x32_bf16 v[70:73], v[170:173], v[206:209], v[70:73]
	v_mfma_f32_16x16x32_bf16 v[122:125], v[150:153], v[186:189], v[122:125]
	v_mfma_f32_16x16x32_bf16 v[126:129], v[174:177], v[186:189], v[126:129]
	v_mfma_f32_16x16x32_bf16 v[110:113], v[150:153], v[194:197], v[110:113]
	v_mfma_f32_16x16x32_bf16 v[102:105], v[174:177], v[194:197], v[102:105]
	v_mfma_f32_16x16x32_bf16 v[94:97], v[150:153], v[202:205], v[94:97]
	v_mfma_f32_16x16x32_bf16 v[86:89], v[174:177], v[202:205], v[86:89]
	v_mfma_f32_16x16x32_bf16 v[78:81], v[150:153], v[210:213], v[78:81]
	v_mfma_f32_16x16x32_bf16 v[70:73], v[174:177], v[210:213], v[70:73]
	s_setprio 0
	s_barrier
	s_add_i32 s33, s36, s24
	s_mov_b32 m0, s33
	ds_read_b128 v[178:181], v184 offset:16384
	ds_read_b128 v[186:189], v184 offset:17408
	ds_read_b128 v[190:193], v184 offset:18432
	ds_read_b128 v[194:197], v184 offset:19456
	ds_read_b128 v[198:201], v184 offset:20480
	ds_read_b128 v[202:205], v184 offset:21504
	ds_read_b128 v[206:209], v184 offset:22528
	ds_read_b128 v[210:213], v184 offset:23552
	global_load_lds_dwordx4 v156, s[16:17]
	s_add_i32 m0, s33, 0x2000
	s_add_u32 s50, s16, 0x2b0000
	s_addc_u32 s51, s17, 0
	s_add_i32 s33, s37, s24
	global_load_lds_dwordx4 v160, s[16:17]
	s_mov_b32 m0, s33
	s_add_u32 s100, s20, 0x80
	s_addc_u32 s101, s21, 0
	global_load_lds_dwordx4 v156, s[50:51]
	s_add_i32 m0, s33, 0x2000
	s_nop 0
	global_load_lds_dwordx4 v160, s[50:51]
	s_mov_b32 m0, s25
	s_nop 0
	global_load_lds_dwordx4 v154, s[20:21]
	s_mov_b32 m0, s26
	s_nop 0
	global_load_lds_dwordx4 v158, s[20:21]
	s_waitcnt vmcnt(8)
	s_waitcnt lgkmcnt(0)
	s_barrier
	s_setprio 1
	s_waitcnt lgkmcnt(0)
	v_mfma_f32_16x16x32_bf16 v[58:61], v[130:133], v[178:181], v[58:61]
	v_mfma_f32_16x16x32_bf16 v[54:57], v[138:141], v[178:181], v[54:57]
	v_mfma_f32_16x16x32_bf16 v[42:45], v[130:133], v[190:193], v[42:45]
	v_mfma_f32_16x16x32_bf16 v[34:37], v[138:141], v[190:193], v[34:37]
	v_mfma_f32_16x16x32_bf16 v[26:29], v[130:133], v[198:201], v[26:29]
	v_mfma_f32_16x16x32_bf16 v[18:21], v[138:141], v[198:201], v[18:21]
	v_mfma_f32_16x16x32_bf16 v[6:9], v[130:133], v[206:209], v[6:9]
	v_mfma_f32_16x16x32_bf16 v[2:5], v[138:141], v[206:209], v[2:5]
	v_mfma_f32_16x16x32_bf16 v[58:61], v[134:137], v[186:189], v[58:61]
	v_mfma_f32_16x16x32_bf16 v[54:57], v[142:145], v[186:189], v[54:57]
	v_mfma_f32_16x16x32_bf16 v[42:45], v[134:137], v[194:197], v[42:45]
	v_mfma_f32_16x16x32_bf16 v[34:37], v[142:145], v[194:197], v[34:37]
	v_mfma_f32_16x16x32_bf16 v[26:29], v[134:137], v[202:205], v[26:29]
	v_mfma_f32_16x16x32_bf16 v[18:21], v[142:145], v[202:205], v[18:21]
	v_mfma_f32_16x16x32_bf16 v[6:9], v[134:137], v[210:213], v[6:9]
	v_mfma_f32_16x16x32_bf16 v[2:5], v[142:145], v[210:213], v[2:5]
	s_setprio 0
	s_setprio 1
	v_mfma_f32_16x16x32_bf16 v[62:65], v[146:149], v[178:181], v[62:65]
	v_mfma_f32_16x16x32_bf16 v[50:53], v[170:173], v[178:181], v[50:53]
	v_mfma_f32_16x16x32_bf16 v[46:49], v[146:149], v[190:193], v[46:49]
	v_mfma_f32_16x16x32_bf16 v[38:41], v[170:173], v[190:193], v[38:41]
	v_mfma_f32_16x16x32_bf16 v[30:33], v[146:149], v[198:201], v[30:33]
	v_mfma_f32_16x16x32_bf16 v[22:25], v[170:173], v[198:201], v[22:25]
	v_mfma_f32_16x16x32_bf16 v[10:13], v[146:149], v[206:209], v[10:13]
	v_mfma_f32_16x16x32_bf16 v[14:17], v[170:173], v[206:209], v[14:17]
	v_mfma_f32_16x16x32_bf16 v[62:65], v[150:153], v[186:189], v[62:65]
	v_mfma_f32_16x16x32_bf16 v[50:53], v[174:177], v[186:189], v[50:53]
	v_mfma_f32_16x16x32_bf16 v[46:49], v[150:153], v[194:197], v[46:49]
	v_mfma_f32_16x16x32_bf16 v[38:41], v[174:177], v[194:197], v[38:41]
	v_mfma_f32_16x16x32_bf16 v[30:33], v[150:153], v[202:205], v[30:33]
	v_mfma_f32_16x16x32_bf16 v[22:25], v[174:177], v[202:205], v[22:25]
	v_mfma_f32_16x16x32_bf16 v[10:13], v[150:153], v[210:213], v[10:13]
	v_mfma_f32_16x16x32_bf16 v[14:17], v[174:177], v[210:213], v[14:17]
	s_setprio 0
	s_barrier
; #define PG8_STAGE(bufoff, gbase, voff) do { _Pragma("unroll") for (int _i = 0; _i < 2; ++_i) \
;         __builtin_amdgcn_global_load_lds((const unsigned*)((const char*)(gbase) + (voff)[_i]), (PG8_LAS unsigned*)(lds + (bufoff) + ldsw + _i * 8192), 16, 0, 0); } while (0)
; #define PG8_LDA(dst, b, h) do { _Pragma("unroll") for (int m = 0; m < 4; ++m) _Pragma("unroll") for (int k = 0; k < 2; ++k) dst[m][k] = *(const PG8_LAS bf16x8*)(lds + PG8_SA(b, h) + aoff + m * 2048 + k * 1024); } while (0)
; #define PG8_LDB(dst, b, h) do { _Pragma("unroll") for (int n = 0; n < 2; ++n) _Pragma("unroll") for (int k = 0; k < 2; ++k) dst[n][k] = *(const PG8_LAS bf16x8*)(lds + PG8_SB(b, h) + boff + n * 2048 + k * 1024); } while (0)
; #define PG8_MMA(ai, bj, At, Bt) do { __builtin_amdgcn_s_setprio(1); _Pragma("unroll") for (int m = 0; m < 4; ++m) _Pragma("unroll") for (int n = 0; n < 2; ++n) _Pragma("unroll") for (int k = 0; k < 2; ++k) \
;         acc[ai][bj][m][n] = __builtin_amdgcn_mfma_f32_16x16x32_bf16(Bt[n][k], At[m][k], acc[ai][bj][m][n], 0, 0, 0); __builtin_amdgcn_s_setprio(0); } while (0)
; #define PG8_WAIT_V(n) asm volatile("s_waitcnt vmcnt(" #n ")" ::: "memory")
; #define PG8_WAIT_L(n) asm volatile("s_waitcnt lgkmcnt(" #n ")" ::: "memory")
; #define PG8_BAR __builtin_amdgcn_s_barrier()
; #define PG8_SCHED __builtin_amdgcn_sched_barrier(0)
; template <class Epi, class Sched, bool ALIGN_EPI = false, bool SP2 = false>
; __device__ __forceinline__ void gemm_phase(PG8_LAS unsigned char* lds, const Gemm g, const Sched& S, const Epi& E) {
;     ...
;             PG8_LDB(B0, 1, 0); PG8_LDB(B1, 1, 1); PG8_SCHED; PG8_LDA(At, 1, 0); PG8_STAGE(PG8_SA(0, 1), a2 + hstep, voffA);
;             PG8_WAIT_V(8); PG8_WAIT_L(0); PG8_BAR; PG8_MMA(0, 0, At, B0); PG8_MMA(0, 1, At, B1); PG8_BAR; PG8_SCHED;
;             PG8_LDA(At, 1, 1); PG8_STAGE(PG8_SB(1, 0), b3, voffB); PG8_STAGE(PG8_SB(1, 1), b3 + hstep, voffB); PG8_STAGE(PG8_SA(1, 0), a3, voffA);
;             PG8_WAIT_V(8); PG8_WAIT_L(0); PG8_BAR; PG8_MMA(1, 0, At, B0); PG8_MMA(1, 1, At, B1); PG8_BAR; PG8_SCHED;
;     ...
;         }
;         if constexpr (ALIGN_EPI) { if (wr == 0) PG8_BAR; }
	s_add_i32 s33, 0, 0x18000
	s_add_i32 s42, 0, 0x1c000
	ds_read_b128 v[130:133], v241 offset:32768
	ds_read_b128 v[134:137], v241 offset:33792
	ds_read_b128 v[138:141], v241 offset:34816
	ds_read_b128 v[142:145], v241 offset:35840
	ds_read_b128 v[146:149], v241 offset:49152
	ds_read_b128 v[150:153], v241 offset:50176
	ds_read_b128 v[170:173], v241 offset:51200
	ds_read_b128 v[174:177], v241 offset:52224
	s_add_u32 s20, s20, 0x2b0000
	s_addc_u32 s21, s21, 0
	s_mov_b32 m0, s27
	ds_read_b128 v[178:181], v184 offset:32768
	ds_read_b128 v[186:189], v184 offset:33792
	ds_read_b128 v[190:193], v184 offset:34816
	ds_read_b128 v[194:197], v184 offset:35840
	ds_read_b128 v[198:201], v184 offset:36864
	ds_read_b128 v[202:205], v184 offset:37888
	ds_read_b128 v[206:209], v184 offset:38912
	ds_read_b128 v[210:213], v184 offset:39936
	global_load_lds_dwordx4 v154, s[20:21]
	s_mov_b32 m0, s28
	s_nop 0
	global_load_lds_dwordx4 v158, s[20:21]
	s_waitcnt vmcnt(8)
	s_waitcnt lgkmcnt(0)
	s_barrier
	s_setprio 1
	s_waitcnt lgkmcnt(0)
	v_mfma_f32_16x16x32_bf16 v[114:117], v[130:133], v[178:181], v[114:117]
	v_mfma_f32_16x16x32_bf16 v[118:121], v[138:141], v[178:181], v[118:121]
	v_mfma_f32_16x16x32_bf16 v[106:109], v[130:133], v[190:193], v[106:109]
	v_mfma_f32_16x16x32_bf16 v[98:101], v[138:141], v[190:193], v[98:101]
	v_mfma_f32_16x16x32_bf16 v[90:93], v[130:133], v[198:201], v[90:93]
	v_mfma_f32_16x16x32_bf16 v[82:85], v[138:141], v[198:201], v[82:85]
	v_mfma_f32_16x16x32_bf16 v[74:77], v[130:133], v[206:209], v[74:77]
	v_mfma_f32_16x16x32_bf16 v[66:69], v[138:141], v[206:209], v[66:69]
	v_mfma_f32_16x16x32_bf16 v[114:117], v[134:137], v[186:189], v[114:117]
	v_mfma_f32_16x16x32_bf16 v[118:121], v[142:145], v[186:189], v[118:121]
	v_mfma_f32_16x16x32_bf16 v[106:109], v[134:137], v[194:197], v[106:109]
	v_mfma_f32_16x16x32_bf16 v[98:101], v[142:145], v[194:197], v[98:101]
	v_mfma_f32_16x16x32_bf16 v[90:93], v[134:137], v[202:205], v[90:93]
	v_mfma_f32_16x16x32_bf16 v[82:85], v[142:145], v[202:205], v[82:85]
	v_mfma_f32_16x16x32_bf16 v[74:77], v[134:137], v[210:213], v[74:77]
	v_mfma_f32_16x16x32_bf16 v[66:69], v[142:145], v[210:213], v[66:69]
	s_setprio 0
	s_setprio 1
	v_mfma_f32_16x16x32_bf16 v[122:125], v[146:149], v[178:181], v[122:125]
	v_mfma_f32_16x16x32_bf16 v[126:129], v[170:173], v[178:181], v[126:129]
	v_mfma_f32_16x16x32_bf16 v[110:113], v[146:149], v[190:193], v[110:113]
	v_mfma_f32_16x16x32_bf16 v[102:105], v[170:173], v[190:193], v[102:105]
	v_mfma_f32_16x16x32_bf16 v[94:97], v[146:149], v[198:201], v[94:97]
	v_mfma_f32_16x16x32_bf16 v[86:89], v[170:173], v[198:201], v[86:89]
	v_mfma_f32_16x16x32_bf16 v[78:81], v[146:149], v[206:209], v[78:81]
	v_mfma_f32_16x16x32_bf16 v[70:73], v[170:173], v[206:209], v[70:73]
	v_mfma_f32_16x16x32_bf16 v[122:125], v[150:153], v[186:189], v[122:125]
	v_mfma_f32_16x16x32_bf16 v[126:129], v[174:177], v[186:189], v[126:129]
	v_mfma_f32_16x16x32_bf16 v[110:113], v[150:153], v[194:197], v[110:113]
	v_mfma_f32_16x16x32_bf16 v[102:105], v[174:177], v[194:197], v[102:105]
	v_mfma_f32_16x16x32_bf16 v[94:97], v[150:153], v[202:205], v[94:97]
	v_mfma_f32_16x16x32_bf16 v[86:89], v[174:177], v[202:205], v[86:89]
	v_mfma_f32_16x16x32_bf16 v[78:81], v[150:153], v[210:213], v[78:81]
	v_mfma_f32_16x16x32_bf16 v[70:73], v[174:177], v[210:213], v[70:73]
	s_setprio 0
	s_barrier
	s_add_i32 s20, s33, s24
	s_add_i32 m0, s20, 0xffffff80
	ds_read_b128 v[178:181], v184 offset:49152
	ds_read_b128 v[186:189], v184 offset:50176
	ds_read_b128 v[190:193], v184 offset:51200
	ds_read_b128 v[194:197], v184 offset:52224
	ds_read_b128 v[198:201], v184 offset:53248
	ds_read_b128 v[202:205], v184 offset:54272
	ds_read_b128 v[206:209], v184 offset:55296
	ds_read_b128 v[210:213], v184 offset:56320
	global_load_lds_dwordx4 v156, s[16:17] offset:128
	s_add_i32 m0, s20, 0x1f80
	s_add_i32 s20, s42, s24
	global_load_lds_dwordx4 v160, s[16:17] offset:128
	s_add_u32 s16, s16, 0x2b0080
	s_addc_u32 s17, s17, 0
	s_mov_b32 m0, s20
	s_nop 0
	global_load_lds_dwordx4 v156, s[16:17]
	s_add_i32 m0, s20, 0x2000
	s_nop 0
	global_load_lds_dwordx4 v160, s[16:17]
	s_mov_b32 m0, s30
	s_nop 0
	global_load_lds_dwordx4 v154, s[100:101]
	s_mov_b32 m0, s31
	s_nop 0
	global_load_lds_dwordx4 v158, s[100:101]
	s_waitcnt vmcnt(8)
	s_waitcnt lgkmcnt(0)
	s_barrier
	s_setprio 1
	s_waitcnt lgkmcnt(0)
	v_mfma_f32_16x16x32_bf16 v[58:61], v[130:133], v[178:181], v[58:61]
	v_mfma_f32_16x16x32_bf16 v[54:57], v[138:141], v[178:181], v[54:57]
	v_mfma_f32_16x16x32_bf16 v[42:45], v[130:133], v[190:193], v[42:45]
	v_mfma_f32_16x16x32_bf16 v[34:37], v[138:141], v[190:193], v[34:37]
	v_mfma_f32_16x16x32_bf16 v[26:29], v[130:133], v[198:201], v[26:29]
	v_mfma_f32_16x16x32_bf16 v[18:21], v[138:141], v[198:201], v[18:21]
	v_mfma_f32_16x16x32_bf16 v[6:9], v[130:133], v[206:209], v[6:9]
	v_mfma_f32_16x16x32_bf16 v[2:5], v[138:141], v[206:209], v[2:5]
	v_mfma_f32_16x16x32_bf16 v[58:61], v[134:137], v[186:189], v[58:61]
	v_mfma_f32_16x16x32_bf16 v[54:57], v[142:145], v[186:189], v[54:57]
	v_mfma_f32_16x16x32_bf16 v[42:45], v[134:137], v[194:197], v[42:45]
	v_mfma_f32_16x16x32_bf16 v[34:37], v[142:145], v[194:197], v[34:37]
	v_mfma_f32_16x16x32_bf16 v[26:29], v[134:137], v[202:205], v[26:29]
	v_mfma_f32_16x16x32_bf16 v[18:21], v[142:145], v[202:205], v[18:21]
	v_mfma_f32_16x16x32_bf16 v[6:9], v[134:137], v[210:213], v[6:9]
	v_mfma_f32_16x16x32_bf16 v[2:5], v[142:145], v[210:213], v[2:5]
	s_setprio 0
	s_setprio 1
	v_mfma_f32_16x16x32_bf16 v[62:65], v[146:149], v[178:181], v[62:65]
	v_mfma_f32_16x16x32_bf16 v[50:53], v[170:173], v[178:181], v[50:53]
	v_mfma_f32_16x16x32_bf16 v[46:49], v[146:149], v[190:193], v[46:49]
	v_mfma_f32_16x16x32_bf16 v[38:41], v[170:173], v[190:193], v[38:41]
	v_mfma_f32_16x16x32_bf16 v[30:33], v[146:149], v[198:201], v[30:33]
	v_mfma_f32_16x16x32_bf16 v[22:25], v[170:173], v[198:201], v[22:25]
	v_mfma_f32_16x16x32_bf16 v[10:13], v[146:149], v[206:209], v[10:13]
	v_mfma_f32_16x16x32_bf16 v[14:17], v[170:173], v[206:209], v[14:17]
	v_mfma_f32_16x16x32_bf16 v[62:65], v[150:153], v[186:189], v[62:65]
	v_mfma_f32_16x16x32_bf16 v[50:53], v[174:177], v[186:189], v[50:53]
	v_mfma_f32_16x16x32_bf16 v[46:49], v[150:153], v[194:197], v[46:49]
	v_mfma_f32_16x16x32_bf16 v[38:41], v[174:177], v[194:197], v[38:41]
	v_mfma_f32_16x16x32_bf16 v[30:33], v[150:153], v[202:205], v[30:33]
	v_mfma_f32_16x16x32_bf16 v[22:25], v[174:177], v[202:205], v[22:25]
	v_mfma_f32_16x16x32_bf16 v[10:13], v[150:153], v[210:213], v[10:13]
	v_mfma_f32_16x16x32_bf16 v[14:17], v[174:177], v[210:213], v[14:17]
	s_setprio 0
	s_barrier
	s_add_i32 s48, s48, 2
	s_add_u32 s18, s18, 0x100
	s_addc_u32 s19, s19, 0
	s_add_u32 s46, s46, 0x100
	s_addc_u32 s47, s47, 0
	s_cmpk_gt_u32 s48, 0xa9
	s_cbranch_scc0 .LBB0_1801
	s_and_b64 vcc, exec, s[12:13]
	s_cbranch_vccz .LBB0_1804
	s_barrier
